# first K-loop iteration of every GEMM unit peeled: first MFMA per accumulator quad uses C=0, the 128 v_mov_b32 accumulator zeroing per unit is gone
# speedup vs baseline: 1.0099x; 1.0037x over previous
; template <class Epi, class Sched, bool ALIGN_EPI = false, bool SP2 = false>
; __device__ __forceinline__ void gemm_phase(PG8_LAS unsigned char* lds, const Gemm g, const Sched& S, const Epi& E) {
;     ...
;     Unit cur, nxt; int ui = 0;
;     if (!S.next(0, cur)) return;
;     int nt = cur.nk;
;     f32x4 acc[2][2][4][2];
; #pragma unroll
;     for (int a = 0; a < 2; ++a)
; #pragma unroll
;         for (int b = 0; b < 2; ++b)
; #pragma unroll
;             for (int m = 0; m < 4; ++m)
; #pragma unroll
;                 for (int n = 0; n < 2; ++n) acc[a][b][m][n] = (f32x4){0.f, 0.f, 0.f, 0.f};
;     bf16x8 At[4][2], B0[2][2], B1[2][2];
;     const char* cA = (const char*)g.A + (size_t)cur.pm * tstep + (size_t)cur.k0 * kstepA; const char* cB = (const char*)g.Bt + (size_t)cur.pn * tstep + (size_t)cur.k0 * kstepB;
;     S.a_ready(cur);
;     if constexpr (SP2) {
;         PG8_STAGE(PG8_SB(0, 0), cB, voffB); PG8_STAGE(PG8_SB(0, 1), cB + hstepB, voffB); PG8_STAGE(PG8_SA(0, 0), cA, voffA); PG8_STAGE(PG8_SA(0, 1), cA + hstepA, voffA);
;         if (wr == 1) PG8_BAR;
;         PG8_WAIT_V(2); PG8_BAR;
;         PG8_STAGE(PG8_SB(1, 0), cB + kstepB, voffB); PG8_STAGE(PG8_SA(1, 0), cA + kstepA, voffA); PG8_STAGE(PG8_SB(1, 1), cB + hstepB + kstepB, voffB);
;         PG8_WAIT_V(6); PG8_BAR;
;     } else {
;         PG8_STAGE(PG8_SB(0, 0), cB, voffB); PG8_STAGE(PG8_SA(0, 0), cA, voffA); PG8_STAGE(PG8_SB(0, 1), cB + hstepB, voffB); PG8_STAGE(PG8_SA(0, 1), cA + hstepA, voffA);
;         if (wr == 1) PG8_BAR;
;         PG8_WAIT_V(4); PG8_BAR;
;         PG8_STAGE(PG8_SB(1, 0), cB + kstepB, voffB); PG8_STAGE(PG8_SA(1, 0), cA + kstepA, voffA); PG8_STAGE(PG8_SB(1, 1), cB + hstepB + kstepB, voffB);
;         PG8_WAIT_V(6); PG8_BAR;
;     }
;     for (;;) {
;         const bool has_next = S.next(ui + 1, nxt);
;         const char* nA = has_next ? (const char*)g.A + (size_t)nxt.pm * tstep + (size_t)nxt.k0 * kstepA : cA; const char* nB = has_next ? (const char*)g.Bt + (size_t)nxt.pn * tstep + (size_t)nxt.k0 * kstepB : cB;
;         for (int t = 0; t < nt; t += 2) {
;             const bool last = (t == nt - 2);
;             const char* a1 = cA + (size_t)(t + 1) * kstepA;
;             const char* a2 = last ? nA : cA + (size_t)(t + 2) * kstepA; const char* b2 = last ? nB : cB + (size_t)(t + 2) * kstepB;
;             const char* a3 = a2 + kstepA; const char* b3 = b2 + kstepB;
.LBB0_276:
	s_ashr_i32 s29, s28, 31
	s_lshl_b64 s[34:35], s[28:29], 20
	s_add_u32 s34, s96, s34
	s_addc_u32 s35, s97, s35
	s_and_b64 s[36:37], s[30:31], exec
	s_cselect_b32 s29, s35, s43
	s_cselect_b32 s52, s34, s42
	s_ashr_i32 s27, s26, 31
	s_lshl_b64 s[36:37], s[26:27], 20
	s_add_u32 s36, s8, s36
	s_addc_u32 s37, s9, s37
	s_and_b64 s[44:45], s[30:31], exec
	s_cselect_b32 s27, s37, s41
	s_cselect_b32 s53, s36, s40
	s_add_u32 s54, s40, 0x10000
	s_addc_u32 s55, s41, 0
	s_add_u32 s40, s42, 0x80080
	s_addc_u32 s41, s43, 0
	s_mov_b32 s56, -2
	s_sub_u32 s100, s40, 0x80000
	s_subb_u32 s101, s41, 0
	ds_read_b128 v[136:139], v129
	ds_read_b128 v[146:149], v129 offset:1024
	ds_read_b128 v[150:153], v129 offset:2048
	ds_read_b128 v[154:157], v129 offset:3072
	ds_read_b128 v[158:161], v143
	ds_read_b128 v[162:165], v143 offset:1024
	ds_read_b128 v[166:169], v143 offset:2048
	ds_read_b128 v[170:173], v143 offset:3072
	s_add_u32 s42, s40, 0xfff80080
	s_addc_u32 s43, s41, -1
	s_cmp_eq_u32 s56, 28
	s_cselect_b32 s45, s29, s43
	s_cselect_b32 s44, s52, s42
	s_cselect_b32 s43, s27, s55
	s_cselect_b32 s42, s53, s54
	ds_read_b128 v[174:177], v144
	ds_read_b128 v[178:181], v144 offset:1024
	ds_read_b128 v[182:185], v144 offset:2048
	ds_read_b128 v[204:207], v144 offset:3072
	ds_read_b128 v[208:211], v144 offset:4096
	ds_read_b128 v[212:215], v144 offset:5120
	ds_read_b128 v[216:219], v144 offset:6144
	ds_read_b128 v[220:223], v144 offset:7168
	s_mov_b32 m0, s15
	s_nop 0
	global_load_lds_dwordx4 v132, s[100:101]
	s_mov_b32 m0, s47
	s_nop 0
	global_load_lds_dwordx4 v134, s[100:101]
	s_add_i32 m0, s10, 0xc000
	s_nop 0
	global_load_lds_dwordx4 v132, s[40:41]
	s_add_i32 m0, s10, 0xe000
	s_nop 0
	global_load_lds_dwordx4 v134, s[40:41]
	s_waitcnt vmcnt(8)
	s_waitcnt lgkmcnt(0)
	s_setprio 1
	s_barrier
	v_mfma_f32_16x16x32_bf16 v[124:127], v[136:139], v[174:177], 0
	v_mfma_f32_16x16x32_bf16 v[120:123], v[150:153], v[174:177], 0
	v_mfma_f32_16x16x32_bf16 v[108:111], v[136:139], v[182:185], 0
	v_mfma_f32_16x16x32_bf16 v[104:107], v[150:153], v[182:185], 0
	v_mfma_f32_16x16x32_bf16 v[92:95], v[136:139], v[208:211], 0
	v_mfma_f32_16x16x32_bf16 v[88:91], v[150:153], v[208:211], 0
	v_mfma_f32_16x16x32_bf16 v[76:79], v[136:139], v[216:219], 0
	v_mfma_f32_16x16x32_bf16 v[72:75], v[150:153], v[216:219], 0
	v_mfma_f32_16x16x32_bf16 v[124:127], v[146:149], v[178:181], v[124:127]
	v_mfma_f32_16x16x32_bf16 v[120:123], v[154:157], v[178:181], v[120:123]
	v_mfma_f32_16x16x32_bf16 v[108:111], v[146:149], v[204:207], v[108:111]
	v_mfma_f32_16x16x32_bf16 v[104:107], v[154:157], v[204:207], v[104:107]
	v_mfma_f32_16x16x32_bf16 v[92:95], v[146:149], v[212:215], v[92:95]
	v_mfma_f32_16x16x32_bf16 v[88:91], v[154:157], v[212:215], v[88:91]
	v_mfma_f32_16x16x32_bf16 v[76:79], v[146:149], v[220:223], v[76:79]
	v_mfma_f32_16x16x32_bf16 v[72:75], v[154:157], v[220:223], v[72:75]
	v_mfma_f32_16x16x32_bf16 v[116:119], v[158:161], v[174:177], 0
	v_mfma_f32_16x16x32_bf16 v[112:115], v[166:169], v[174:177], 0
	v_mfma_f32_16x16x32_bf16 v[100:103], v[158:161], v[182:185], 0
	v_mfma_f32_16x16x32_bf16 v[96:99], v[166:169], v[182:185], 0
	v_mfma_f32_16x16x32_bf16 v[84:87], v[158:161], v[208:211], 0
	v_mfma_f32_16x16x32_bf16 v[80:83], v[166:169], v[208:211], 0
	v_mfma_f32_16x16x32_bf16 v[68:71], v[158:161], v[216:219], 0
	v_mfma_f32_16x16x32_bf16 v[64:67], v[166:169], v[216:219], 0
	v_mfma_f32_16x16x32_bf16 v[116:119], v[162:165], v[178:181], v[116:119]
	v_mfma_f32_16x16x32_bf16 v[112:115], v[170:173], v[178:181], v[112:115]
	v_mfma_f32_16x16x32_bf16 v[100:103], v[162:165], v[204:207], v[100:103]
	v_mfma_f32_16x16x32_bf16 v[96:99], v[170:173], v[204:207], v[96:99]
	v_mfma_f32_16x16x32_bf16 v[84:87], v[162:165], v[212:215], v[84:87]
	v_mfma_f32_16x16x32_bf16 v[80:83], v[170:173], v[212:215], v[80:83]
	v_mfma_f32_16x16x32_bf16 v[68:71], v[162:165], v[220:223], v[68:71]
	v_mfma_f32_16x16x32_bf16 v[64:67], v[170:173], v[220:223], v[64:67]
	s_barrier
	s_add_u32 s98, s44, s20
	s_addc_u32 s99, s45, s21
	s_setprio 0
	s_add_i32 s57, s49, s2
	s_mov_b32 m0, s57
	ds_read_b128 v[174:177], v144 offset:16384
	ds_read_b128 v[178:181], v144 offset:17408
	ds_read_b128 v[182:185], v144 offset:18432
	ds_read_b128 v[204:207], v144 offset:19456
	ds_read_b128 v[208:211], v144 offset:20480
	ds_read_b128 v[212:215], v144 offset:21504
	ds_read_b128 v[216:219], v144 offset:22528
	ds_read_b128 v[220:223], v144 offset:23552
	global_load_lds_dwordx4 v194, s[42:43]
	s_add_i32 m0, s57, 0x2000
	s_add_u32 s58, s42, 0x4000
	s_addc_u32 s59, s43, 0
	s_add_i32 s57, s50, s2
	global_load_lds_dwordx4 v198, s[42:43]
	s_mov_b32 m0, s57
	s_nop 0
	global_load_lds_dwordx4 v194, s[58:59]
	s_add_i32 m0, s57, 0x2000
	s_nop 0
	global_load_lds_dwordx4 v198, s[58:59]
	s_waitcnt vmcnt(6)
	s_waitcnt lgkmcnt(0)
	s_setprio 1
	s_barrier
; #define PG8_STAGE(bufoff, gbase, voff) do { _Pragma("unroll") for (int _i = 0; _i < 2; ++_i) \
;         __builtin_amdgcn_global_load_lds((const unsigned*)((const char*)(gbase) + (voff)[_i]), (PG8_LAS unsigned*)(lds + (bufoff) + ldsw + _i * 8192), 16, 0, 0); } while (0)
; #define PG8_LDA(dst, b, h) do { _Pragma("unroll") for (int m = 0; m < 4; ++m) _Pragma("unroll") for (int k = 0; k < 2; ++k) dst[m][k] = *(const PG8_LAS bf16x8*)(lds + PG8_SA(b, h) + aoff + m * 2048 + k * 1024); } while (0)
; #define PG8_LDB(dst, b, h) do { _Pragma("unroll") for (int n = 0; n < 2; ++n) _Pragma("unroll") for (int k = 0; k < 2; ++k) dst[n][k] = *(const PG8_LAS bf16x8*)(lds + PG8_SB(b, h) + boff + n * 2048 + k * 1024); } while (0)
; #define PG8_MMA(ai, bj, At, Bt) do { __builtin_amdgcn_s_setprio(1); _Pragma("unroll") for (int m = 0; m < 4; ++m) _Pragma("unroll") for (int n = 0; n < 2; ++n) _Pragma("unroll") for (int k = 0; k < 2; ++k) \
;         acc[ai][bj][m][n] = __builtin_amdgcn_mfma_f32_16x16x32_bf16(Bt[n][k], At[m][k], acc[ai][bj][m][n], 0, 0, 0); __builtin_amdgcn_s_setprio(0); } while (0)
; #define PG8_WAIT_V(n) asm volatile("s_waitcnt vmcnt(" #n ")" ::: "memory")
; #define PG8_WAIT_L(n) asm volatile("s_waitcnt lgkmcnt(" #n ")" ::: "memory")
; #define PG8_BAR __builtin_amdgcn_s_barrier()
; #define PG8_SCHED __builtin_amdgcn_sched_barrier(0)
; template <class Epi, class Sched, bool ALIGN_EPI = false, bool SP2 = false>
; __device__ __forceinline__ void gemm_phase(PG8_LAS unsigned char* lds, const Gemm g, const Sched& S, const Epi& E) {
;     ...
;             PG8_WAIT_V(8); PG8_WAIT_L(0); PG8_BAR; PG8_MMA(1, 0, At, B0); PG8_MMA(1, 1, At, B1); PG8_BAR; PG8_SCHED;
;             PG8_LDB(B0, 1, 0); PG8_LDB(B1, 1, 1); PG8_SCHED; PG8_LDA(At, 1, 0); PG8_STAGE(PG8_SA(0, 1), a2 + hstepA, voffA);
	v_mfma_f32_16x16x32_bf16 v[60:63], v[136:139], v[174:177], 0
	v_mfma_f32_16x16x32_bf16 v[56:59], v[150:153], v[174:177], 0
	v_mfma_f32_16x16x32_bf16 v[44:47], v[136:139], v[182:185], 0
	v_mfma_f32_16x16x32_bf16 v[40:43], v[150:153], v[182:185], 0
	v_mfma_f32_16x16x32_bf16 v[28:31], v[136:139], v[208:211], 0
	v_mfma_f32_16x16x32_bf16 v[24:27], v[150:153], v[208:211], 0
	v_mfma_f32_16x16x32_bf16 v[12:15], v[136:139], v[216:219], 0
	v_mfma_f32_16x16x32_bf16 v[8:11], v[150:153], v[216:219], 0
	v_mfma_f32_16x16x32_bf16 v[60:63], v[146:149], v[178:181], v[60:63]
	v_mfma_f32_16x16x32_bf16 v[56:59], v[154:157], v[178:181], v[56:59]
	v_mfma_f32_16x16x32_bf16 v[44:47], v[146:149], v[204:207], v[44:47]
	v_mfma_f32_16x16x32_bf16 v[40:43], v[154:157], v[204:207], v[40:43]
	v_mfma_f32_16x16x32_bf16 v[28:31], v[146:149], v[212:215], v[28:31]
	v_mfma_f32_16x16x32_bf16 v[24:27], v[154:157], v[212:215], v[24:27]
	v_mfma_f32_16x16x32_bf16 v[12:15], v[146:149], v[220:223], v[12:15]
	v_mfma_f32_16x16x32_bf16 v[8:11], v[154:157], v[220:223], v[8:11]
	v_mfma_f32_16x16x32_bf16 v[52:55], v[158:161], v[174:177], 0
	v_mfma_f32_16x16x32_bf16 v[48:51], v[166:169], v[174:177], 0
	v_mfma_f32_16x16x32_bf16 v[36:39], v[158:161], v[182:185], 0
	v_mfma_f32_16x16x32_bf16 v[32:35], v[166:169], v[182:185], 0
	v_mfma_f32_16x16x32_bf16 v[20:23], v[158:161], v[208:211], 0
	v_mfma_f32_16x16x32_bf16 v[16:19], v[166:169], v[208:211], 0
	v_mfma_f32_16x16x32_bf16 v[4:7], v[158:161], v[216:219], 0
	v_mfma_f32_16x16x32_bf16 v[0:3], v[166:169], v[216:219], 0
	v_mfma_f32_16x16x32_bf16 v[52:55], v[162:165], v[178:181], v[52:55]
	v_mfma_f32_16x16x32_bf16 v[48:51], v[170:173], v[178:181], v[48:51]
	v_mfma_f32_16x16x32_bf16 v[36:39], v[162:165], v[204:207], v[36:39]
	v_mfma_f32_16x16x32_bf16 v[32:35], v[170:173], v[204:207], v[32:35]
	v_mfma_f32_16x16x32_bf16 v[20:23], v[162:165], v[212:215], v[20:23]
	v_mfma_f32_16x16x32_bf16 v[16:19], v[170:173], v[212:215], v[16:19]
	v_mfma_f32_16x16x32_bf16 v[4:7], v[162:165], v[220:223], v[4:7]
	v_mfma_f32_16x16x32_bf16 v[0:3], v[170:173], v[220:223], v[0:3]
	s_barrier
	s_setprio 0
	s_add_i32 s57, 0, 0x18000
	s_add_i32 s58, 0, 0x1c000
	v_add_u32_e32 v154, s57, v142
	v_add_u32_e32 v170, s58, v142
	ds_read_b128 v[136:139], v154
	ds_read_b128 v[146:149], v154 offset:1024
	ds_read_b128 v[150:153], v154 offset:2048
	ds_read_b128 v[154:157], v154 offset:3072
	ds_read_b128 v[158:161], v170
	ds_read_b128 v[162:165], v170 offset:1024
	ds_read_b128 v[166:169], v170 offset:2048
	ds_read_b128 v[170:173], v170 offset:3072
	s_mov_b32 m0, s10
	s_nop 0
	global_load_lds_dwordx4 v192, s[44:45]
	s_mov_b32 m0, s12
	s_nop 0
	global_load_lds_dwordx4 v196, s[44:45]
	s_add_u32 s44, s44, 0x80000
	s_addc_u32 s45, s45, 0
	s_mov_b32 m0, s13
	ds_read_b128 v[174:177], v144 offset:32768
	ds_read_b128 v[178:181], v144 offset:33792
	ds_read_b128 v[182:185], v144 offset:34816
	ds_read_b128 v[204:207], v144 offset:35840
	ds_read_b128 v[208:211], v144 offset:36864
	ds_read_b128 v[212:215], v144 offset:37888
	ds_read_b128 v[216:219], v144 offset:38912
	ds_read_b128 v[220:223], v144 offset:39936
	global_load_lds_dwordx4 v192, s[44:45]
	s_mov_b32 m0, s14
	s_nop 0
	global_load_lds_dwordx4 v196, s[44:45]
	s_waitcnt vmcnt(8)
	s_waitcnt lgkmcnt(0)
	s_setprio 1
	s_barrier
; #define PG8_STAGE(bufoff, gbase, voff) do { _Pragma("unroll") for (int _i = 0; _i < 2; ++_i) \
;         __builtin_amdgcn_global_load_lds((const unsigned*)((const char*)(gbase) + (voff)[_i]), (PG8_LAS unsigned*)(lds + (bufoff) + ldsw + _i * 8192), 16, 0, 0); } while (0)
; #define PG8_LDA(dst, b, h) do { _Pragma("unroll") for (int m = 0; m < 4; ++m) _Pragma("unroll") for (int k = 0; k < 2; ++k) dst[m][k] = *(const PG8_LAS bf16x8*)(lds + PG8_SA(b, h) + aoff + m * 2048 + k * 1024); } while (0)
; #define PG8_MMA(ai, bj, At, Bt) do { __builtin_amdgcn_s_setprio(1); _Pragma("unroll") for (int m = 0; m < 4; ++m) _Pragma("unroll") for (int n = 0; n < 2; ++n) _Pragma("unroll") for (int k = 0; k < 2; ++k) \
;         acc[ai][bj][m][n] = __builtin_amdgcn_mfma_f32_16x16x32_bf16(Bt[n][k], At[m][k], acc[ai][bj][m][n], 0, 0, 0); __builtin_amdgcn_s_setprio(0); } while (0)
; #define PG8_WAIT_V(n) asm volatile("s_waitcnt vmcnt(" #n ")" ::: "memory")
; #define PG8_WAIT_L(n) asm volatile("s_waitcnt lgkmcnt(" #n ")" ::: "memory")
; #define PG8_BAR __builtin_amdgcn_s_barrier()
; #define PG8_SCHED __builtin_amdgcn_sched_barrier(0)
; template <class Epi, class Sched, bool ALIGN_EPI = false, bool SP2 = false>
; __device__ __forceinline__ void gemm_phase(PG8_LAS unsigned char* lds, const Gemm g, const Sched& S, const Epi& E) {
;     ...
;         for (int t = 0; t < nt; t += 2) {
;     ...
;             PG8_WAIT_V(8); PG8_WAIT_L(0); PG8_BAR; PG8_MMA(0, 0, At, B0); PG8_MMA(0, 1, At, B1); PG8_BAR; PG8_SCHED;
;             PG8_LDA(At, 1, 1); PG8_STAGE(PG8_SB(1, 0), b3, voffB); PG8_STAGE(PG8_SB(1, 1), b3 + hstepB, voffB); PG8_STAGE(PG8_SA(1, 0), a3, voffA);
;             PG8_WAIT_V(8); PG8_WAIT_L(0); PG8_BAR; PG8_MMA(1, 0, At, B0); PG8_MMA(1, 1, At, B1); PG8_BAR; PG8_SCHED;
	v_mfma_f32_16x16x32_bf16 v[124:127], v[136:139], v[174:177], v[124:127]
	v_mfma_f32_16x16x32_bf16 v[120:123], v[150:153], v[174:177], v[120:123]
	v_mfma_f32_16x16x32_bf16 v[108:111], v[136:139], v[182:185], v[108:111]
	v_mfma_f32_16x16x32_bf16 v[104:107], v[150:153], v[182:185], v[104:107]
	v_mfma_f32_16x16x32_bf16 v[92:95], v[136:139], v[208:211], v[92:95]
	v_mfma_f32_16x16x32_bf16 v[88:91], v[150:153], v[208:211], v[88:91]
	v_mfma_f32_16x16x32_bf16 v[76:79], v[136:139], v[216:219], v[76:79]
	v_mfma_f32_16x16x32_bf16 v[72:75], v[150:153], v[216:219], v[72:75]
	v_mfma_f32_16x16x32_bf16 v[124:127], v[146:149], v[178:181], v[124:127]
	v_mfma_f32_16x16x32_bf16 v[120:123], v[154:157], v[178:181], v[120:123]
	v_mfma_f32_16x16x32_bf16 v[108:111], v[146:149], v[204:207], v[108:111]
	v_mfma_f32_16x16x32_bf16 v[104:107], v[154:157], v[204:207], v[104:107]
	v_mfma_f32_16x16x32_bf16 v[92:95], v[146:149], v[212:215], v[92:95]
	v_mfma_f32_16x16x32_bf16 v[88:91], v[154:157], v[212:215], v[88:91]
	v_mfma_f32_16x16x32_bf16 v[76:79], v[146:149], v[220:223], v[76:79]
	v_mfma_f32_16x16x32_bf16 v[72:75], v[154:157], v[220:223], v[72:75]
	v_mfma_f32_16x16x32_bf16 v[116:119], v[158:161], v[174:177], v[116:119]
	v_mfma_f32_16x16x32_bf16 v[112:115], v[166:169], v[174:177], v[112:115]
	v_mfma_f32_16x16x32_bf16 v[100:103], v[158:161], v[182:185], v[100:103]
	v_mfma_f32_16x16x32_bf16 v[96:99], v[166:169], v[182:185], v[96:99]
	v_mfma_f32_16x16x32_bf16 v[84:87], v[158:161], v[208:211], v[84:87]
	v_mfma_f32_16x16x32_bf16 v[80:83], v[166:169], v[208:211], v[80:83]
	v_mfma_f32_16x16x32_bf16 v[68:71], v[158:161], v[216:219], v[68:71]
	v_mfma_f32_16x16x32_bf16 v[64:67], v[166:169], v[216:219], v[64:67]
	v_mfma_f32_16x16x32_bf16 v[116:119], v[162:165], v[178:181], v[116:119]
	v_mfma_f32_16x16x32_bf16 v[112:115], v[170:173], v[178:181], v[112:115]
	v_mfma_f32_16x16x32_bf16 v[100:103], v[162:165], v[204:207], v[100:103]
	v_mfma_f32_16x16x32_bf16 v[96:99], v[170:173], v[204:207], v[96:99]
	v_mfma_f32_16x16x32_bf16 v[84:87], v[162:165], v[212:215], v[84:87]
	v_mfma_f32_16x16x32_bf16 v[80:83], v[170:173], v[212:215], v[80:83]
	v_mfma_f32_16x16x32_bf16 v[68:71], v[162:165], v[220:223], v[68:71]
	v_mfma_f32_16x16x32_bf16 v[64:67], v[170:173], v[220:223], v[64:67]
	s_barrier
	s_setprio 0
	s_add_u32 s44, s42, 0x8000
	s_addc_u32 s45, s43, 0
	s_add_i32 s57, s57, s2
	s_mov_b32 m0, s57
	ds_read_b128 v[174:177], v144 offset:49152
	ds_read_b128 v[178:181], v144 offset:50176
	ds_read_b128 v[182:185], v144 offset:51200
	ds_read_b128 v[204:207], v144 offset:52224
	ds_read_b128 v[208:211], v144 offset:53248
	ds_read_b128 v[212:215], v144 offset:54272
	ds_read_b128 v[216:219], v144 offset:55296
	ds_read_b128 v[220:223], v144 offset:56320
	global_load_lds_dwordx4 v194, s[44:45]
	s_add_i32 m0, s57, 0x2000
	s_add_u32 s42, s42, 0xc000
	s_addc_u32 s43, s43, 0
	global_load_lds_dwordx4 v198, s[44:45]
	s_add_i32 s44, s58, s2
	s_mov_b32 m0, s44
	s_nop 0
	global_load_lds_dwordx4 v194, s[42:43]
	s_add_i32 m0, s44, 0x2000
	s_nop 0
	global_load_lds_dwordx4 v198, s[42:43]
	s_waitcnt vmcnt(6)
	s_waitcnt lgkmcnt(0)
	s_setprio 1
	s_barrier
	v_mfma_f32_16x16x32_bf16 v[60:63], v[136:139], v[174:177], v[60:63]
	v_mfma_f32_16x16x32_bf16 v[56:59], v[150:153], v[174:177], v[56:59]
	v_mfma_f32_16x16x32_bf16 v[44:47], v[136:139], v[182:185], v[44:47]
	v_mfma_f32_16x16x32_bf16 v[40:43], v[150:153], v[182:185], v[40:43]
	v_mfma_f32_16x16x32_bf16 v[28:31], v[136:139], v[208:211], v[28:31]
	v_mfma_f32_16x16x32_bf16 v[24:27], v[150:153], v[208:211], v[24:27]
	v_mfma_f32_16x16x32_bf16 v[12:15], v[136:139], v[216:219], v[12:15]
	v_mfma_f32_16x16x32_bf16 v[8:11], v[150:153], v[216:219], v[8:11]
	v_mfma_f32_16x16x32_bf16 v[60:63], v[146:149], v[178:181], v[60:63]
	v_mfma_f32_16x16x32_bf16 v[56:59], v[154:157], v[178:181], v[56:59]
	v_mfma_f32_16x16x32_bf16 v[44:47], v[146:149], v[204:207], v[44:47]
	v_mfma_f32_16x16x32_bf16 v[40:43], v[154:157], v[204:207], v[40:43]
	v_mfma_f32_16x16x32_bf16 v[28:31], v[146:149], v[212:215], v[28:31]
	v_mfma_f32_16x16x32_bf16 v[24:27], v[154:157], v[212:215], v[24:27]
	v_mfma_f32_16x16x32_bf16 v[12:15], v[146:149], v[220:223], v[12:15]
	v_mfma_f32_16x16x32_bf16 v[8:11], v[154:157], v[220:223], v[8:11]
	v_mfma_f32_16x16x32_bf16 v[52:55], v[158:161], v[174:177], v[52:55]
	v_mfma_f32_16x16x32_bf16 v[48:51], v[166:169], v[174:177], v[48:51]
	v_mfma_f32_16x16x32_bf16 v[36:39], v[158:161], v[182:185], v[36:39]
	v_mfma_f32_16x16x32_bf16 v[32:35], v[166:169], v[182:185], v[32:35]
	v_mfma_f32_16x16x32_bf16 v[20:23], v[158:161], v[208:211], v[20:23]
	v_mfma_f32_16x16x32_bf16 v[16:19], v[166:169], v[208:211], v[16:19]
	v_mfma_f32_16x16x32_bf16 v[4:7], v[158:161], v[216:219], v[4:7]
	v_mfma_f32_16x16x32_bf16 v[0:3], v[166:169], v[216:219], v[0:3]
	v_mfma_f32_16x16x32_bf16 v[52:55], v[162:165], v[178:181], v[52:55]
	v_mfma_f32_16x16x32_bf16 v[48:51], v[170:173], v[178:181], v[48:51]
	v_mfma_f32_16x16x32_bf16 v[36:39], v[162:165], v[204:207], v[36:39]
	v_mfma_f32_16x16x32_bf16 v[32:35], v[170:173], v[204:207], v[32:35]
	v_mfma_f32_16x16x32_bf16 v[20:23], v[162:165], v[212:215], v[20:23]
	v_mfma_f32_16x16x32_bf16 v[16:19], v[170:173], v[212:215], v[16:19]
	v_mfma_f32_16x16x32_bf16 v[4:7], v[162:165], v[220:223], v[4:7]
	v_mfma_f32_16x16x32_bf16 v[0:3], v[170:173], v[220:223], v[0:3]
	s_barrier
	s_setprio 0
	s_add_i32 s56, s56, 2
	s_add_u32 s54, s54, 0x10000
	s_addc_u32 s55, s55, 0
	s_add_u32 s40, s40, 0x100
	s_addc_u32 s41, s41, 0
	s_cmp_gt_u32 s56, 29
	s_cbranch_scc1 .Lpeel_exit_0

; #define PG8_BAR __builtin_amdgcn_s_barrier()
; template <class Epi, class Sched, bool ALIGN_EPI = false, bool SP2 = false>
; __device__ __forceinline__ void gemm_phase(PG8_LAS unsigned char* lds, const Gemm g, const Sched& S, const Epi& E) {
;     ...
;         if constexpr (ALIGN_EPI) { if (wr == 0) PG8_BAR; }
;         if constexpr (!Epi::AFTER_DRAIN) { if (cur.part < 0) E(acc, cur, wr, wc, fr, fq); else store_part<Epi::PERM>(acc, cur, g.part, wr, wc, fr, fq); S.done(cur); }
.Lpeel_exit_0:
	s_and_b64 vcc, exec, s[24:25]
	s_cbranch_vccz .LBB0_280
	s_barrier

; #define PG8_STAGE(bufoff, gbase, voff) do { _Pragma("unroll") for (int _i = 0; _i < 2; ++_i) \
;         __builtin_amdgcn_global_load_lds((const unsigned*)((const char*)(gbase) + (voff)[_i]), (PG8_LAS unsigned*)(lds + (bufoff) + ldsw + _i * 8192), 16, 0, 0); } while (0)
; #define PG8_LDA(dst, b, h) do { _Pragma("unroll") for (int m = 0; m < 4; ++m) _Pragma("unroll") for (int k = 0; k < 2; ++k) dst[m][k] = *(const PG8_LAS bf16x8*)(lds + PG8_SA(b, h) + aoff + m * 2048 + k * 1024); } while (0)
; #define PG8_LDB(dst, b, h) do { _Pragma("unroll") for (int n = 0; n < 2; ++n) _Pragma("unroll") for (int k = 0; k < 2; ++k) dst[n][k] = *(const PG8_LAS bf16x8*)(lds + PG8_SB(b, h) + boff + n * 2048 + k * 1024); } while (0)
; #define PG8_MMA(ai, bj, At, Bt) do { __builtin_amdgcn_s_setprio(1); _Pragma("unroll") for (int m = 0; m < 4; ++m) _Pragma("unroll") for (int n = 0; n < 2; ++n) _Pragma("unroll") for (int k = 0; k < 2; ++k) \
;         acc[ai][bj][m][n] = __builtin_amdgcn_mfma_f32_16x16x32_bf16(Bt[n][k], At[m][k], acc[ai][bj][m][n], 0, 0, 0); __builtin_amdgcn_s_setprio(0); } while (0)
; #define PG8_WAIT_V(n) asm volatile("s_waitcnt vmcnt(" #n ")" ::: "memory")
; #define PG8_WAIT_L(n) asm volatile("s_waitcnt lgkmcnt(" #n ")" ::: "memory")
; #define PG8_BAR __builtin_amdgcn_s_barrier()
; #define PG8_SCHED __builtin_amdgcn_sched_barrier(0)
; template <class Epi, class Sched, bool ALIGN_EPI = false, bool SP2 = false>
; __device__ __forceinline__ void gemm_phase(PG8_LAS unsigned char* lds, const Gemm g, const Sched& S, const Epi& E) {
;     ...
;             PG8_LDB(B0, 0, 0); PG8_LDB(B1, 0, 1); PG8_SCHED; PG8_LDA(At, 0, 0); PG8_STAGE(PG8_SA(1, 1), a1 + hstepA, voffA);
;             PG8_WAIT_V(8); PG8_WAIT_L(0); PG8_BAR; PG8_MMA(0, 0, At, B0); PG8_MMA(0, 1, At, B1); PG8_BAR; PG8_SCHED;
;             PG8_LDA(At, 0, 1); PG8_STAGE(PG8_SB(0, 0), b2, voffB); PG8_STAGE(PG8_SB(0, 1), b2 + hstepB, voffB); PG8_STAGE(PG8_SA(0, 0), a2, voffA);
;             PG8_WAIT_V(8); PG8_WAIT_L(0); PG8_BAR; PG8_MMA(1, 0, At, B0); PG8_MMA(1, 1, At, B1); PG8_BAR; PG8_SCHED;
.LBB0_359:
	s_add_i32 s27, s54, -2
	s_add_u32 s34, s34, 0xc000
	s_addc_u32 s35, s35, 0
	s_add_u32 s55, s36, 0x10000
	s_addc_u32 s56, s37, 0
	s_mov_b32 s36, 0
	s_waitcnt lgkmcnt(0)
	s_sub_u32 s100, s34, 0x4000
	s_subb_u32 s101, s35, 0
	ds_read_b128 v[140:143], v185
	ds_read_b128 v[144:147], v185 offset:1024
	ds_read_b128 v[148:151], v185 offset:2048
	ds_read_b128 v[152:155], v185 offset:3072
	ds_read_b128 v[156:159], v201
	ds_read_b128 v[160:163], v201 offset:1024
	ds_read_b128 v[164:167], v201 offset:2048
	ds_read_b128 v[168:171], v201 offset:3072
	s_add_i32 s57, s36, 2
	s_add_u32 s37, s34, 0x4000
	s_addc_u32 s38, s35, 0
	s_cmp_eq_u32 s27, s36
	s_cselect_b32 s40, s28, s37
	s_cselect_b32 s41, s29, s38
	s_cselect_b32 s38, s30, s55
	s_cselect_b32 s39, s31, s56
	s_add_u32 s36, s40, 0x8000
	s_addc_u32 s37, s41, 0
	ds_read_b128 v[172:175], v204
	ds_read_b128 v[176:179], v204 offset:1024
	ds_read_b128 v[206:209], v204 offset:2048
	ds_read_b128 v[210:213], v204 offset:3072
	ds_read_b128 v[214:217], v204 offset:4096
	ds_read_b128 v[218:221], v204 offset:5120
	ds_read_b128 v[222:225], v204 offset:6144
	ds_read_b128 v[226:229], v204 offset:7168
	s_mov_b32 m0, s15
	s_nop 0
	global_load_lds_dwordx4 v132, s[100:101]
	s_mov_b32 m0, s42
	s_nop 0
	global_load_lds_dwordx4 v134, s[100:101]
	s_add_i32 m0, s10, 0xc000
	s_nop 0
	global_load_lds_dwordx4 v132, s[34:35]
	s_add_i32 m0, s10, 0xe000
	s_nop 0
	global_load_lds_dwordx4 v134, s[34:35]
	s_waitcnt vmcnt(8)
	s_waitcnt lgkmcnt(0)
	s_setprio 1
	s_barrier
	v_mfma_f32_16x16x32_bf16 v[124:127], v[140:143], v[172:175], 0
	v_mfma_f32_16x16x32_bf16 v[120:123], v[148:151], v[172:175], 0
	v_mfma_f32_16x16x32_bf16 v[108:111], v[140:143], v[206:209], 0
	v_mfma_f32_16x16x32_bf16 v[104:107], v[148:151], v[206:209], 0
	v_mfma_f32_16x16x32_bf16 v[92:95], v[140:143], v[214:217], 0
	v_mfma_f32_16x16x32_bf16 v[88:91], v[148:151], v[214:217], 0
	v_mfma_f32_16x16x32_bf16 v[76:79], v[140:143], v[222:225], 0
	v_mfma_f32_16x16x32_bf16 v[72:75], v[148:151], v[222:225], 0
	v_mfma_f32_16x16x32_bf16 v[124:127], v[144:147], v[176:179], v[124:127]
	v_mfma_f32_16x16x32_bf16 v[120:123], v[152:155], v[176:179], v[120:123]
	v_mfma_f32_16x16x32_bf16 v[108:111], v[144:147], v[210:213], v[108:111]
	v_mfma_f32_16x16x32_bf16 v[104:107], v[152:155], v[210:213], v[104:107]
	v_mfma_f32_16x16x32_bf16 v[92:95], v[144:147], v[218:221], v[92:95]
	v_mfma_f32_16x16x32_bf16 v[88:91], v[152:155], v[218:221], v[88:91]
	v_mfma_f32_16x16x32_bf16 v[76:79], v[144:147], v[226:229], v[76:79]
	v_mfma_f32_16x16x32_bf16 v[72:75], v[152:155], v[226:229], v[72:75]
	v_mfma_f32_16x16x32_bf16 v[116:119], v[156:159], v[172:175], 0
	v_mfma_f32_16x16x32_bf16 v[112:115], v[164:167], v[172:175], 0
	v_mfma_f32_16x16x32_bf16 v[100:103], v[156:159], v[206:209], 0
	v_mfma_f32_16x16x32_bf16 v[96:99], v[164:167], v[206:209], 0
	v_mfma_f32_16x16x32_bf16 v[84:87], v[156:159], v[214:217], 0
	v_mfma_f32_16x16x32_bf16 v[80:83], v[164:167], v[214:217], 0
	v_mfma_f32_16x16x32_bf16 v[68:71], v[156:159], v[222:225], 0
	v_mfma_f32_16x16x32_bf16 v[64:67], v[164:167], v[222:225], 0
	v_mfma_f32_16x16x32_bf16 v[116:119], v[160:163], v[176:179], v[116:119]
	v_mfma_f32_16x16x32_bf16 v[112:115], v[168:171], v[176:179], v[112:115]
	v_mfma_f32_16x16x32_bf16 v[100:103], v[160:163], v[210:213], v[100:103]
	v_mfma_f32_16x16x32_bf16 v[96:99], v[168:171], v[210:213], v[96:99]
	v_mfma_f32_16x16x32_bf16 v[84:87], v[160:163], v[218:221], v[84:87]
	v_mfma_f32_16x16x32_bf16 v[80:83], v[168:171], v[218:221], v[80:83]
	v_mfma_f32_16x16x32_bf16 v[68:71], v[160:163], v[226:229], v[68:71]
	v_mfma_f32_16x16x32_bf16 v[64:67], v[168:171], v[226:229], v[64:67]
	s_barrier
	s_setprio 0
	s_add_i32 s58, s44, s2
	s_mov_b32 m0, s58
	ds_read_b128 v[172:175], v204 offset:16384
	ds_read_b128 v[176:179], v204 offset:17408
	ds_read_b128 v[206:209], v204 offset:18432
	ds_read_b128 v[210:213], v204 offset:19456
	ds_read_b128 v[214:217], v204 offset:20480
	ds_read_b128 v[218:221], v204 offset:21504
	ds_read_b128 v[222:225], v204 offset:22528
	ds_read_b128 v[226:229], v204 offset:23552
	global_load_lds_dwordx4 v128, s[38:39]
	s_add_i32 m0, s58, 0x2000
	s_add_u32 s58, s38, 0x4000
	s_addc_u32 s59, s39, 0
	s_add_i32 s60, s45, s2
	global_load_lds_dwordx4 v130, s[38:39]
	s_mov_b32 m0, s60
	s_nop 0
	global_load_lds_dwordx4 v128, s[58:59]
	s_add_i32 m0, s60, 0x2000
	s_nop 0
	global_load_lds_dwordx4 v130, s[58:59]
	s_waitcnt vmcnt(6)
	s_waitcnt lgkmcnt(0)
	s_setprio 1
	s_barrier
	v_mfma_f32_16x16x32_bf16 v[60:63], v[140:143], v[172:175], 0
	v_mfma_f32_16x16x32_bf16 v[56:59], v[148:151], v[172:175], 0
	v_mfma_f32_16x16x32_bf16 v[44:47], v[140:143], v[206:209], 0
	v_mfma_f32_16x16x32_bf16 v[40:43], v[148:151], v[206:209], 0
	v_mfma_f32_16x16x32_bf16 v[28:31], v[140:143], v[214:217], 0
	v_mfma_f32_16x16x32_bf16 v[24:27], v[148:151], v[214:217], 0
	v_mfma_f32_16x16x32_bf16 v[12:15], v[140:143], v[222:225], 0
	v_mfma_f32_16x16x32_bf16 v[8:11], v[148:151], v[222:225], 0
	v_mfma_f32_16x16x32_bf16 v[60:63], v[144:147], v[176:179], v[60:63]
	v_mfma_f32_16x16x32_bf16 v[56:59], v[152:155], v[176:179], v[56:59]
	v_mfma_f32_16x16x32_bf16 v[44:47], v[144:147], v[210:213], v[44:47]
	v_mfma_f32_16x16x32_bf16 v[40:43], v[152:155], v[210:213], v[40:43]
	v_mfma_f32_16x16x32_bf16 v[28:31], v[144:147], v[218:221], v[28:31]
	v_mfma_f32_16x16x32_bf16 v[24:27], v[152:155], v[218:221], v[24:27]
	v_mfma_f32_16x16x32_bf16 v[12:15], v[144:147], v[226:229], v[12:15]
	v_mfma_f32_16x16x32_bf16 v[8:11], v[152:155], v[226:229], v[8:11]
	v_mfma_f32_16x16x32_bf16 v[52:55], v[156:159], v[172:175], 0
	v_mfma_f32_16x16x32_bf16 v[48:51], v[164:167], v[172:175], 0
	v_mfma_f32_16x16x32_bf16 v[36:39], v[156:159], v[206:209], 0
	v_mfma_f32_16x16x32_bf16 v[32:35], v[164:167], v[206:209], 0
	v_mfma_f32_16x16x32_bf16 v[20:23], v[156:159], v[214:217], 0
	v_mfma_f32_16x16x32_bf16 v[16:19], v[164:167], v[214:217], 0
	v_mfma_f32_16x16x32_bf16 v[4:7], v[156:159], v[222:225], 0
	v_mfma_f32_16x16x32_bf16 v[0:3], v[164:167], v[222:225], 0
	v_mfma_f32_16x16x32_bf16 v[52:55], v[160:163], v[176:179], v[52:55]
	v_mfma_f32_16x16x32_bf16 v[48:51], v[168:171], v[176:179], v[48:51]
	v_mfma_f32_16x16x32_bf16 v[36:39], v[160:163], v[210:213], v[36:39]
	v_mfma_f32_16x16x32_bf16 v[32:35], v[168:171], v[210:213], v[32:35]
	v_mfma_f32_16x16x32_bf16 v[20:23], v[160:163], v[218:221], v[20:23]
	v_mfma_f32_16x16x32_bf16 v[16:19], v[168:171], v[218:221], v[16:19]
	v_mfma_f32_16x16x32_bf16 v[4:7], v[160:163], v[226:229], v[4:7]
	v_mfma_f32_16x16x32_bf16 v[0:3], v[168:171], v[226:229], v[0:3]
	s_barrier
; #define PG8_STAGE(bufoff, gbase, voff) do { _Pragma("unroll") for (int _i = 0; _i < 2; ++_i) \
;         __builtin_amdgcn_global_load_lds((const unsigned*)((const char*)(gbase) + (voff)[_i]), (PG8_LAS unsigned*)(lds + (bufoff) + ldsw + _i * 8192), 16, 0, 0); } while (0)
; #define PG8_LDA(dst, b, h) do { _Pragma("unroll") for (int m = 0; m < 4; ++m) _Pragma("unroll") for (int k = 0; k < 2; ++k) dst[m][k] = *(const PG8_LAS bf16x8*)(lds + PG8_SA(b, h) + aoff + m * 2048 + k * 1024); } while (0)
; #define PG8_LDB(dst, b, h) do { _Pragma("unroll") for (int n = 0; n < 2; ++n) _Pragma("unroll") for (int k = 0; k < 2; ++k) dst[n][k] = *(const PG8_LAS bf16x8*)(lds + PG8_SB(b, h) + boff + n * 2048 + k * 1024); } while (0)
; #define PG8_MMA(ai, bj, At, Bt) do { __builtin_amdgcn_s_setprio(1); _Pragma("unroll") for (int m = 0; m < 4; ++m) _Pragma("unroll") for (int n = 0; n < 2; ++n) _Pragma("unroll") for (int k = 0; k < 2; ++k) \
;         acc[ai][bj][m][n] = __builtin_amdgcn_mfma_f32_16x16x32_bf16(Bt[n][k], At[m][k], acc[ai][bj][m][n], 0, 0, 0); __builtin_amdgcn_s_setprio(0); } while (0)
; #define PG8_WAIT_V(n) asm volatile("s_waitcnt vmcnt(" #n ")" ::: "memory")
; #define PG8_WAIT_L(n) asm volatile("s_waitcnt lgkmcnt(" #n ")" ::: "memory")
; #define PG8_BAR __builtin_amdgcn_s_barrier()
; #define PG8_SCHED __builtin_amdgcn_sched_barrier(0)
; template <class Epi, class Sched, bool ALIGN_EPI = false, bool SP2 = false>
; __device__ __forceinline__ void gemm_phase(PG8_LAS unsigned char* lds, const Gemm g, const Sched& S, const Epi& E) {
;     ...
;             PG8_LDB(B0, 1, 0); PG8_LDB(B1, 1, 1); PG8_SCHED; PG8_LDA(At, 1, 0); PG8_STAGE(PG8_SA(0, 1), a2 + hstepA, voffA);
;             PG8_WAIT_V(8); PG8_WAIT_L(0); PG8_BAR; PG8_MMA(0, 0, At, B0); PG8_MMA(0, 1, At, B1); PG8_BAR; PG8_SCHED;
;             PG8_LDA(At, 1, 1); PG8_STAGE(PG8_SB(1, 0), b3, voffB); PG8_STAGE(PG8_SB(1, 1), b3 + hstepB, voffB); PG8_STAGE(PG8_SA(1, 0), a3, voffA);
;             PG8_WAIT_V(8); PG8_WAIT_L(0); PG8_BAR; PG8_MMA(1, 0, At, B0); PG8_MMA(1, 1, At, B1); PG8_BAR; PG8_SCHED;
	s_setprio 0
	s_add_i32 s58, 0, 0x18000
	s_add_i32 s59, 0, 0x1c000
	v_add_u32_e32 v152, s58, v183
	v_add_u32_e32 v168, s59, v183
	ds_read_b128 v[140:143], v152
	ds_read_b128 v[144:147], v152 offset:1024
	ds_read_b128 v[148:151], v152 offset:2048
	ds_read_b128 v[152:155], v152 offset:3072
	ds_read_b128 v[156:159], v168
	ds_read_b128 v[160:163], v168 offset:1024
	ds_read_b128 v[164:167], v168 offset:2048
	ds_read_b128 v[168:171], v168 offset:3072
	s_mov_b32 m0, s10
	s_nop 0
	global_load_lds_dwordx4 v128, s[40:41]
	s_mov_b32 m0, s12
	s_nop 0
	global_load_lds_dwordx4 v130, s[40:41]
	s_add_u32 s40, s40, 0x4000
	s_addc_u32 s41, s41, 0
	s_mov_b32 m0, s13
	ds_read_b128 v[172:175], v204 offset:32768
	ds_read_b128 v[176:179], v204 offset:33792
	ds_read_b128 v[206:209], v204 offset:34816
	ds_read_b128 v[210:213], v204 offset:35840
	ds_read_b128 v[214:217], v204 offset:36864
	ds_read_b128 v[218:221], v204 offset:37888
	ds_read_b128 v[222:225], v204 offset:38912
	ds_read_b128 v[226:229], v204 offset:39936
	global_load_lds_dwordx4 v128, s[40:41]
	s_mov_b32 m0, s14
	s_nop 0
	global_load_lds_dwordx4 v130, s[40:41]
	s_waitcnt vmcnt(8)
	s_waitcnt lgkmcnt(0)
	s_setprio 1
	s_barrier
	v_mfma_f32_16x16x32_bf16 v[124:127], v[140:143], v[172:175], v[124:127]
	v_mfma_f32_16x16x32_bf16 v[120:123], v[148:151], v[172:175], v[120:123]
	v_mfma_f32_16x16x32_bf16 v[108:111], v[140:143], v[206:209], v[108:111]
	v_mfma_f32_16x16x32_bf16 v[104:107], v[148:151], v[206:209], v[104:107]
	v_mfma_f32_16x16x32_bf16 v[92:95], v[140:143], v[214:217], v[92:95]
	v_mfma_f32_16x16x32_bf16 v[88:91], v[148:151], v[214:217], v[88:91]
	v_mfma_f32_16x16x32_bf16 v[76:79], v[140:143], v[222:225], v[76:79]
	v_mfma_f32_16x16x32_bf16 v[72:75], v[148:151], v[222:225], v[72:75]
	v_mfma_f32_16x16x32_bf16 v[124:127], v[144:147], v[176:179], v[124:127]
	v_mfma_f32_16x16x32_bf16 v[120:123], v[152:155], v[176:179], v[120:123]
	v_mfma_f32_16x16x32_bf16 v[108:111], v[144:147], v[210:213], v[108:111]
	v_mfma_f32_16x16x32_bf16 v[104:107], v[152:155], v[210:213], v[104:107]
	v_mfma_f32_16x16x32_bf16 v[92:95], v[144:147], v[218:221], v[92:95]
	v_mfma_f32_16x16x32_bf16 v[88:91], v[152:155], v[218:221], v[88:91]
	v_mfma_f32_16x16x32_bf16 v[76:79], v[144:147], v[226:229], v[76:79]
	v_mfma_f32_16x16x32_bf16 v[72:75], v[152:155], v[226:229], v[72:75]
	v_mfma_f32_16x16x32_bf16 v[116:119], v[156:159], v[172:175], v[116:119]
	v_mfma_f32_16x16x32_bf16 v[112:115], v[164:167], v[172:175], v[112:115]
	v_mfma_f32_16x16x32_bf16 v[100:103], v[156:159], v[206:209], v[100:103]
	v_mfma_f32_16x16x32_bf16 v[96:99], v[164:167], v[206:209], v[96:99]
	v_mfma_f32_16x16x32_bf16 v[84:87], v[156:159], v[214:217], v[84:87]
	v_mfma_f32_16x16x32_bf16 v[80:83], v[164:167], v[214:217], v[80:83]
	v_mfma_f32_16x16x32_bf16 v[68:71], v[156:159], v[222:225], v[68:71]
	v_mfma_f32_16x16x32_bf16 v[64:67], v[164:167], v[222:225], v[64:67]
	v_mfma_f32_16x16x32_bf16 v[116:119], v[160:163], v[176:179], v[116:119]
	v_mfma_f32_16x16x32_bf16 v[112:115], v[168:171], v[176:179], v[112:115]
	v_mfma_f32_16x16x32_bf16 v[100:103], v[160:163], v[210:213], v[100:103]
	v_mfma_f32_16x16x32_bf16 v[96:99], v[168:171], v[210:213], v[96:99]
	v_mfma_f32_16x16x32_bf16 v[84:87], v[160:163], v[218:221], v[84:87]
	v_mfma_f32_16x16x32_bf16 v[80:83], v[168:171], v[218:221], v[80:83]
	v_mfma_f32_16x16x32_bf16 v[68:71], v[160:163], v[226:229], v[68:71]
	v_mfma_f32_16x16x32_bf16 v[64:67], v[168:171], v[226:229], v[64:67]
	s_barrier
	s_setprio 0
	s_add_u32 s40, s38, 0x8000
	s_addc_u32 s41, s39, 0
	s_add_i32 s58, s58, s2
	s_mov_b32 m0, s58
	ds_read_b128 v[172:175], v204 offset:49152
	ds_read_b128 v[176:179], v204 offset:50176
	ds_read_b128 v[206:209], v204 offset:51200
	ds_read_b128 v[210:213], v204 offset:52224
	ds_read_b128 v[214:217], v204 offset:53248
	ds_read_b128 v[218:221], v204 offset:54272
	ds_read_b128 v[222:225], v204 offset:55296
	ds_read_b128 v[226:229], v204 offset:56320
	global_load_lds_dwordx4 v128, s[40:41]
	s_add_i32 m0, s58, 0x2000
	s_add_u32 s38, s38, 0xc000
	s_addc_u32 s39, s39, 0
	global_load_lds_dwordx4 v130, s[40:41]
	s_add_i32 s40, s59, s2
	s_mov_b32 m0, s40
	s_nop 0
	global_load_lds_dwordx4 v128, s[38:39]
	s_add_i32 m0, s40, 0x2000
	s_nop 0
	global_load_lds_dwordx4 v130, s[38:39]
	s_waitcnt vmcnt(6)
	s_waitcnt lgkmcnt(0)
	s_setprio 1
	s_barrier
	v_mfma_f32_16x16x32_bf16 v[60:63], v[140:143], v[172:175], v[60:63]
	v_mfma_f32_16x16x32_bf16 v[56:59], v[148:151], v[172:175], v[56:59]
	v_mfma_f32_16x16x32_bf16 v[44:47], v[140:143], v[206:209], v[44:47]
	v_mfma_f32_16x16x32_bf16 v[40:43], v[148:151], v[206:209], v[40:43]
	v_mfma_f32_16x16x32_bf16 v[28:31], v[140:143], v[214:217], v[28:31]
	v_mfma_f32_16x16x32_bf16 v[24:27], v[148:151], v[214:217], v[24:27]
	v_mfma_f32_16x16x32_bf16 v[12:15], v[140:143], v[222:225], v[12:15]
	v_mfma_f32_16x16x32_bf16 v[8:11], v[148:151], v[222:225], v[8:11]
	v_mfma_f32_16x16x32_bf16 v[60:63], v[144:147], v[176:179], v[60:63]
	v_mfma_f32_16x16x32_bf16 v[56:59], v[152:155], v[176:179], v[56:59]
	v_mfma_f32_16x16x32_bf16 v[44:47], v[144:147], v[210:213], v[44:47]
	v_mfma_f32_16x16x32_bf16 v[40:43], v[152:155], v[210:213], v[40:43]
	v_mfma_f32_16x16x32_bf16 v[28:31], v[144:147], v[218:221], v[28:31]
	v_mfma_f32_16x16x32_bf16 v[24:27], v[152:155], v[218:221], v[24:27]
	v_mfma_f32_16x16x32_bf16 v[12:15], v[144:147], v[226:229], v[12:15]
	v_mfma_f32_16x16x32_bf16 v[8:11], v[152:155], v[226:229], v[8:11]
	v_mfma_f32_16x16x32_bf16 v[52:55], v[156:159], v[172:175], v[52:55]
	v_mfma_f32_16x16x32_bf16 v[48:51], v[164:167], v[172:175], v[48:51]
	v_mfma_f32_16x16x32_bf16 v[36:39], v[156:159], v[206:209], v[36:39]
	v_mfma_f32_16x16x32_bf16 v[32:35], v[164:167], v[206:209], v[32:35]
	v_mfma_f32_16x16x32_bf16 v[20:23], v[156:159], v[214:217], v[20:23]
	v_mfma_f32_16x16x32_bf16 v[16:19], v[164:167], v[214:217], v[16:19]
	v_mfma_f32_16x16x32_bf16 v[4:7], v[156:159], v[222:225], v[4:7]
	v_mfma_f32_16x16x32_bf16 v[0:3], v[164:167], v[222:225], v[0:3]
	v_mfma_f32_16x16x32_bf16 v[52:55], v[160:163], v[176:179], v[52:55]
	v_mfma_f32_16x16x32_bf16 v[48:51], v[168:171], v[176:179], v[48:51]
	v_mfma_f32_16x16x32_bf16 v[36:39], v[160:163], v[210:213], v[36:39]
	v_mfma_f32_16x16x32_bf16 v[32:35], v[168:171], v[210:213], v[32:35]
	v_mfma_f32_16x16x32_bf16 v[20:23], v[160:163], v[218:221], v[20:23]
	v_mfma_f32_16x16x32_bf16 v[16:19], v[168:171], v[218:221], v[16:19]
	v_mfma_f32_16x16x32_bf16 v[4:7], v[160:163], v[226:229], v[4:7]
	v_mfma_f32_16x16x32_bf16 v[0:3], v[168:171], v[226:229], v[0:3]
	s_barrier
	s_setprio 0
	s_add_u32 s34, s34, 0x10000
	s_addc_u32 s35, s35, 0
	s_add_u32 s55, s55, 0x10000
	s_addc_u32 s56, s56, 0
	s_cmp_ge_i32 s57, s54
	s_mov_b32 s36, s57
	s_cbranch_scc1 .Lpeel_exit_1

; #define PG8_BAR __builtin_amdgcn_s_barrier()
; template <class Epi, class Sched, bool ALIGN_EPI = false, bool SP2 = false>
; __device__ __forceinline__ void gemm_phase(PG8_LAS unsigned char* lds, const Gemm g, const Sched& S, const Epi& E) {
;     ...
;         if constexpr (ALIGN_EPI) { if (wr == 0) PG8_BAR; }
;         if constexpr (!Epi::AFTER_DRAIN) { if (cur.part < 0) E(acc, cur, wr, wc, fr, fq); else store_part<Epi::PERM>(acc, cur, g.part, wr, wc, fr, fq); S.done(cur); }
.Lpeel_exit_1:
	s_and_b64 vcc, exec, s[24:25]
	s_cbranch_vccnz .LBB0_365
	s_mov_b64 s[34:35], -1
	s_cmp_gt_i32 s20, -1
	v_lshl_or_b32 v140, s53, 8, v184
	s_cbranch_scc1 .LBB0_366

; #define PG8_STAGE(bufoff, gbase, voff) do { _Pragma("unroll") for (int _i = 0; _i < 2; ++_i) \
;         __builtin_amdgcn_global_load_lds((const unsigned*)((const char*)(gbase) + (voff)[_i]), (PG8_LAS unsigned*)(lds + (bufoff) + ldsw + _i * 8192), 16, 0, 0); } while (0)
; #define PG8_LDA(dst, b, h) do { _Pragma("unroll") for (int m = 0; m < 4; ++m) _Pragma("unroll") for (int k = 0; k < 2; ++k) dst[m][k] = *(const PG8_LAS bf16x8*)(lds + PG8_SA(b, h) + aoff + m * 2048 + k * 1024); } while (0)
; #define PG8_LDB(dst, b, h) do { _Pragma("unroll") for (int n = 0; n < 2; ++n) _Pragma("unroll") for (int k = 0; k < 2; ++k) dst[n][k] = *(const PG8_LAS bf16x8*)(lds + PG8_SB(b, h) + boff + n * 2048 + k * 1024); } while (0)
; #define PG8_MMA(ai, bj, At, Bt) do { __builtin_amdgcn_s_setprio(1); _Pragma("unroll") for (int m = 0; m < 4; ++m) _Pragma("unroll") for (int n = 0; n < 2; ++n) _Pragma("unroll") for (int k = 0; k < 2; ++k) \
;         acc[ai][bj][m][n] = __builtin_amdgcn_mfma_f32_16x16x32_bf16(Bt[n][k], At[m][k], acc[ai][bj][m][n], 0, 0, 0); __builtin_amdgcn_s_setprio(0); } while (0)
; #define PG8_WAIT_V(n) asm volatile("s_waitcnt vmcnt(" #n ")" ::: "memory")
; #define PG8_WAIT_L(n) asm volatile("s_waitcnt lgkmcnt(" #n ")" ::: "memory")
; template <class Epi, class Sched, bool ALIGN_EPI = false, bool SP2 = false>
; __device__ __forceinline__ void gemm_phase(PG8_LAS unsigned char* lds, const Gemm g, const Sched& S, const Epi& E) {
;     ...
;             const bool last = (t == nt - 2);
;             const char* a1 = cA + (size_t)(t + 1) * kstepA;
;             const char* a2 = last ? nA : cA + (size_t)(t + 2) * kstepA; const char* b2 = last ? nB : cB + (size_t)(t + 2) * kstepB;
;             const char* a3 = a2 + kstepA; const char* b3 = b2 + kstepB;
;             if (last && has_next) S.a_ready(nxt);
;             if constexpr (SP2) {
;             PG8_LDB(B0, 0, 0); PG8_LDB(B1, 0, 1); PG8_SCHED; PG8_LDA(At, 0, 0); PG8_STAGE(PG8_SA(1, 1), a1 + hstepA, voffA);
;             PG8_WAIT_V(8); PG8_WAIT_L(0); PG8_BAR; PG8_MMA(0, 0, At, B0); PG8_MMA(0, 1, At, B1); PG8_BAR; PG8_SCHED;
;             PG8_LDA(At, 0, 1); PG8_STAGE(PG8_SB(0, 0), b2, voffB); PG8_STAGE(PG8_SB(0, 1), b2 + hstepB, voffB); PG8_STAGE(PG8_SA(0, 0), a2, voffA);
;             PG8_WAIT_V(8); PG8_WAIT_L(0); PG8_BAR; PG8_MMA(1, 0, At, B0); PG8_MMA(1, 1, At, B1); PG8_BAR; PG8_SCHED;
.Lhf4:
	s_ashr_i32 s27, s26, 31
	s_lshl_b64 s[30:31], s[26:27], 20
	s_add_u32 s30, s96, s30
	s_addc_u32 s31, s97, s31
	s_and_b64 s[34:35], s[28:29], exec
	s_cselect_b32 s1, s31, s41
	s_cselect_b32 s27, s30, s40
	s_ashr_i32 s25, s24, 31
	s_lshl_b64 s[34:35], s[24:25], 20
	s_add_u32 s34, s10, s34
	s_addc_u32 s35, s12, s35
	s_and_b64 s[42:43], s[28:29], exec
	s_cselect_b32 s25, s35, s39
	s_cselect_b32 s37, s34, s38
	s_add_u32 s53, s38, 0x10000
	s_addc_u32 s54, s39, 0
	s_add_u32 s38, s40, 0x80080
	s_addc_u32 s39, s41, 0
	s_mov_b32 s55, -2
	s_sub_u32 s100, s38, 0x80000
	s_subb_u32 s101, s39, 0
	ds_read_b128 v[132:135], v147
	ds_read_b128 v[136:139], v147 offset:1024
	ds_read_b128 v[140:143], v147 offset:2048
	ds_read_b128 v[152:155], v147 offset:3072
	ds_read_b128 v[156:159], v148
	ds_read_b128 v[160:163], v148 offset:1024
	ds_read_b128 v[164:167], v148 offset:2048
	ds_read_b128 v[168:171], v148 offset:3072
	s_add_u32 s40, s38, 0xfff80080
	s_addc_u32 s41, s39, -1
	s_cmp_eq_u32 s55, 28
	s_cselect_b32 s43, s1, s41
	s_cselect_b32 s42, s27, s40
	s_cselect_b32 s41, s25, s54
	s_cselect_b32 s40, s37, s53
	ds_read_b128 v[172:175], v149
	ds_read_b128 v[176:179], v149 offset:1024
	ds_read_b128 v[180:183], v149 offset:2048
	ds_read_b128 v[204:207], v149 offset:3072
	ds_read_b128 v[208:211], v149 offset:4096
	ds_read_b128 v[212:215], v149 offset:5120
	ds_read_b128 v[216:219], v149 offset:6144
	ds_read_b128 v[220:223], v149 offset:7168
	s_mov_b32 m0, s48
	s_nop 0
	global_load_lds_dwordx4 v128, s[100:101]
	s_mov_b32 m0, s49
	s_nop 0
	global_load_lds_dwordx4 v130, s[100:101]
	s_add_i32 m0, s13, 0xc000
	s_nop 0
	global_load_lds_dwordx4 v128, s[38:39]
	s_add_i32 m0, s13, 0xe000
	s_nop 0
	global_load_lds_dwordx4 v130, s[38:39]
	s_waitcnt vmcnt(8)
	s_waitcnt lgkmcnt(0)
	s_setprio 1
	s_barrier
	v_mfma_f32_16x16x32_bf16 v[124:127], v[132:135], v[172:175], 0
	v_mfma_f32_16x16x32_bf16 v[120:123], v[140:143], v[172:175], 0
	v_mfma_f32_16x16x32_bf16 v[108:111], v[132:135], v[180:183], 0
	v_mfma_f32_16x16x32_bf16 v[104:107], v[140:143], v[180:183], 0
	v_mfma_f32_16x16x32_bf16 v[92:95], v[132:135], v[208:211], 0
	v_mfma_f32_16x16x32_bf16 v[88:91], v[140:143], v[208:211], 0
	v_mfma_f32_16x16x32_bf16 v[76:79], v[132:135], v[216:219], 0
	v_mfma_f32_16x16x32_bf16 v[72:75], v[140:143], v[216:219], 0
	v_mfma_f32_16x16x32_bf16 v[124:127], v[136:139], v[176:179], v[124:127]
	v_mfma_f32_16x16x32_bf16 v[120:123], v[152:155], v[176:179], v[120:123]
	v_mfma_f32_16x16x32_bf16 v[108:111], v[136:139], v[204:207], v[108:111]
	v_mfma_f32_16x16x32_bf16 v[104:107], v[152:155], v[204:207], v[104:107]
	v_mfma_f32_16x16x32_bf16 v[92:95], v[136:139], v[212:215], v[92:95]
	v_mfma_f32_16x16x32_bf16 v[88:91], v[152:155], v[212:215], v[88:91]
	v_mfma_f32_16x16x32_bf16 v[76:79], v[136:139], v[220:223], v[76:79]
	v_mfma_f32_16x16x32_bf16 v[72:75], v[152:155], v[220:223], v[72:75]
	v_mfma_f32_16x16x32_bf16 v[116:119], v[156:159], v[172:175], 0
	v_mfma_f32_16x16x32_bf16 v[112:115], v[164:167], v[172:175], 0
	v_mfma_f32_16x16x32_bf16 v[100:103], v[156:159], v[180:183], 0
	v_mfma_f32_16x16x32_bf16 v[96:99], v[164:167], v[180:183], 0
	v_mfma_f32_16x16x32_bf16 v[84:87], v[156:159], v[208:211], 0
	v_mfma_f32_16x16x32_bf16 v[80:83], v[164:167], v[208:211], 0
	v_mfma_f32_16x16x32_bf16 v[68:71], v[156:159], v[216:219], 0
	v_mfma_f32_16x16x32_bf16 v[64:67], v[164:167], v[216:219], 0
	v_mfma_f32_16x16x32_bf16 v[116:119], v[160:163], v[176:179], v[116:119]
	v_mfma_f32_16x16x32_bf16 v[112:115], v[168:171], v[176:179], v[112:115]
	v_mfma_f32_16x16x32_bf16 v[100:103], v[160:163], v[204:207], v[100:103]
	v_mfma_f32_16x16x32_bf16 v[96:99], v[168:171], v[204:207], v[96:99]
	v_mfma_f32_16x16x32_bf16 v[84:87], v[160:163], v[212:215], v[84:87]
	v_mfma_f32_16x16x32_bf16 v[80:83], v[168:171], v[212:215], v[80:83]
	v_mfma_f32_16x16x32_bf16 v[68:71], v[160:163], v[220:223], v[68:71]
	v_mfma_f32_16x16x32_bf16 v[64:67], v[168:171], v[220:223], v[64:67]
	s_barrier
	s_setprio 0
	s_add_i32 s56, s50, s2
	s_mov_b32 m0, s56
	ds_read_b128 v[172:175], v149 offset:16384
	ds_read_b128 v[176:179], v149 offset:17408
	ds_read_b128 v[180:183], v149 offset:18432
	ds_read_b128 v[204:207], v149 offset:19456
	ds_read_b128 v[208:211], v149 offset:20480
	ds_read_b128 v[212:215], v149 offset:21504
	ds_read_b128 v[216:219], v149 offset:22528
	ds_read_b128 v[220:223], v149 offset:23552
	global_load_lds_dwordx4 v194, s[40:41]
	s_add_i32 m0, s56, 0x2000
	s_add_u32 s56, s40, 0x4000
	s_addc_u32 s57, s41, 0
	s_add_i32 s58, s51, s2
	global_load_lds_dwordx4 v198, s[40:41]
	s_mov_b32 m0, s58
	s_nop 0
	global_load_lds_dwordx4 v194, s[56:57]
	s_add_i32 m0, s58, 0x2000
	s_nop 0
	global_load_lds_dwordx4 v198, s[56:57]
	s_waitcnt vmcnt(6)
	s_waitcnt lgkmcnt(0)
	s_setprio 1
	s_barrier
; #define PG8_STAGE(bufoff, gbase, voff) do { _Pragma("unroll") for (int _i = 0; _i < 2; ++_i) \
;         __builtin_amdgcn_global_load_lds((const unsigned*)((const char*)(gbase) + (voff)[_i]), (PG8_LAS unsigned*)(lds + (bufoff) + ldsw + _i * 8192), 16, 0, 0); } while (0)
; #define PG8_LDA(dst, b, h) do { _Pragma("unroll") for (int m = 0; m < 4; ++m) _Pragma("unroll") for (int k = 0; k < 2; ++k) dst[m][k] = *(const PG8_LAS bf16x8*)(lds + PG8_SA(b, h) + aoff + m * 2048 + k * 1024); } while (0)
; #define PG8_LDB(dst, b, h) do { _Pragma("unroll") for (int n = 0; n < 2; ++n) _Pragma("unroll") for (int k = 0; k < 2; ++k) dst[n][k] = *(const PG8_LAS bf16x8*)(lds + PG8_SB(b, h) + boff + n * 2048 + k * 1024); } while (0)
; #define PG8_MMA(ai, bj, At, Bt) do { __builtin_amdgcn_s_setprio(1); _Pragma("unroll") for (int m = 0; m < 4; ++m) _Pragma("unroll") for (int n = 0; n < 2; ++n) _Pragma("unroll") for (int k = 0; k < 2; ++k) \
;         acc[ai][bj][m][n] = __builtin_amdgcn_mfma_f32_16x16x32_bf16(Bt[n][k], At[m][k], acc[ai][bj][m][n], 0, 0, 0); __builtin_amdgcn_s_setprio(0); } while (0)
; #define PG8_WAIT_V(n) asm volatile("s_waitcnt vmcnt(" #n ")" ::: "memory")
; #define PG8_WAIT_L(n) asm volatile("s_waitcnt lgkmcnt(" #n ")" ::: "memory")
; #define PG8_BAR __builtin_amdgcn_s_barrier()
; #define PG8_SCHED __builtin_amdgcn_sched_barrier(0)
; template <class Epi, class Sched, bool ALIGN_EPI = false, bool SP2 = false>
; __device__ __forceinline__ void gemm_phase(PG8_LAS unsigned char* lds, const Gemm g, const Sched& S, const Epi& E) {
;     ...
;             PG8_WAIT_V(8); PG8_WAIT_L(0); PG8_BAR; PG8_MMA(1, 0, At, B0); PG8_MMA(1, 1, At, B1); PG8_BAR; PG8_SCHED;
;             PG8_LDB(B0, 1, 0); PG8_LDB(B1, 1, 1); PG8_SCHED; PG8_LDA(At, 1, 0); PG8_STAGE(PG8_SA(0, 1), a2 + hstepA, voffA);
	v_mfma_f32_16x16x32_bf16 v[60:63], v[132:135], v[172:175], 0
	v_mfma_f32_16x16x32_bf16 v[56:59], v[140:143], v[172:175], 0
	v_mfma_f32_16x16x32_bf16 v[44:47], v[132:135], v[180:183], 0
	v_mfma_f32_16x16x32_bf16 v[40:43], v[140:143], v[180:183], 0
	v_mfma_f32_16x16x32_bf16 v[28:31], v[132:135], v[208:211], 0
	v_mfma_f32_16x16x32_bf16 v[24:27], v[140:143], v[208:211], 0
	v_mfma_f32_16x16x32_bf16 v[12:15], v[132:135], v[216:219], 0
	v_mfma_f32_16x16x32_bf16 v[8:11], v[140:143], v[216:219], 0
	v_mfma_f32_16x16x32_bf16 v[60:63], v[136:139], v[176:179], v[60:63]
	v_mfma_f32_16x16x32_bf16 v[56:59], v[152:155], v[176:179], v[56:59]
	v_mfma_f32_16x16x32_bf16 v[44:47], v[136:139], v[204:207], v[44:47]
	v_mfma_f32_16x16x32_bf16 v[40:43], v[152:155], v[204:207], v[40:43]
	v_mfma_f32_16x16x32_bf16 v[28:31], v[136:139], v[212:215], v[28:31]
	v_mfma_f32_16x16x32_bf16 v[24:27], v[152:155], v[212:215], v[24:27]
	v_mfma_f32_16x16x32_bf16 v[12:15], v[136:139], v[220:223], v[12:15]
	v_mfma_f32_16x16x32_bf16 v[8:11], v[152:155], v[220:223], v[8:11]
	v_mfma_f32_16x16x32_bf16 v[52:55], v[156:159], v[172:175], 0
	v_mfma_f32_16x16x32_bf16 v[48:51], v[164:167], v[172:175], 0
	v_mfma_f32_16x16x32_bf16 v[36:39], v[156:159], v[180:183], 0
	v_mfma_f32_16x16x32_bf16 v[32:35], v[164:167], v[180:183], 0
	v_mfma_f32_16x16x32_bf16 v[20:23], v[156:159], v[208:211], 0
	v_mfma_f32_16x16x32_bf16 v[16:19], v[164:167], v[208:211], 0
	v_mfma_f32_16x16x32_bf16 v[4:7], v[156:159], v[216:219], 0
	v_mfma_f32_16x16x32_bf16 v[0:3], v[164:167], v[216:219], 0
	v_mfma_f32_16x16x32_bf16 v[52:55], v[160:163], v[176:179], v[52:55]
	v_mfma_f32_16x16x32_bf16 v[48:51], v[168:171], v[176:179], v[48:51]
	v_mfma_f32_16x16x32_bf16 v[36:39], v[160:163], v[204:207], v[36:39]
	v_mfma_f32_16x16x32_bf16 v[32:35], v[168:171], v[204:207], v[32:35]
	v_mfma_f32_16x16x32_bf16 v[20:23], v[160:163], v[212:215], v[20:23]
	v_mfma_f32_16x16x32_bf16 v[16:19], v[168:171], v[212:215], v[16:19]
	v_mfma_f32_16x16x32_bf16 v[4:7], v[160:163], v[220:223], v[4:7]
	v_mfma_f32_16x16x32_bf16 v[0:3], v[168:171], v[220:223], v[0:3]
	s_barrier
	s_setprio 0
	s_add_i32 s56, 0, 0x18000
	v_add_u32_e32 v151, s56, v145
	s_add_i32 s57, 0, 0x1c000
	ds_read_b128 v[132:135], v151
	ds_read_b128 v[136:139], v151 offset:1024
	ds_read_b128 v[140:143], v151 offset:2048
	ds_read_b128 v[152:155], v151 offset:3072
	v_add_u32_e32 v151, s57, v145
	ds_read_b128 v[156:159], v151
	ds_read_b128 v[160:163], v151 offset:1024
	ds_read_b128 v[164:167], v151 offset:2048
	ds_read_b128 v[168:171], v151 offset:3072
	s_mov_b32 m0, s13
	s_nop 0
	global_load_lds_dwordx4 v192, s[42:43]
	s_mov_b32 m0, s14
	s_nop 0
	global_load_lds_dwordx4 v196, s[42:43]
	s_add_u32 s42, s42, 0x80000
	s_addc_u32 s43, s43, 0
	s_mov_b32 m0, s15
	ds_read_b128 v[172:175], v149 offset:32768
	ds_read_b128 v[176:179], v149 offset:33792
	ds_read_b128 v[180:183], v149 offset:34816
	ds_read_b128 v[204:207], v149 offset:35840
	ds_read_b128 v[208:211], v149 offset:36864
	ds_read_b128 v[212:215], v149 offset:37888
	ds_read_b128 v[216:219], v149 offset:38912
	ds_read_b128 v[220:223], v149 offset:39936
	global_load_lds_dwordx4 v192, s[42:43]
	s_mov_b32 m0, s44
	s_nop 0
	global_load_lds_dwordx4 v196, s[42:43]
	s_waitcnt vmcnt(8)
	s_waitcnt lgkmcnt(0)
	s_setprio 1
	s_barrier
; #define PG8_STAGE(bufoff, gbase, voff) do { _Pragma("unroll") for (int _i = 0; _i < 2; ++_i) \
;         __builtin_amdgcn_global_load_lds((const unsigned*)((const char*)(gbase) + (voff)[_i]), (PG8_LAS unsigned*)(lds + (bufoff) + ldsw + _i * 8192), 16, 0, 0); } while (0)
; #define PG8_LDA(dst, b, h) do { _Pragma("unroll") for (int m = 0; m < 4; ++m) _Pragma("unroll") for (int k = 0; k < 2; ++k) dst[m][k] = *(const PG8_LAS bf16x8*)(lds + PG8_SA(b, h) + aoff + m * 2048 + k * 1024); } while (0)
; #define PG8_MMA(ai, bj, At, Bt) do { __builtin_amdgcn_s_setprio(1); _Pragma("unroll") for (int m = 0; m < 4; ++m) _Pragma("unroll") for (int n = 0; n < 2; ++n) _Pragma("unroll") for (int k = 0; k < 2; ++k) \
;         acc[ai][bj][m][n] = __builtin_amdgcn_mfma_f32_16x16x32_bf16(Bt[n][k], At[m][k], acc[ai][bj][m][n], 0, 0, 0); __builtin_amdgcn_s_setprio(0); } while (0)
; #define PG8_WAIT_V(n) asm volatile("s_waitcnt vmcnt(" #n ")" ::: "memory")
; #define PG8_WAIT_L(n) asm volatile("s_waitcnt lgkmcnt(" #n ")" ::: "memory")
; #define PG8_BAR __builtin_amdgcn_s_barrier()
; #define PG8_SCHED __builtin_amdgcn_sched_barrier(0)
; template <class Epi, class Sched, bool ALIGN_EPI = false, bool SP2 = false>
; __device__ __forceinline__ void gemm_phase(PG8_LAS unsigned char* lds, const Gemm g, const Sched& S, const Epi& E) {
;     ...
;         for (int t = 0; t < nt; t += 2) {
;     ...
;             PG8_WAIT_V(8); PG8_WAIT_L(0); PG8_BAR; PG8_MMA(0, 0, At, B0); PG8_MMA(0, 1, At, B1); PG8_BAR; PG8_SCHED;
;             PG8_LDA(At, 1, 1); PG8_STAGE(PG8_SB(1, 0), b3, voffB); PG8_STAGE(PG8_SB(1, 1), b3 + hstepB, voffB); PG8_STAGE(PG8_SA(1, 0), a3, voffA);
;             PG8_WAIT_V(8); PG8_WAIT_L(0); PG8_BAR; PG8_MMA(1, 0, At, B0); PG8_MMA(1, 1, At, B1); PG8_BAR; PG8_SCHED;
	v_mfma_f32_16x16x32_bf16 v[124:127], v[132:135], v[172:175], v[124:127]
	v_mfma_f32_16x16x32_bf16 v[120:123], v[140:143], v[172:175], v[120:123]
	v_mfma_f32_16x16x32_bf16 v[108:111], v[132:135], v[180:183], v[108:111]
	v_mfma_f32_16x16x32_bf16 v[104:107], v[140:143], v[180:183], v[104:107]
	v_mfma_f32_16x16x32_bf16 v[92:95], v[132:135], v[208:211], v[92:95]
	v_mfma_f32_16x16x32_bf16 v[88:91], v[140:143], v[208:211], v[88:91]
	v_mfma_f32_16x16x32_bf16 v[76:79], v[132:135], v[216:219], v[76:79]
	v_mfma_f32_16x16x32_bf16 v[72:75], v[140:143], v[216:219], v[72:75]
	v_mfma_f32_16x16x32_bf16 v[124:127], v[136:139], v[176:179], v[124:127]
	v_mfma_f32_16x16x32_bf16 v[120:123], v[152:155], v[176:179], v[120:123]
	v_mfma_f32_16x16x32_bf16 v[108:111], v[136:139], v[204:207], v[108:111]
	v_mfma_f32_16x16x32_bf16 v[104:107], v[152:155], v[204:207], v[104:107]
	v_mfma_f32_16x16x32_bf16 v[92:95], v[136:139], v[212:215], v[92:95]
	v_mfma_f32_16x16x32_bf16 v[88:91], v[152:155], v[212:215], v[88:91]
	v_mfma_f32_16x16x32_bf16 v[76:79], v[136:139], v[220:223], v[76:79]
	v_mfma_f32_16x16x32_bf16 v[72:75], v[152:155], v[220:223], v[72:75]
	v_mfma_f32_16x16x32_bf16 v[116:119], v[156:159], v[172:175], v[116:119]
	v_mfma_f32_16x16x32_bf16 v[112:115], v[164:167], v[172:175], v[112:115]
	v_mfma_f32_16x16x32_bf16 v[100:103], v[156:159], v[180:183], v[100:103]
	v_mfma_f32_16x16x32_bf16 v[96:99], v[164:167], v[180:183], v[96:99]
	v_mfma_f32_16x16x32_bf16 v[84:87], v[156:159], v[208:211], v[84:87]
	v_mfma_f32_16x16x32_bf16 v[80:83], v[164:167], v[208:211], v[80:83]
	v_mfma_f32_16x16x32_bf16 v[68:71], v[156:159], v[216:219], v[68:71]
	v_mfma_f32_16x16x32_bf16 v[64:67], v[164:167], v[216:219], v[64:67]
	v_mfma_f32_16x16x32_bf16 v[116:119], v[160:163], v[176:179], v[116:119]
	v_mfma_f32_16x16x32_bf16 v[112:115], v[168:171], v[176:179], v[112:115]
	v_mfma_f32_16x16x32_bf16 v[100:103], v[160:163], v[204:207], v[100:103]
	v_mfma_f32_16x16x32_bf16 v[96:99], v[168:171], v[204:207], v[96:99]
	v_mfma_f32_16x16x32_bf16 v[84:87], v[160:163], v[212:215], v[84:87]
	v_mfma_f32_16x16x32_bf16 v[80:83], v[168:171], v[212:215], v[80:83]
	v_mfma_f32_16x16x32_bf16 v[68:71], v[160:163], v[220:223], v[68:71]
	v_mfma_f32_16x16x32_bf16 v[64:67], v[168:171], v[220:223], v[64:67]
	s_barrier
	s_setprio 0
	s_add_u32 s42, s40, 0x8000
	s_addc_u32 s43, s41, 0
	s_add_i32 s56, s56, s2
	s_mov_b32 m0, s56
	ds_read_b128 v[172:175], v149 offset:49152
	ds_read_b128 v[176:179], v149 offset:50176
	ds_read_b128 v[180:183], v149 offset:51200
	ds_read_b128 v[204:207], v149 offset:52224
	ds_read_b128 v[208:211], v149 offset:53248
	ds_read_b128 v[212:215], v149 offset:54272
	ds_read_b128 v[216:219], v149 offset:55296
	ds_read_b128 v[220:223], v149 offset:56320
	global_load_lds_dwordx4 v194, s[42:43]
	s_add_i32 m0, s56, 0x2000
	s_add_u32 s40, s40, 0xc000
	s_addc_u32 s41, s41, 0
	global_load_lds_dwordx4 v198, s[42:43]
	s_add_i32 s42, s57, s2
	s_mov_b32 m0, s42
	s_nop 0
	global_load_lds_dwordx4 v194, s[40:41]
	s_add_i32 m0, s42, 0x2000
	s_nop 0
	global_load_lds_dwordx4 v198, s[40:41]
	s_waitcnt vmcnt(6)
	s_waitcnt lgkmcnt(0)
	s_setprio 1
	s_barrier
	v_mfma_f32_16x16x32_bf16 v[60:63], v[132:135], v[172:175], v[60:63]
	v_mfma_f32_16x16x32_bf16 v[56:59], v[140:143], v[172:175], v[56:59]
	v_mfma_f32_16x16x32_bf16 v[44:47], v[132:135], v[180:183], v[44:47]
	v_mfma_f32_16x16x32_bf16 v[40:43], v[140:143], v[180:183], v[40:43]
	v_mfma_f32_16x16x32_bf16 v[28:31], v[132:135], v[208:211], v[28:31]
	v_mfma_f32_16x16x32_bf16 v[24:27], v[140:143], v[208:211], v[24:27]
	v_mfma_f32_16x16x32_bf16 v[12:15], v[132:135], v[216:219], v[12:15]
	v_mfma_f32_16x16x32_bf16 v[8:11], v[140:143], v[216:219], v[8:11]
	v_mfma_f32_16x16x32_bf16 v[60:63], v[136:139], v[176:179], v[60:63]
	v_mfma_f32_16x16x32_bf16 v[56:59], v[152:155], v[176:179], v[56:59]
	v_mfma_f32_16x16x32_bf16 v[44:47], v[136:139], v[204:207], v[44:47]
	v_mfma_f32_16x16x32_bf16 v[40:43], v[152:155], v[204:207], v[40:43]
	v_mfma_f32_16x16x32_bf16 v[28:31], v[136:139], v[212:215], v[28:31]
	v_mfma_f32_16x16x32_bf16 v[24:27], v[152:155], v[212:215], v[24:27]
	v_mfma_f32_16x16x32_bf16 v[12:15], v[136:139], v[220:223], v[12:15]
	v_mfma_f32_16x16x32_bf16 v[8:11], v[152:155], v[220:223], v[8:11]
	v_mfma_f32_16x16x32_bf16 v[52:55], v[156:159], v[172:175], v[52:55]
	v_mfma_f32_16x16x32_bf16 v[48:51], v[164:167], v[172:175], v[48:51]
	v_mfma_f32_16x16x32_bf16 v[36:39], v[156:159], v[180:183], v[36:39]
	v_mfma_f32_16x16x32_bf16 v[32:35], v[164:167], v[180:183], v[32:35]
	v_mfma_f32_16x16x32_bf16 v[20:23], v[156:159], v[208:211], v[20:23]
	v_mfma_f32_16x16x32_bf16 v[16:19], v[164:167], v[208:211], v[16:19]
	v_mfma_f32_16x16x32_bf16 v[4:7], v[156:159], v[216:219], v[4:7]
	v_mfma_f32_16x16x32_bf16 v[0:3], v[164:167], v[216:219], v[0:3]
	v_mfma_f32_16x16x32_bf16 v[52:55], v[160:163], v[176:179], v[52:55]
	v_mfma_f32_16x16x32_bf16 v[48:51], v[168:171], v[176:179], v[48:51]
	v_mfma_f32_16x16x32_bf16 v[36:39], v[160:163], v[204:207], v[36:39]
	v_mfma_f32_16x16x32_bf16 v[32:35], v[168:171], v[204:207], v[32:35]
	v_mfma_f32_16x16x32_bf16 v[20:23], v[160:163], v[212:215], v[20:23]
	v_mfma_f32_16x16x32_bf16 v[16:19], v[168:171], v[212:215], v[16:19]
	v_mfma_f32_16x16x32_bf16 v[4:7], v[160:163], v[220:223], v[4:7]
	v_mfma_f32_16x16x32_bf16 v[0:3], v[168:171], v[220:223], v[0:3]
	s_barrier
	s_setprio 0
	s_add_i32 s55, s55, 2
	s_add_u32 s53, s53, 0x10000
	s_addc_u32 s54, s54, 0
	s_add_u32 s38, s38, 0x100
	s_addc_u32 s39, s39, 0
	s_cmp_gt_u32 s55, 29
	s_cbranch_scc1 .Lpeel_exit_2

; #define PG8_BAR __builtin_amdgcn_s_barrier()
; template <class Epi, class Sched, bool ALIGN_EPI = false, bool SP2 = false>
; __device__ __forceinline__ void gemm_phase(PG8_LAS unsigned char* lds, const Gemm g, const Sched& S, const Epi& E) {
;     ...
;         if constexpr (ALIGN_EPI) { if (wr == 0) PG8_BAR; }
;         if constexpr (!Epi::AFTER_DRAIN) { if (cur.part < 0) E(acc, cur, wr, wc, fr, fq); else store_part<Epi::PERM>(acc, cur, g.part, wr, wc, fr, fq); S.done(cur); }
.Lpeel_exit_2:
	s_and_b64 vcc, exec, s[22:23]
	s_cbranch_vccz .LBB0_619
	s_barrier

; #define PG8_STAGE(bufoff, gbase, voff) do { _Pragma("unroll") for (int _i = 0; _i < 2; ++_i) \
;         __builtin_amdgcn_global_load_lds((const unsigned*)((const char*)(gbase) + (voff)[_i]), (PG8_LAS unsigned*)(lds + (bufoff) + ldsw + _i * 8192), 16, 0, 0); } while (0)
; #define PG8_LDA(dst, b, h) do { _Pragma("unroll") for (int m = 0; m < 4; ++m) _Pragma("unroll") for (int k = 0; k < 2; ++k) dst[m][k] = *(const PG8_LAS bf16x8*)(lds + PG8_SA(b, h) + aoff + m * 2048 + k * 1024); } while (0)
; #define PG8_LDB(dst, b, h) do { _Pragma("unroll") for (int n = 0; n < 2; ++n) _Pragma("unroll") for (int k = 0; k < 2; ++k) dst[n][k] = *(const PG8_LAS bf16x8*)(lds + PG8_SB(b, h) + boff + n * 2048 + k * 1024); } while (0)
; #define PG8_MMA(ai, bj, At, Bt) do { __builtin_amdgcn_s_setprio(1); _Pragma("unroll") for (int m = 0; m < 4; ++m) _Pragma("unroll") for (int n = 0; n < 2; ++n) _Pragma("unroll") for (int k = 0; k < 2; ++k) \
;         acc[ai][bj][m][n] = __builtin_amdgcn_mfma_f32_16x16x32_bf16(Bt[n][k], At[m][k], acc[ai][bj][m][n], 0, 0, 0); __builtin_amdgcn_s_setprio(0); } while (0)
; #define PG8_WAIT_V(n) asm volatile("s_waitcnt vmcnt(" #n ")" ::: "memory")
; #define PG8_WAIT_L(n) asm volatile("s_waitcnt lgkmcnt(" #n ")" ::: "memory")
; template <class Epi, class Sched, bool ALIGN_EPI = false, bool SP2 = false>
; __device__ __forceinline__ void gemm_phase(PG8_LAS unsigned char* lds, const Gemm g, const Sched& S, const Epi& E) {
;     ...
;             const bool last = (t == nt - 2);
;             const char* a1 = cA + (size_t)(t + 1) * kstepA;
;             const char* a2 = last ? nA : cA + (size_t)(t + 2) * kstepA; const char* b2 = last ? nB : cB + (size_t)(t + 2) * kstepB;
;             const char* a3 = a2 + kstepA; const char* b3 = b2 + kstepB;
;             if (last && has_next) S.a_ready(nxt);
;             if constexpr (SP2) {
;             PG8_LDB(B0, 0, 0); PG8_LDB(B1, 0, 1); PG8_SCHED; PG8_LDA(At, 0, 0); PG8_STAGE(PG8_SA(1, 1), a1 + hstepA, voffA);
;             PG8_WAIT_V(8); PG8_WAIT_L(0); PG8_BAR; PG8_MMA(0, 0, At, B0); PG8_MMA(0, 1, At, B1); PG8_BAR; PG8_SCHED;
;             PG8_LDA(At, 0, 1); PG8_STAGE(PG8_SB(0, 0), b2, voffB); PG8_STAGE(PG8_SB(0, 1), b2 + hstepB, voffB); PG8_STAGE(PG8_SA(0, 0), a2, voffA);
;             PG8_WAIT_V(8); PG8_WAIT_L(0); PG8_BAR; PG8_MMA(1, 0, At, B0); PG8_MMA(1, 1, At, B1); PG8_BAR; PG8_SCHED;
.LBB0_937:
	s_ashr_i32 s37, s36, 31
	s_lshl_b64 s[40:41], s[36:37], 19
	s_add_u32 s1, s53, s40
	s_addc_u32 s35, s52, s41
	s_ashr_i32 s31, s30, 31
	s_lshl_b64 s[42:43], s[30:31], 7
	s_add_u32 s40, s1, s42
	s_addc_u32 s41, s35, s43
	s_and_b64 s[50:51], s[38:39], exec
	s_cselect_b32 s1, s41, s47
	s_cselect_b32 s31, s40, s46
	s_ashr_i32 s35, s34, 31
	s_lshl_b64 s[50:51], s[34:35], 19
	s_add_u32 s35, s54, s50
	s_addc_u32 s37, s55, s51
	s_add_u32 s42, s35, s42
	s_addc_u32 s43, s37, s43
	s_and_b64 s[50:51], s[38:39], exec
	s_cselect_b32 s35, s43, s49
	s_cselect_b32 s37, s42, s48
	s_add_i32 s68, s67, -2
	s_add_u32 s46, s46, 0x40080
	s_addc_u32 s47, s47, 0
	s_add_u32 s69, s48, 0x100
	s_addc_u32 s70, s49, 0
	s_mov_b32 s48, 0
	s_sub_u32 s100, s46, 0x40000
	s_subb_u32 s101, s47, 0
	s_add_i32 s71, s48, 2
	s_add_u32 s49, s46, 0xfffc0080
	s_addc_u32 s50, s47, -1
	s_add_i32 s72, 0, 0x10000
	s_cmp_eq_u32 s68, s48
	s_cselect_b32 s51, s1, s50
	s_cselect_b32 s50, s31, s49
	s_cselect_b32 s49, s35, s70
	s_cselect_b32 s48, s37, s69
	s_add_i32 s74, 0, 0x14000
	v_add_u32_e32 v140, s72, v247
	v_add_u32_e32 v156, s74, v247
	ds_read_b128 v[128:131], v140
	ds_read_b128 v[132:135], v140 offset:1024
	ds_read_b128 v[136:139], v140 offset:2048
	ds_read_b128 v[140:143], v140 offset:3072
	ds_read_b128 v[144:147], v156
	ds_read_b128 v[148:151], v156 offset:1024
	ds_read_b128 v[152:155], v156 offset:2048
	ds_read_b128 v[156:159], v156 offset:3072
	ds_read_b128 v[160:163], v249
	ds_read_b128 v[164:167], v249 offset:1024
	ds_read_b128 v[168:171], v249 offset:2048
	ds_read_b128 v[172:175], v249 offset:3072
	ds_read_b128 v[176:179], v249 offset:4096
	ds_read_b128 v[180:183], v249 offset:5120
	ds_read_b128 v[184:187], v249 offset:6144
	ds_read_b128 v[188:191], v249 offset:7168
	s_mov_b32 m0, s62
	s_nop 0
	global_load_lds_dwordx4 v212, s[100:101]
	s_mov_b32 m0, s63
	s_nop 0
	global_load_lds_dwordx4 v214, s[100:101]
	s_add_i32 m0, s45, 0xc000
	s_nop 0
	global_load_lds_dwordx4 v212, s[46:47]
	s_add_i32 m0, s45, 0xe000
	s_nop 0
	global_load_lds_dwordx4 v214, s[46:47]
	s_waitcnt vmcnt(8)
	s_waitcnt lgkmcnt(0)
	s_setprio 1
	s_barrier
	v_mfma_f32_16x16x32_bf16 v[124:127], v[128:131], v[160:163], 0
	v_mfma_f32_16x16x32_bf16 v[120:123], v[136:139], v[160:163], 0
	v_mfma_f32_16x16x32_bf16 v[112:115], v[128:131], v[168:171], 0
	v_mfma_f32_16x16x32_bf16 v[104:107], v[136:139], v[168:171], 0
	v_mfma_f32_16x16x32_bf16 v[96:99], v[128:131], v[176:179], 0
	v_mfma_f32_16x16x32_bf16 v[88:91], v[136:139], v[176:179], 0
	v_mfma_f32_16x16x32_bf16 v[80:83], v[128:131], v[184:187], 0
	v_mfma_f32_16x16x32_bf16 v[72:75], v[136:139], v[184:187], 0
	v_mfma_f32_16x16x32_bf16 v[124:127], v[132:135], v[164:167], v[124:127]
	v_mfma_f32_16x16x32_bf16 v[120:123], v[140:143], v[164:167], v[120:123]
	v_mfma_f32_16x16x32_bf16 v[112:115], v[132:135], v[172:175], v[112:115]
	v_mfma_f32_16x16x32_bf16 v[104:107], v[140:143], v[172:175], v[104:107]
	v_mfma_f32_16x16x32_bf16 v[96:99], v[132:135], v[180:183], v[96:99]
	v_mfma_f32_16x16x32_bf16 v[88:91], v[140:143], v[180:183], v[88:91]
	v_mfma_f32_16x16x32_bf16 v[80:83], v[132:135], v[188:191], v[80:83]
	v_mfma_f32_16x16x32_bf16 v[72:75], v[140:143], v[188:191], v[72:75]
	v_mfma_f32_16x16x32_bf16 v[116:119], v[144:147], v[160:163], 0
	v_mfma_f32_16x16x32_bf16 v[108:111], v[152:155], v[160:163], 0
	v_mfma_f32_16x16x32_bf16 v[100:103], v[144:147], v[168:171], 0
	v_mfma_f32_16x16x32_bf16 v[92:95], v[152:155], v[168:171], 0
	v_mfma_f32_16x16x32_bf16 v[84:87], v[144:147], v[176:179], 0
	v_mfma_f32_16x16x32_bf16 v[76:79], v[152:155], v[176:179], 0
	v_mfma_f32_16x16x32_bf16 v[68:71], v[144:147], v[184:187], 0
	v_mfma_f32_16x16x32_bf16 v[64:67], v[152:155], v[184:187], 0
	v_mfma_f32_16x16x32_bf16 v[116:119], v[148:151], v[164:167], v[116:119]
	v_mfma_f32_16x16x32_bf16 v[108:111], v[156:159], v[164:167], v[108:111]
	v_mfma_f32_16x16x32_bf16 v[100:103], v[148:151], v[172:175], v[100:103]
	v_mfma_f32_16x16x32_bf16 v[92:95], v[156:159], v[172:175], v[92:95]
	v_mfma_f32_16x16x32_bf16 v[84:87], v[148:151], v[180:183], v[84:87]
	v_mfma_f32_16x16x32_bf16 v[76:79], v[156:159], v[180:183], v[76:79]
	v_mfma_f32_16x16x32_bf16 v[68:71], v[148:151], v[188:191], v[68:71]
	v_mfma_f32_16x16x32_bf16 v[64:67], v[156:159], v[188:191], v[64:67]
	s_barrier
	s_add_u32 s98, s48, s20
	s_addc_u32 s99, s49, s21
	s_add_u32 s100, s50, s20
	s_addc_u32 s101, s51, s21
	s_setprio 0
	s_add_i32 s72, s72, s56
	s_mov_b32 m0, s72
	ds_read_b128 v[160:163], v249 offset:16384
	ds_read_b128 v[164:167], v249 offset:17408
	ds_read_b128 v[168:171], v249 offset:18432
	ds_read_b128 v[172:175], v249 offset:19456
	ds_read_b128 v[176:179], v249 offset:20480
	ds_read_b128 v[180:183], v249 offset:21504
	ds_read_b128 v[184:187], v249 offset:22528
	ds_read_b128 v[188:191], v249 offset:23552
	global_load_lds_dwordx4 v206, s[48:49]
	s_add_i32 m0, s72, 0x2000
	s_add_u32 s72, s48, 0x40000
	s_addc_u32 s73, s49, 0
	s_add_i32 s74, s74, s56
	global_load_lds_dwordx4 v210, s[48:49]
	s_mov_b32 m0, s74
	s_nop 0
	global_load_lds_dwordx4 v206, s[72:73]
	s_add_i32 m0, s74, 0x2000
	s_nop 0
	global_load_lds_dwordx4 v210, s[72:73]
	s_waitcnt vmcnt(6)
	s_waitcnt lgkmcnt(0)
	s_setprio 1
	s_barrier
; #define PG8_STAGE(bufoff, gbase, voff) do { _Pragma("unroll") for (int _i = 0; _i < 2; ++_i) \
;         __builtin_amdgcn_global_load_lds((const unsigned*)((const char*)(gbase) + (voff)[_i]), (PG8_LAS unsigned*)(lds + (bufoff) + ldsw + _i * 8192), 16, 0, 0); } while (0)
; #define PG8_LDA(dst, b, h) do { _Pragma("unroll") for (int m = 0; m < 4; ++m) _Pragma("unroll") for (int k = 0; k < 2; ++k) dst[m][k] = *(const PG8_LAS bf16x8*)(lds + PG8_SA(b, h) + aoff + m * 2048 + k * 1024); } while (0)
; #define PG8_LDB(dst, b, h) do { _Pragma("unroll") for (int n = 0; n < 2; ++n) _Pragma("unroll") for (int k = 0; k < 2; ++k) dst[n][k] = *(const PG8_LAS bf16x8*)(lds + PG8_SB(b, h) + boff + n * 2048 + k * 1024); } while (0)
; #define PG8_MMA(ai, bj, At, Bt) do { __builtin_amdgcn_s_setprio(1); _Pragma("unroll") for (int m = 0; m < 4; ++m) _Pragma("unroll") for (int n = 0; n < 2; ++n) _Pragma("unroll") for (int k = 0; k < 2; ++k) \
;         acc[ai][bj][m][n] = __builtin_amdgcn_mfma_f32_16x16x32_bf16(Bt[n][k], At[m][k], acc[ai][bj][m][n], 0, 0, 0); __builtin_amdgcn_s_setprio(0); } while (0)
; #define PG8_WAIT_V(n) asm volatile("s_waitcnt vmcnt(" #n ")" ::: "memory")
; #define PG8_WAIT_L(n) asm volatile("s_waitcnt lgkmcnt(" #n ")" ::: "memory")
; #define PG8_BAR __builtin_amdgcn_s_barrier()
; #define PG8_SCHED __builtin_amdgcn_sched_barrier(0)
; template <class Epi, class Sched, bool ALIGN_EPI = false, bool SP2 = false>
; __device__ __forceinline__ void gemm_phase(PG8_LAS unsigned char* lds, const Gemm g, const Sched& S, const Epi& E) {
;     ...
;             PG8_WAIT_V(8); PG8_WAIT_L(0); PG8_BAR; PG8_MMA(1, 0, At, B0); PG8_MMA(1, 1, At, B1); PG8_BAR; PG8_SCHED;
;             PG8_LDB(B0, 1, 0); PG8_LDB(B1, 1, 1); PG8_SCHED; PG8_LDA(At, 1, 0); PG8_STAGE(PG8_SA(0, 1), a2 + hstepA, voffA);
	v_mfma_f32_16x16x32_bf16 v[60:63], v[128:131], v[160:163], 0
	v_mfma_f32_16x16x32_bf16 v[56:59], v[136:139], v[160:163], 0
	v_mfma_f32_16x16x32_bf16 v[48:51], v[128:131], v[168:171], 0
	v_mfma_f32_16x16x32_bf16 v[40:43], v[136:139], v[168:171], 0
	v_mfma_f32_16x16x32_bf16 v[32:35], v[128:131], v[176:179], 0
	v_mfma_f32_16x16x32_bf16 v[24:27], v[136:139], v[176:179], 0
	v_mfma_f32_16x16x32_bf16 v[16:19], v[128:131], v[184:187], 0
	v_mfma_f32_16x16x32_bf16 v[8:11], v[136:139], v[184:187], 0
	v_mfma_f32_16x16x32_bf16 v[60:63], v[132:135], v[164:167], v[60:63]
	v_mfma_f32_16x16x32_bf16 v[56:59], v[140:143], v[164:167], v[56:59]
	v_mfma_f32_16x16x32_bf16 v[48:51], v[132:135], v[172:175], v[48:51]
	v_mfma_f32_16x16x32_bf16 v[40:43], v[140:143], v[172:175], v[40:43]
	v_mfma_f32_16x16x32_bf16 v[32:35], v[132:135], v[180:183], v[32:35]
	v_mfma_f32_16x16x32_bf16 v[24:27], v[140:143], v[180:183], v[24:27]
	v_mfma_f32_16x16x32_bf16 v[16:19], v[132:135], v[188:191], v[16:19]
	v_mfma_f32_16x16x32_bf16 v[8:11], v[140:143], v[188:191], v[8:11]
	v_mfma_f32_16x16x32_bf16 v[52:55], v[144:147], v[160:163], 0
	v_mfma_f32_16x16x32_bf16 v[44:47], v[152:155], v[160:163], 0
	v_mfma_f32_16x16x32_bf16 v[36:39], v[144:147], v[168:171], 0
	v_mfma_f32_16x16x32_bf16 v[28:31], v[152:155], v[168:171], 0
	v_mfma_f32_16x16x32_bf16 v[20:23], v[144:147], v[176:179], 0
	v_mfma_f32_16x16x32_bf16 v[12:15], v[152:155], v[176:179], 0
	v_mfma_f32_16x16x32_bf16 v[4:7], v[144:147], v[184:187], 0
	v_mfma_f32_16x16x32_bf16 v[0:3], v[152:155], v[184:187], 0
	v_mfma_f32_16x16x32_bf16 v[52:55], v[148:151], v[164:167], v[52:55]
	v_mfma_f32_16x16x32_bf16 v[44:47], v[156:159], v[164:167], v[44:47]
	v_mfma_f32_16x16x32_bf16 v[36:39], v[148:151], v[172:175], v[36:39]
	v_mfma_f32_16x16x32_bf16 v[28:31], v[156:159], v[172:175], v[28:31]
	v_mfma_f32_16x16x32_bf16 v[20:23], v[148:151], v[180:183], v[20:23]
	v_mfma_f32_16x16x32_bf16 v[12:15], v[156:159], v[180:183], v[12:15]
	v_mfma_f32_16x16x32_bf16 v[4:7], v[148:151], v[188:191], v[4:7]
	v_mfma_f32_16x16x32_bf16 v[0:3], v[156:159], v[188:191], v[0:3]
	s_barrier
	s_setprio 0
	s_add_i32 s72, 0, 0x18000
	s_add_i32 s73, 0, 0x1c000
	v_add_u32_e32 v140, s72, v247
	v_add_u32_e32 v156, s73, v247
	ds_read_b128 v[128:131], v140
	ds_read_b128 v[132:135], v140 offset:1024
	ds_read_b128 v[136:139], v140 offset:2048
	ds_read_b128 v[140:143], v140 offset:3072
	ds_read_b128 v[144:147], v156
	ds_read_b128 v[148:151], v156 offset:1024
	ds_read_b128 v[152:155], v156 offset:2048
	ds_read_b128 v[156:159], v156 offset:3072
	s_mov_b32 m0, s45
	s_nop 0
	global_load_lds_dwordx4 v204, s[50:51]
	s_mov_b32 m0, s57
	s_nop 0
	global_load_lds_dwordx4 v208, s[50:51]
	s_add_u32 s50, s50, 0x40000
	s_addc_u32 s51, s51, 0
	s_mov_b32 m0, s58
	ds_read_b128 v[160:163], v249 offset:32768
	ds_read_b128 v[164:167], v249 offset:33792
	ds_read_b128 v[168:171], v249 offset:34816
	ds_read_b128 v[172:175], v249 offset:35840
	ds_read_b128 v[176:179], v249 offset:36864
	ds_read_b128 v[180:183], v249 offset:37888
	ds_read_b128 v[184:187], v249 offset:38912
	ds_read_b128 v[188:191], v249 offset:39936
	global_load_lds_dwordx4 v204, s[50:51]
	s_mov_b32 m0, s59
	s_nop 0
	global_load_lds_dwordx4 v208, s[50:51]
	s_waitcnt vmcnt(8)
	s_waitcnt lgkmcnt(0)
	s_setprio 1
	s_barrier
; #define PG8_STAGE(bufoff, gbase, voff) do { _Pragma("unroll") for (int _i = 0; _i < 2; ++_i) \
;         __builtin_amdgcn_global_load_lds((const unsigned*)((const char*)(gbase) + (voff)[_i]), (PG8_LAS unsigned*)(lds + (bufoff) + ldsw + _i * 8192), 16, 0, 0); } while (0)
; #define PG8_LDA(dst, b, h) do { _Pragma("unroll") for (int m = 0; m < 4; ++m) _Pragma("unroll") for (int k = 0; k < 2; ++k) dst[m][k] = *(const PG8_LAS bf16x8*)(lds + PG8_SA(b, h) + aoff + m * 2048 + k * 1024); } while (0)
; #define PG8_MMA(ai, bj, At, Bt) do { __builtin_amdgcn_s_setprio(1); _Pragma("unroll") for (int m = 0; m < 4; ++m) _Pragma("unroll") for (int n = 0; n < 2; ++n) _Pragma("unroll") for (int k = 0; k < 2; ++k) \
;         acc[ai][bj][m][n] = __builtin_amdgcn_mfma_f32_16x16x32_bf16(Bt[n][k], At[m][k], acc[ai][bj][m][n], 0, 0, 0); __builtin_amdgcn_s_setprio(0); } while (0)
; #define PG8_WAIT_V(n) asm volatile("s_waitcnt vmcnt(" #n ")" ::: "memory")
; #define PG8_WAIT_L(n) asm volatile("s_waitcnt lgkmcnt(" #n ")" ::: "memory")
; #define PG8_BAR __builtin_amdgcn_s_barrier()
; #define PG8_SCHED __builtin_amdgcn_sched_barrier(0)
; template <class Epi, class Sched, bool ALIGN_EPI = false, bool SP2 = false>
; __device__ __forceinline__ void gemm_phase(PG8_LAS unsigned char* lds, const Gemm g, const Sched& S, const Epi& E) {
;     ...
;         for (int t = 0; t < nt; t += 2) {
;     ...
;             PG8_WAIT_V(8); PG8_WAIT_L(0); PG8_BAR; PG8_MMA(0, 0, At, B0); PG8_MMA(0, 1, At, B1); PG8_BAR; PG8_SCHED;
;             PG8_LDA(At, 1, 1); PG8_STAGE(PG8_SB(1, 0), b3, voffB); PG8_STAGE(PG8_SB(1, 1), b3 + hstepB, voffB); PG8_STAGE(PG8_SA(1, 0), a3, voffA);
;             PG8_WAIT_V(8); PG8_WAIT_L(0); PG8_BAR; PG8_MMA(1, 0, At, B0); PG8_MMA(1, 1, At, B1); PG8_BAR; PG8_SCHED;
	v_mfma_f32_16x16x32_bf16 v[124:127], v[128:131], v[160:163], v[124:127]
	v_mfma_f32_16x16x32_bf16 v[120:123], v[136:139], v[160:163], v[120:123]
	v_mfma_f32_16x16x32_bf16 v[112:115], v[128:131], v[168:171], v[112:115]
	v_mfma_f32_16x16x32_bf16 v[104:107], v[136:139], v[168:171], v[104:107]
	v_mfma_f32_16x16x32_bf16 v[96:99], v[128:131], v[176:179], v[96:99]
	v_mfma_f32_16x16x32_bf16 v[88:91], v[136:139], v[176:179], v[88:91]
	v_mfma_f32_16x16x32_bf16 v[80:83], v[128:131], v[184:187], v[80:83]
	v_mfma_f32_16x16x32_bf16 v[72:75], v[136:139], v[184:187], v[72:75]
	v_mfma_f32_16x16x32_bf16 v[124:127], v[132:135], v[164:167], v[124:127]
	v_mfma_f32_16x16x32_bf16 v[120:123], v[140:143], v[164:167], v[120:123]
	v_mfma_f32_16x16x32_bf16 v[112:115], v[132:135], v[172:175], v[112:115]
	v_mfma_f32_16x16x32_bf16 v[104:107], v[140:143], v[172:175], v[104:107]
	v_mfma_f32_16x16x32_bf16 v[96:99], v[132:135], v[180:183], v[96:99]
	v_mfma_f32_16x16x32_bf16 v[88:91], v[140:143], v[180:183], v[88:91]
	v_mfma_f32_16x16x32_bf16 v[80:83], v[132:135], v[188:191], v[80:83]
	v_mfma_f32_16x16x32_bf16 v[72:75], v[140:143], v[188:191], v[72:75]
	v_mfma_f32_16x16x32_bf16 v[116:119], v[144:147], v[160:163], v[116:119]
	v_mfma_f32_16x16x32_bf16 v[108:111], v[152:155], v[160:163], v[108:111]
	v_mfma_f32_16x16x32_bf16 v[100:103], v[144:147], v[168:171], v[100:103]
	v_mfma_f32_16x16x32_bf16 v[92:95], v[152:155], v[168:171], v[92:95]
	v_mfma_f32_16x16x32_bf16 v[84:87], v[144:147], v[176:179], v[84:87]
	v_mfma_f32_16x16x32_bf16 v[76:79], v[152:155], v[176:179], v[76:79]
	v_mfma_f32_16x16x32_bf16 v[68:71], v[144:147], v[184:187], v[68:71]
	v_mfma_f32_16x16x32_bf16 v[64:67], v[152:155], v[184:187], v[64:67]
	v_mfma_f32_16x16x32_bf16 v[116:119], v[148:151], v[164:167], v[116:119]
	v_mfma_f32_16x16x32_bf16 v[108:111], v[156:159], v[164:167], v[108:111]
	v_mfma_f32_16x16x32_bf16 v[100:103], v[148:151], v[172:175], v[100:103]
	v_mfma_f32_16x16x32_bf16 v[92:95], v[156:159], v[172:175], v[92:95]
	v_mfma_f32_16x16x32_bf16 v[84:87], v[148:151], v[180:183], v[84:87]
	v_mfma_f32_16x16x32_bf16 v[76:79], v[156:159], v[180:183], v[76:79]
	v_mfma_f32_16x16x32_bf16 v[68:71], v[148:151], v[188:191], v[68:71]
	v_mfma_f32_16x16x32_bf16 v[64:67], v[156:159], v[188:191], v[64:67]
	s_barrier
	s_setprio 0
	s_add_i32 s50, s72, s56
	s_mov_b32 m0, s50
	ds_read_b128 v[160:163], v249 offset:49152
	ds_read_b128 v[164:167], v249 offset:50176
	ds_read_b128 v[168:171], v249 offset:51200
	ds_read_b128 v[172:175], v249 offset:52224
	ds_read_b128 v[176:179], v249 offset:53248
	ds_read_b128 v[180:183], v249 offset:54272
	ds_read_b128 v[184:187], v249 offset:55296
	ds_read_b128 v[188:191], v249 offset:56320
	global_load_lds_dwordx4 v206, s[98:99]
	s_add_i32 m0, s50, 0x2000
	s_add_u32 s48, s48, 0x40080
	s_addc_u32 s49, s49, 0
	s_add_i32 s50, s73, s56
	global_load_lds_dwordx4 v210, s[98:99]
	s_mov_b32 m0, s50
	s_nop 0
	global_load_lds_dwordx4 v206, s[48:49]
	s_add_i32 m0, s50, 0x2000
	s_nop 0
	global_load_lds_dwordx4 v210, s[48:49]
	s_waitcnt vmcnt(6)
	s_waitcnt lgkmcnt(0)
	s_setprio 1
	s_barrier
	v_mfma_f32_16x16x32_bf16 v[60:63], v[128:131], v[160:163], v[60:63]
	v_mfma_f32_16x16x32_bf16 v[56:59], v[136:139], v[160:163], v[56:59]
	v_mfma_f32_16x16x32_bf16 v[48:51], v[128:131], v[168:171], v[48:51]
	v_mfma_f32_16x16x32_bf16 v[40:43], v[136:139], v[168:171], v[40:43]
	v_mfma_f32_16x16x32_bf16 v[32:35], v[128:131], v[176:179], v[32:35]
	v_mfma_f32_16x16x32_bf16 v[24:27], v[136:139], v[176:179], v[24:27]
	v_mfma_f32_16x16x32_bf16 v[16:19], v[128:131], v[184:187], v[16:19]
	v_mfma_f32_16x16x32_bf16 v[8:11], v[136:139], v[184:187], v[8:11]
	v_mfma_f32_16x16x32_bf16 v[60:63], v[132:135], v[164:167], v[60:63]
	v_mfma_f32_16x16x32_bf16 v[56:59], v[140:143], v[164:167], v[56:59]
	v_mfma_f32_16x16x32_bf16 v[48:51], v[132:135], v[172:175], v[48:51]
	v_mfma_f32_16x16x32_bf16 v[40:43], v[140:143], v[172:175], v[40:43]
	v_mfma_f32_16x16x32_bf16 v[32:35], v[132:135], v[180:183], v[32:35]
	v_mfma_f32_16x16x32_bf16 v[24:27], v[140:143], v[180:183], v[24:27]
	v_mfma_f32_16x16x32_bf16 v[16:19], v[132:135], v[188:191], v[16:19]
	v_mfma_f32_16x16x32_bf16 v[8:11], v[140:143], v[188:191], v[8:11]
	v_mfma_f32_16x16x32_bf16 v[52:55], v[144:147], v[160:163], v[52:55]
	v_mfma_f32_16x16x32_bf16 v[44:47], v[152:155], v[160:163], v[44:47]
	v_mfma_f32_16x16x32_bf16 v[36:39], v[144:147], v[168:171], v[36:39]
	v_mfma_f32_16x16x32_bf16 v[28:31], v[152:155], v[168:171], v[28:31]
	v_mfma_f32_16x16x32_bf16 v[20:23], v[144:147], v[176:179], v[20:23]
	v_mfma_f32_16x16x32_bf16 v[12:15], v[152:155], v[176:179], v[12:15]
	v_mfma_f32_16x16x32_bf16 v[4:7], v[144:147], v[184:187], v[4:7]
	v_mfma_f32_16x16x32_bf16 v[0:3], v[152:155], v[184:187], v[0:3]
	v_mfma_f32_16x16x32_bf16 v[52:55], v[148:151], v[164:167], v[52:55]
	v_mfma_f32_16x16x32_bf16 v[44:47], v[156:159], v[164:167], v[44:47]
	v_mfma_f32_16x16x32_bf16 v[36:39], v[148:151], v[172:175], v[36:39]
	v_mfma_f32_16x16x32_bf16 v[28:31], v[156:159], v[172:175], v[28:31]
	v_mfma_f32_16x16x32_bf16 v[20:23], v[148:151], v[180:183], v[20:23]
	v_mfma_f32_16x16x32_bf16 v[12:15], v[156:159], v[180:183], v[12:15]
	v_mfma_f32_16x16x32_bf16 v[4:7], v[148:151], v[188:191], v[4:7]
	v_mfma_f32_16x16x32_bf16 v[0:3], v[156:159], v[188:191], v[0:3]
	s_barrier
	s_setprio 0
	s_add_u32 s46, s46, 0x100
	s_addc_u32 s47, s47, 0
	s_add_u32 s69, s69, 0x100
	s_addc_u32 s70, s70, 0
	s_cmp_ge_i32 s71, s67
	s_mov_b32 s48, s71
	s_cbranch_scc1 .Lpeel_exit_3

; #define PG8_BAR __builtin_amdgcn_s_barrier()
; template <class Epi, class Sched, bool ALIGN_EPI = false, bool SP2 = false>
; __device__ __forceinline__ void gemm_phase(PG8_LAS unsigned char* lds, const Gemm g, const Sched& S, const Epi& E) {
;     ...
;         if constexpr (ALIGN_EPI) { if (wr == 0) PG8_BAR; }
;         if constexpr (!Epi::AFTER_DRAIN) { if (cur.part < 0) E(acc, cur, wr, wc, fr, fq); else store_part<Epi::PERM>(acc, cur, g.part, wr, wc, fr, fq); S.done(cur); }
.Lpeel_exit_3:
	s_and_b64 vcc, exec, s[26:27]
	s_cbranch_vccnz .LBB0_943
	s_mov_b64 s[46:47], -1
	s_cmp_gt_i32 s18, -1
	v_lshl_or_b32 v218, s44, 8, v248
	s_cbranch_scc1 .LBB0_944

; #define PG8_STAGE(bufoff, gbase, voff) do { _Pragma("unroll") for (int _i = 0; _i < 2; ++_i) \
;         __builtin_amdgcn_global_load_lds((const unsigned*)((const char*)(gbase) + (voff)[_i]), (PG8_LAS unsigned*)(lds + (bufoff) + ldsw + _i * 8192), 16, 0, 0); } while (0)
; #define PG8_LDA(dst, b, h) do { _Pragma("unroll") for (int m = 0; m < 4; ++m) _Pragma("unroll") for (int k = 0; k < 2; ++k) dst[m][k] = *(const PG8_LAS bf16x8*)(lds + PG8_SA(b, h) + aoff + m * 2048 + k * 1024); } while (0)
; #define PG8_LDB(dst, b, h) do { _Pragma("unroll") for (int n = 0; n < 2; ++n) _Pragma("unroll") for (int k = 0; k < 2; ++k) dst[n][k] = *(const PG8_LAS bf16x8*)(lds + PG8_SB(b, h) + boff + n * 2048 + k * 1024); } while (0)
; #define PG8_MMA(ai, bj, At, Bt) do { __builtin_amdgcn_s_setprio(1); _Pragma("unroll") for (int m = 0; m < 4; ++m) _Pragma("unroll") for (int n = 0; n < 2; ++n) _Pragma("unroll") for (int k = 0; k < 2; ++k) \
;         acc[ai][bj][m][n] = __builtin_amdgcn_mfma_f32_16x16x32_bf16(Bt[n][k], At[m][k], acc[ai][bj][m][n], 0, 0, 0); __builtin_amdgcn_s_setprio(0); } while (0)
; #define PG8_WAIT_V(n) asm volatile("s_waitcnt vmcnt(" #n ")" ::: "memory")
; #define PG8_WAIT_L(n) asm volatile("s_waitcnt lgkmcnt(" #n ")" ::: "memory")
; template <class Epi, class Sched, bool ALIGN_EPI = false, bool SP2 = false>
; __device__ __forceinline__ void gemm_phase(PG8_LAS unsigned char* lds, const Gemm g, const Sched& S, const Epi& E) {
;     ...
;             const bool last = (t == nt - 2);
;             const char* a1 = cA + (size_t)(t + 1) * kstepA;
;             const char* a2 = last ? nA : cA + (size_t)(t + 2) * kstepA; const char* b2 = last ? nB : cB + (size_t)(t + 2) * kstepB;
;             const char* a3 = a2 + kstepA; const char* b3 = b2 + kstepB;
;             if (last && has_next) S.a_ready(nxt);
;             if constexpr (SP2) {
;             PG8_LDB(B0, 0, 0); PG8_LDB(B1, 0, 1); PG8_SCHED; PG8_LDA(At, 0, 0); PG8_STAGE(PG8_SA(1, 1), a1 + hstepA, voffA);
;             PG8_WAIT_V(8); PG8_WAIT_L(0); PG8_BAR; PG8_MMA(0, 0, At, B0); PG8_MMA(0, 1, At, B1); PG8_BAR; PG8_SCHED;
;             PG8_LDA(At, 0, 1); PG8_STAGE(PG8_SB(0, 0), b2, voffB); PG8_STAGE(PG8_SB(0, 1), b2 + hstepB, voffB); PG8_STAGE(PG8_SA(0, 0), a2, voffA);
;             PG8_WAIT_V(8); PG8_WAIT_L(0); PG8_BAR; PG8_MMA(1, 0, At, B0); PG8_MMA(1, 1, At, B1); PG8_BAR; PG8_SCHED;
.LBB0_1112:
	s_ashr_i32 s29, s28, 31
	s_lshl_b64 s[34:35], s[28:29], 20
	s_add_u32 s27, s8, s34
	s_addc_u32 s29, s9, s35
	s_ashr_i32 s25, s24, 31
	s_lshl_b64 s[36:37], s[24:25], 7
	s_add_u32 s34, s27, s36
	s_addc_u32 s35, s29, s37
	s_and_b64 s[46:47], s[30:31], exec
	s_cselect_b32 s25, s35, s43
	s_cselect_b32 s29, s34, s42
	s_ashr_i32 s27, s26, 31
	s_lshl_b64 s[46:47], s[26:27], 20
	s_add_u32 s27, s10, s46
	s_addc_u32 s39, s12, s47
	s_add_u32 s36, s27, s36
	s_addc_u32 s37, s39, s37
	s_and_b64 s[46:47], s[30:31], exec
	s_cselect_b32 s27, s37, s45
	s_cselect_b32 s39, s36, s44
	s_add_i32 s57, s56, -2
	s_add_u32 s42, s42, 0x80080
	s_addc_u32 s43, s43, 0
	s_add_u32 s58, s44, 0x100
	s_addc_u32 s59, s45, 0
	s_mov_b32 s44, 0
	s_waitcnt lgkmcnt(0)
	s_sub_u32 s100, s42, 0x80000
	s_subb_u32 s101, s43, 0
	ds_read_b128 v[136:139], v181
	ds_read_b128 v[140:143], v181 offset:1024
	ds_read_b128 v[144:147], v181 offset:2048
	ds_read_b128 v[148:151], v181 offset:3072
	ds_read_b128 v[152:155], v182
	ds_read_b128 v[156:159], v182 offset:1024
	ds_read_b128 v[160:163], v182 offset:2048
	ds_read_b128 v[164:167], v182 offset:3072
	s_add_i32 s60, s44, 2
	s_add_u32 s45, s42, 0xfff80080
	s_addc_u32 s46, s43, -1
	s_cmp_eq_u32 s57, s44
	s_cselect_b32 s44, s39, s58
	s_cselect_b32 s47, s25, s46
	s_cselect_b32 s46, s29, s45
	s_cselect_b32 s45, s27, s59
	ds_read_b128 v[168:171], v183
	ds_read_b128 v[172:175], v183 offset:1024
	ds_read_b128 v[186:189], v183 offset:2048
	ds_read_b128 v[204:207], v183 offset:3072
	ds_read_b128 v[208:211], v183 offset:4096
	ds_read_b128 v[212:215], v183 offset:5120
	ds_read_b128 v[216:219], v183 offset:6144
	ds_read_b128 v[220:223], v183 offset:7168
	s_mov_b32 m0, s48
	s_nop 0
	global_load_lds_dwordx4 v128, s[100:101]
	s_mov_b32 m0, s49
	s_nop 0
	global_load_lds_dwordx4 v130, s[100:101]
	s_add_i32 m0, s13, 0xc000
	s_nop 0
	global_load_lds_dwordx4 v128, s[42:43]
	s_add_i32 m0, s13, 0xe000
	s_nop 0
	global_load_lds_dwordx4 v130, s[42:43]
	s_waitcnt vmcnt(8)
	s_waitcnt lgkmcnt(0)
	s_setprio 1
	s_barrier
	v_mfma_f32_16x16x32_bf16 v[124:127], v[136:139], v[168:171], 0
	v_mfma_f32_16x16x32_bf16 v[120:123], v[144:147], v[168:171], 0
	v_mfma_f32_16x16x32_bf16 v[108:111], v[136:139], v[186:189], 0
	v_mfma_f32_16x16x32_bf16 v[104:107], v[144:147], v[186:189], 0
	v_mfma_f32_16x16x32_bf16 v[92:95], v[136:139], v[208:211], 0
	v_mfma_f32_16x16x32_bf16 v[88:91], v[144:147], v[208:211], 0
	v_mfma_f32_16x16x32_bf16 v[76:79], v[136:139], v[216:219], 0
	v_mfma_f32_16x16x32_bf16 v[72:75], v[144:147], v[216:219], 0
	v_mfma_f32_16x16x32_bf16 v[124:127], v[140:143], v[172:175], v[124:127]
	v_mfma_f32_16x16x32_bf16 v[120:123], v[148:151], v[172:175], v[120:123]
	v_mfma_f32_16x16x32_bf16 v[108:111], v[140:143], v[204:207], v[108:111]
	v_mfma_f32_16x16x32_bf16 v[104:107], v[148:151], v[204:207], v[104:107]
	v_mfma_f32_16x16x32_bf16 v[92:95], v[140:143], v[212:215], v[92:95]
	v_mfma_f32_16x16x32_bf16 v[88:91], v[148:151], v[212:215], v[88:91]
	v_mfma_f32_16x16x32_bf16 v[76:79], v[140:143], v[220:223], v[76:79]
	v_mfma_f32_16x16x32_bf16 v[72:75], v[148:151], v[220:223], v[72:75]
	v_mfma_f32_16x16x32_bf16 v[116:119], v[152:155], v[168:171], 0
	v_mfma_f32_16x16x32_bf16 v[112:115], v[160:163], v[168:171], 0
	v_mfma_f32_16x16x32_bf16 v[100:103], v[152:155], v[186:189], 0
	v_mfma_f32_16x16x32_bf16 v[96:99], v[160:163], v[186:189], 0
	v_mfma_f32_16x16x32_bf16 v[84:87], v[152:155], v[208:211], 0
	v_mfma_f32_16x16x32_bf16 v[80:83], v[160:163], v[208:211], 0
	v_mfma_f32_16x16x32_bf16 v[68:71], v[152:155], v[216:219], 0
	v_mfma_f32_16x16x32_bf16 v[64:67], v[160:163], v[216:219], 0
	v_mfma_f32_16x16x32_bf16 v[116:119], v[156:159], v[172:175], v[116:119]
	v_mfma_f32_16x16x32_bf16 v[112:115], v[164:167], v[172:175], v[112:115]
	v_mfma_f32_16x16x32_bf16 v[100:103], v[156:159], v[204:207], v[100:103]
	v_mfma_f32_16x16x32_bf16 v[96:99], v[164:167], v[204:207], v[96:99]
	v_mfma_f32_16x16x32_bf16 v[84:87], v[156:159], v[212:215], v[84:87]
	v_mfma_f32_16x16x32_bf16 v[80:83], v[164:167], v[212:215], v[80:83]
	v_mfma_f32_16x16x32_bf16 v[68:71], v[156:159], v[220:223], v[68:71]
	v_mfma_f32_16x16x32_bf16 v[64:67], v[164:167], v[220:223], v[64:67]
	s_barrier
	s_add_u32 s98, s44, s20
	s_addc_u32 s99, s45, s21
	s_add_u32 s100, s46, s20
	s_addc_u32 s101, s47, s21
	s_setprio 0
	s_add_i32 s61, s51, s2
	s_mov_b32 m0, s61
	ds_read_b128 v[168:171], v183 offset:16384
	ds_read_b128 v[172:175], v183 offset:17408
	ds_read_b128 v[186:189], v183 offset:18432
	ds_read_b128 v[204:207], v183 offset:19456
	ds_read_b128 v[208:211], v183 offset:20480
	ds_read_b128 v[212:215], v183 offset:21504
	ds_read_b128 v[216:219], v183 offset:22528
	ds_read_b128 v[220:223], v183 offset:23552
	global_load_lds_dwordx4 v192, s[44:45]
	s_add_i32 m0, s61, 0x2000
	s_add_u32 s62, s44, 0x80000
	s_addc_u32 s63, s45, 0
	s_add_i32 s61, s52, s2
	global_load_lds_dwordx4 v196, s[44:45]
	s_mov_b32 m0, s61
	s_nop 0
	global_load_lds_dwordx4 v192, s[62:63]
	s_add_i32 m0, s61, 0x2000
	s_nop 0
	global_load_lds_dwordx4 v196, s[62:63]
	s_waitcnt vmcnt(6)
	s_waitcnt lgkmcnt(0)
	s_setprio 1
	s_barrier
; #define PG8_STAGE(bufoff, gbase, voff) do { _Pragma("unroll") for (int _i = 0; _i < 2; ++_i) \
;         __builtin_amdgcn_global_load_lds((const unsigned*)((const char*)(gbase) + (voff)[_i]), (PG8_LAS unsigned*)(lds + (bufoff) + ldsw + _i * 8192), 16, 0, 0); } while (0)
; #define PG8_LDA(dst, b, h) do { _Pragma("unroll") for (int m = 0; m < 4; ++m) _Pragma("unroll") for (int k = 0; k < 2; ++k) dst[m][k] = *(const PG8_LAS bf16x8*)(lds + PG8_SA(b, h) + aoff + m * 2048 + k * 1024); } while (0)
; #define PG8_LDB(dst, b, h) do { _Pragma("unroll") for (int n = 0; n < 2; ++n) _Pragma("unroll") for (int k = 0; k < 2; ++k) dst[n][k] = *(const PG8_LAS bf16x8*)(lds + PG8_SB(b, h) + boff + n * 2048 + k * 1024); } while (0)
; #define PG8_MMA(ai, bj, At, Bt) do { __builtin_amdgcn_s_setprio(1); _Pragma("unroll") for (int m = 0; m < 4; ++m) _Pragma("unroll") for (int n = 0; n < 2; ++n) _Pragma("unroll") for (int k = 0; k < 2; ++k) \
;         acc[ai][bj][m][n] = __builtin_amdgcn_mfma_f32_16x16x32_bf16(Bt[n][k], At[m][k], acc[ai][bj][m][n], 0, 0, 0); __builtin_amdgcn_s_setprio(0); } while (0)
; #define PG8_WAIT_V(n) asm volatile("s_waitcnt vmcnt(" #n ")" ::: "memory")
; #define PG8_WAIT_L(n) asm volatile("s_waitcnt lgkmcnt(" #n ")" ::: "memory")
; #define PG8_BAR __builtin_amdgcn_s_barrier()
; #define PG8_SCHED __builtin_amdgcn_sched_barrier(0)
; template <class Epi, class Sched, bool ALIGN_EPI = false, bool SP2 = false>
; __device__ __forceinline__ void gemm_phase(PG8_LAS unsigned char* lds, const Gemm g, const Sched& S, const Epi& E) {
;     ...
;             PG8_WAIT_V(8); PG8_WAIT_L(0); PG8_BAR; PG8_MMA(1, 0, At, B0); PG8_MMA(1, 1, At, B1); PG8_BAR; PG8_SCHED;
;             PG8_LDB(B0, 1, 0); PG8_LDB(B1, 1, 1); PG8_SCHED; PG8_LDA(At, 1, 0); PG8_STAGE(PG8_SA(0, 1), a2 + hstepA, voffA);
	v_mfma_f32_16x16x32_bf16 v[60:63], v[136:139], v[168:171], 0
	v_mfma_f32_16x16x32_bf16 v[56:59], v[144:147], v[168:171], 0
	v_mfma_f32_16x16x32_bf16 v[44:47], v[136:139], v[186:189], 0
	v_mfma_f32_16x16x32_bf16 v[40:43], v[144:147], v[186:189], 0
	v_mfma_f32_16x16x32_bf16 v[28:31], v[136:139], v[208:211], 0
	v_mfma_f32_16x16x32_bf16 v[24:27], v[144:147], v[208:211], 0
	v_mfma_f32_16x16x32_bf16 v[12:15], v[136:139], v[216:219], 0
	v_mfma_f32_16x16x32_bf16 v[8:11], v[144:147], v[216:219], 0
	v_mfma_f32_16x16x32_bf16 v[60:63], v[140:143], v[172:175], v[60:63]
	v_mfma_f32_16x16x32_bf16 v[56:59], v[148:151], v[172:175], v[56:59]
	v_mfma_f32_16x16x32_bf16 v[44:47], v[140:143], v[204:207], v[44:47]
	v_mfma_f32_16x16x32_bf16 v[40:43], v[148:151], v[204:207], v[40:43]
	v_mfma_f32_16x16x32_bf16 v[28:31], v[140:143], v[212:215], v[28:31]
	v_mfma_f32_16x16x32_bf16 v[24:27], v[148:151], v[212:215], v[24:27]
	v_mfma_f32_16x16x32_bf16 v[12:15], v[140:143], v[220:223], v[12:15]
	v_mfma_f32_16x16x32_bf16 v[8:11], v[148:151], v[220:223], v[8:11]
	v_mfma_f32_16x16x32_bf16 v[52:55], v[152:155], v[168:171], 0
	v_mfma_f32_16x16x32_bf16 v[48:51], v[160:163], v[168:171], 0
	v_mfma_f32_16x16x32_bf16 v[36:39], v[152:155], v[186:189], 0
	v_mfma_f32_16x16x32_bf16 v[32:35], v[160:163], v[186:189], 0
	v_mfma_f32_16x16x32_bf16 v[20:23], v[152:155], v[208:211], 0
	v_mfma_f32_16x16x32_bf16 v[16:19], v[160:163], v[208:211], 0
	v_mfma_f32_16x16x32_bf16 v[4:7], v[152:155], v[216:219], 0
	v_mfma_f32_16x16x32_bf16 v[0:3], v[160:163], v[216:219], 0
	v_mfma_f32_16x16x32_bf16 v[52:55], v[156:159], v[172:175], v[52:55]
	v_mfma_f32_16x16x32_bf16 v[48:51], v[164:167], v[172:175], v[48:51]
	v_mfma_f32_16x16x32_bf16 v[36:39], v[156:159], v[204:207], v[36:39]
	v_mfma_f32_16x16x32_bf16 v[32:35], v[164:167], v[204:207], v[32:35]
	v_mfma_f32_16x16x32_bf16 v[20:23], v[156:159], v[212:215], v[20:23]
	v_mfma_f32_16x16x32_bf16 v[16:19], v[164:167], v[212:215], v[16:19]
	v_mfma_f32_16x16x32_bf16 v[4:7], v[156:159], v[220:223], v[4:7]
	v_mfma_f32_16x16x32_bf16 v[0:3], v[164:167], v[220:223], v[0:3]
	s_barrier
	s_setprio 0
	s_add_i32 s61, 0, 0x18000
	s_add_i32 s62, 0, 0x1c000
	v_add_u32_e32 v148, s61, v179
	v_add_u32_e32 v164, s62, v179
	ds_read_b128 v[136:139], v148
	ds_read_b128 v[140:143], v148 offset:1024
	ds_read_b128 v[144:147], v148 offset:2048
	ds_read_b128 v[148:151], v148 offset:3072
	ds_read_b128 v[152:155], v164
	ds_read_b128 v[156:159], v164 offset:1024
	ds_read_b128 v[160:163], v164 offset:2048
	ds_read_b128 v[164:167], v164 offset:3072
	s_mov_b32 m0, s13
	s_nop 0
	global_load_lds_dwordx4 v192, s[46:47]
	s_mov_b32 m0, s14
	s_nop 0
	global_load_lds_dwordx4 v196, s[46:47]
	s_add_u32 s46, s46, 0x80000
	s_addc_u32 s47, s47, 0
	s_mov_b32 m0, s15
	ds_read_b128 v[168:171], v183 offset:32768
	ds_read_b128 v[172:175], v183 offset:33792
	ds_read_b128 v[186:189], v183 offset:34816
	ds_read_b128 v[204:207], v183 offset:35840
	ds_read_b128 v[208:211], v183 offset:36864
	ds_read_b128 v[212:215], v183 offset:37888
	ds_read_b128 v[216:219], v183 offset:38912
	ds_read_b128 v[220:223], v183 offset:39936
	global_load_lds_dwordx4 v192, s[46:47]
	s_mov_b32 m0, s41
	s_nop 0
	global_load_lds_dwordx4 v196, s[46:47]
	s_waitcnt vmcnt(8)
	s_waitcnt lgkmcnt(0)
	s_setprio 1
	s_barrier
; #define PG8_STAGE(bufoff, gbase, voff) do { _Pragma("unroll") for (int _i = 0; _i < 2; ++_i) \
;         __builtin_amdgcn_global_load_lds((const unsigned*)((const char*)(gbase) + (voff)[_i]), (PG8_LAS unsigned*)(lds + (bufoff) + ldsw + _i * 8192), 16, 0, 0); } while (0)
; #define PG8_LDA(dst, b, h) do { _Pragma("unroll") for (int m = 0; m < 4; ++m) _Pragma("unroll") for (int k = 0; k < 2; ++k) dst[m][k] = *(const PG8_LAS bf16x8*)(lds + PG8_SA(b, h) + aoff + m * 2048 + k * 1024); } while (0)
; #define PG8_MMA(ai, bj, At, Bt) do { __builtin_amdgcn_s_setprio(1); _Pragma("unroll") for (int m = 0; m < 4; ++m) _Pragma("unroll") for (int n = 0; n < 2; ++n) _Pragma("unroll") for (int k = 0; k < 2; ++k) \
;         acc[ai][bj][m][n] = __builtin_amdgcn_mfma_f32_16x16x32_bf16(Bt[n][k], At[m][k], acc[ai][bj][m][n], 0, 0, 0); __builtin_amdgcn_s_setprio(0); } while (0)
; #define PG8_WAIT_V(n) asm volatile("s_waitcnt vmcnt(" #n ")" ::: "memory")
; #define PG8_WAIT_L(n) asm volatile("s_waitcnt lgkmcnt(" #n ")" ::: "memory")
; #define PG8_BAR __builtin_amdgcn_s_barrier()
; #define PG8_SCHED __builtin_amdgcn_sched_barrier(0)
; template <class Epi, class Sched, bool ALIGN_EPI = false, bool SP2 = false>
; __device__ __forceinline__ void gemm_phase(PG8_LAS unsigned char* lds, const Gemm g, const Sched& S, const Epi& E) {
;     ...
;         for (int t = 0; t < nt; t += 2) {
;     ...
;             PG8_WAIT_V(8); PG8_WAIT_L(0); PG8_BAR; PG8_MMA(0, 0, At, B0); PG8_MMA(0, 1, At, B1); PG8_BAR; PG8_SCHED;
;             PG8_LDA(At, 1, 1); PG8_STAGE(PG8_SB(1, 0), b3, voffB); PG8_STAGE(PG8_SB(1, 1), b3 + hstepB, voffB); PG8_STAGE(PG8_SA(1, 0), a3, voffA);
;             PG8_WAIT_V(8); PG8_WAIT_L(0); PG8_BAR; PG8_MMA(1, 0, At, B0); PG8_MMA(1, 1, At, B1); PG8_BAR; PG8_SCHED;
	v_mfma_f32_16x16x32_bf16 v[124:127], v[136:139], v[168:171], v[124:127]
	v_mfma_f32_16x16x32_bf16 v[120:123], v[144:147], v[168:171], v[120:123]
	v_mfma_f32_16x16x32_bf16 v[108:111], v[136:139], v[186:189], v[108:111]
	v_mfma_f32_16x16x32_bf16 v[104:107], v[144:147], v[186:189], v[104:107]
	v_mfma_f32_16x16x32_bf16 v[92:95], v[136:139], v[208:211], v[92:95]
	v_mfma_f32_16x16x32_bf16 v[88:91], v[144:147], v[208:211], v[88:91]
	v_mfma_f32_16x16x32_bf16 v[76:79], v[136:139], v[216:219], v[76:79]
	v_mfma_f32_16x16x32_bf16 v[72:75], v[144:147], v[216:219], v[72:75]
	v_mfma_f32_16x16x32_bf16 v[124:127], v[140:143], v[172:175], v[124:127]
	v_mfma_f32_16x16x32_bf16 v[120:123], v[148:151], v[172:175], v[120:123]
	v_mfma_f32_16x16x32_bf16 v[108:111], v[140:143], v[204:207], v[108:111]
	v_mfma_f32_16x16x32_bf16 v[104:107], v[148:151], v[204:207], v[104:107]
	v_mfma_f32_16x16x32_bf16 v[92:95], v[140:143], v[212:215], v[92:95]
	v_mfma_f32_16x16x32_bf16 v[88:91], v[148:151], v[212:215], v[88:91]
	v_mfma_f32_16x16x32_bf16 v[76:79], v[140:143], v[220:223], v[76:79]
	v_mfma_f32_16x16x32_bf16 v[72:75], v[148:151], v[220:223], v[72:75]
	v_mfma_f32_16x16x32_bf16 v[116:119], v[152:155], v[168:171], v[116:119]
	v_mfma_f32_16x16x32_bf16 v[112:115], v[160:163], v[168:171], v[112:115]
	v_mfma_f32_16x16x32_bf16 v[100:103], v[152:155], v[186:189], v[100:103]
	v_mfma_f32_16x16x32_bf16 v[96:99], v[160:163], v[186:189], v[96:99]
	v_mfma_f32_16x16x32_bf16 v[84:87], v[152:155], v[208:211], v[84:87]
	v_mfma_f32_16x16x32_bf16 v[80:83], v[160:163], v[208:211], v[80:83]
	v_mfma_f32_16x16x32_bf16 v[68:71], v[152:155], v[216:219], v[68:71]
	v_mfma_f32_16x16x32_bf16 v[64:67], v[160:163], v[216:219], v[64:67]
	v_mfma_f32_16x16x32_bf16 v[116:119], v[156:159], v[172:175], v[116:119]
	v_mfma_f32_16x16x32_bf16 v[112:115], v[164:167], v[172:175], v[112:115]
	v_mfma_f32_16x16x32_bf16 v[100:103], v[156:159], v[204:207], v[100:103]
	v_mfma_f32_16x16x32_bf16 v[96:99], v[164:167], v[204:207], v[96:99]
	v_mfma_f32_16x16x32_bf16 v[84:87], v[156:159], v[212:215], v[84:87]
	v_mfma_f32_16x16x32_bf16 v[80:83], v[164:167], v[212:215], v[80:83]
	v_mfma_f32_16x16x32_bf16 v[68:71], v[156:159], v[220:223], v[68:71]
	v_mfma_f32_16x16x32_bf16 v[64:67], v[164:167], v[220:223], v[64:67]
	s_barrier
	s_setprio 0
	s_add_i32 s46, s61, s2
	s_mov_b32 m0, s46
	ds_read_b128 v[168:171], v183 offset:49152
	ds_read_b128 v[172:175], v183 offset:50176
	ds_read_b128 v[186:189], v183 offset:51200
	ds_read_b128 v[204:207], v183 offset:52224
	ds_read_b128 v[208:211], v183 offset:53248
	ds_read_b128 v[212:215], v183 offset:54272
	ds_read_b128 v[216:219], v183 offset:55296
	ds_read_b128 v[220:223], v183 offset:56320
	global_load_lds_dwordx4 v192, s[98:99]
	s_add_i32 m0, s46, 0x2000
	s_add_u32 s44, s44, 0x80080
	s_addc_u32 s45, s45, 0
	s_add_i32 s46, s62, s2
	global_load_lds_dwordx4 v196, s[98:99]
	s_mov_b32 m0, s46
	s_nop 0
	global_load_lds_dwordx4 v192, s[44:45]
	s_add_i32 m0, s46, 0x2000
	s_nop 0
	global_load_lds_dwordx4 v196, s[44:45]
	s_waitcnt vmcnt(6)
	s_waitcnt lgkmcnt(0)
	s_setprio 1
	s_barrier
	v_mfma_f32_16x16x32_bf16 v[60:63], v[136:139], v[168:171], v[60:63]
	v_mfma_f32_16x16x32_bf16 v[56:59], v[144:147], v[168:171], v[56:59]
	v_mfma_f32_16x16x32_bf16 v[44:47], v[136:139], v[186:189], v[44:47]
	v_mfma_f32_16x16x32_bf16 v[40:43], v[144:147], v[186:189], v[40:43]
	v_mfma_f32_16x16x32_bf16 v[28:31], v[136:139], v[208:211], v[28:31]
	v_mfma_f32_16x16x32_bf16 v[24:27], v[144:147], v[208:211], v[24:27]
	v_mfma_f32_16x16x32_bf16 v[12:15], v[136:139], v[216:219], v[12:15]
	v_mfma_f32_16x16x32_bf16 v[8:11], v[144:147], v[216:219], v[8:11]
	v_mfma_f32_16x16x32_bf16 v[60:63], v[140:143], v[172:175], v[60:63]
	v_mfma_f32_16x16x32_bf16 v[56:59], v[148:151], v[172:175], v[56:59]
	v_mfma_f32_16x16x32_bf16 v[44:47], v[140:143], v[204:207], v[44:47]
	v_mfma_f32_16x16x32_bf16 v[40:43], v[148:151], v[204:207], v[40:43]
	v_mfma_f32_16x16x32_bf16 v[28:31], v[140:143], v[212:215], v[28:31]
	v_mfma_f32_16x16x32_bf16 v[24:27], v[148:151], v[212:215], v[24:27]
	v_mfma_f32_16x16x32_bf16 v[12:15], v[140:143], v[220:223], v[12:15]
	v_mfma_f32_16x16x32_bf16 v[8:11], v[148:151], v[220:223], v[8:11]
	v_mfma_f32_16x16x32_bf16 v[52:55], v[152:155], v[168:171], v[52:55]
	v_mfma_f32_16x16x32_bf16 v[48:51], v[160:163], v[168:171], v[48:51]
	v_mfma_f32_16x16x32_bf16 v[36:39], v[152:155], v[186:189], v[36:39]
	v_mfma_f32_16x16x32_bf16 v[32:35], v[160:163], v[186:189], v[32:35]
	v_mfma_f32_16x16x32_bf16 v[20:23], v[152:155], v[208:211], v[20:23]
	v_mfma_f32_16x16x32_bf16 v[16:19], v[160:163], v[208:211], v[16:19]
	v_mfma_f32_16x16x32_bf16 v[4:7], v[152:155], v[216:219], v[4:7]
	v_mfma_f32_16x16x32_bf16 v[0:3], v[160:163], v[216:219], v[0:3]
	v_mfma_f32_16x16x32_bf16 v[52:55], v[156:159], v[172:175], v[52:55]
	v_mfma_f32_16x16x32_bf16 v[48:51], v[164:167], v[172:175], v[48:51]
	v_mfma_f32_16x16x32_bf16 v[36:39], v[156:159], v[204:207], v[36:39]
	v_mfma_f32_16x16x32_bf16 v[32:35], v[164:167], v[204:207], v[32:35]
	v_mfma_f32_16x16x32_bf16 v[20:23], v[156:159], v[212:215], v[20:23]
	v_mfma_f32_16x16x32_bf16 v[16:19], v[164:167], v[212:215], v[16:19]
	v_mfma_f32_16x16x32_bf16 v[4:7], v[156:159], v[220:223], v[4:7]
	v_mfma_f32_16x16x32_bf16 v[0:3], v[164:167], v[220:223], v[0:3]
	s_barrier
	s_setprio 0
	s_add_u32 s42, s42, 0x100
	s_addc_u32 s43, s43, 0
	s_add_u32 s58, s58, 0x100
	s_addc_u32 s59, s59, 0
	s_cmp_ge_i32 s60, s56
	s_mov_b32 s44, s60
	s_cbranch_scc1 .Lpeel_exit_4

; #define PG8_BAR __builtin_amdgcn_s_barrier()
; template <class Epi, class Sched, bool ALIGN_EPI = false, bool SP2 = false>
; __device__ __forceinline__ void gemm_phase(PG8_LAS unsigned char* lds, const Gemm g, const Sched& S, const Epi& E) {
;     ...
;         if constexpr (ALIGN_EPI) { if (wr == 0) PG8_BAR; }
;         if constexpr (!Epi::AFTER_DRAIN) { if (cur.part < 0) E(acc, cur, wr, wc, fr, fq); else store_part<Epi::PERM>(acc, cur, g.part, wr, wc, fr, fq); S.done(cur); }
.Lpeel_exit_4:
	s_and_b64 vcc, exec, s[22:23]
	s_cbranch_vccnz .LBB0_1118
	s_mov_b64 s[42:43], -1
	s_cmp_gt_i32 s16, -1
	v_lshl_or_b32 v136, s40, 8, v180
	s_cbranch_scc1 .LBB0_1119

; #define PG8_STAGE(bufoff, gbase, voff) do { _Pragma("unroll") for (int _i = 0; _i < 2; ++_i) \
;         __builtin_amdgcn_global_load_lds((const unsigned*)((const char*)(gbase) + (voff)[_i]), (PG8_LAS unsigned*)(lds + (bufoff) + ldsw + _i * 8192), 16, 0, 0); } while (0)
; #define PG8_LDA(dst, b, h) do { _Pragma("unroll") for (int m = 0; m < 4; ++m) _Pragma("unroll") for (int k = 0; k < 2; ++k) dst[m][k] = *(const PG8_LAS bf16x8*)(lds + PG8_SA(b, h) + aoff + m * 2048 + k * 1024); } while (0)
; #define PG8_LDB(dst, b, h) do { _Pragma("unroll") for (int n = 0; n < 2; ++n) _Pragma("unroll") for (int k = 0; k < 2; ++k) dst[n][k] = *(const PG8_LAS bf16x8*)(lds + PG8_SB(b, h) + boff + n * 2048 + k * 1024); } while (0)
; #define PG8_MMA(ai, bj, At, Bt) do { __builtin_amdgcn_s_setprio(1); _Pragma("unroll") for (int m = 0; m < 4; ++m) _Pragma("unroll") for (int n = 0; n < 2; ++n) _Pragma("unroll") for (int k = 0; k < 2; ++k) \
;         acc[ai][bj][m][n] = __builtin_amdgcn_mfma_f32_16x16x32_bf16(Bt[n][k], At[m][k], acc[ai][bj][m][n], 0, 0, 0); __builtin_amdgcn_s_setprio(0); } while (0)
; #define PG8_WAIT_V(n) asm volatile("s_waitcnt vmcnt(" #n ")" ::: "memory")
; #define PG8_WAIT_L(n) asm volatile("s_waitcnt lgkmcnt(" #n ")" ::: "memory")
; template <class Epi, class Sched, bool ALIGN_EPI = false, bool SP2 = false>
; __device__ __forceinline__ void gemm_phase(PG8_LAS unsigned char* lds, const Gemm g, const Sched& S, const Epi& E) {
;     ...
;             const bool last = (t == nt - 2);
;             const char* a1 = cA + (size_t)(t + 1) * kstepA;
;             const char* a2 = last ? nA : cA + (size_t)(t + 2) * kstepA; const char* b2 = last ? nB : cB + (size_t)(t + 2) * kstepB;
;             const char* a3 = a2 + kstepA; const char* b3 = b2 + kstepB;
;             if (last && has_next) S.a_ready(nxt);
;             if constexpr (SP2) {
;             PG8_LDB(B0, 0, 0); PG8_LDB(B1, 0, 1); PG8_SCHED; PG8_LDA(At, 0, 0); PG8_STAGE(PG8_SA(1, 1), a1 + hstepA, voffA);
;             PG8_WAIT_V(8); PG8_WAIT_L(0); PG8_BAR; PG8_MMA(0, 0, At, B0); PG8_MMA(0, 1, At, B1); PG8_BAR; PG8_SCHED;
;             PG8_LDA(At, 0, 1); PG8_STAGE(PG8_SB(0, 0), b2, voffB); PG8_STAGE(PG8_SB(0, 1), b2 + hstepB, voffB); PG8_STAGE(PG8_SA(0, 0), a2, voffA);
;             PG8_WAIT_V(8); PG8_WAIT_L(0); PG8_BAR; PG8_MMA(1, 0, At, B0); PG8_MMA(1, 1, At, B1); PG8_BAR; PG8_SCHED;
.Lhf10:
	s_ashr_i32 s23, s22, 31
	s_lshl_b64 s[26:27], s[22:23], 20
	s_add_u32 s26, s96, s26
	s_addc_u32 s27, s97, s27
	s_and_b64 s[28:29], s[24:25], exec
	s_cselect_b32 s23, s27, s37
	s_cselect_b32 s49, s26, s36
	s_ashr_i32 s21, s20, 31
	s_lshl_b64 s[28:29], s[20:21], 20
	s_add_u32 s28, s10, s28
	s_addc_u32 s29, s14, s29
	s_and_b64 s[38:39], s[24:25], exec
	s_cselect_b32 s21, s29, s35
	s_cselect_b32 s50, s28, s34
	s_add_u32 s51, s34, 0x10000
	s_addc_u32 s52, s35, 0
	s_add_u32 s34, s36, 0x80080
	s_addc_u32 s35, s37, 0
	s_mov_b32 s53, -2
	s_sub_u32 s100, s34, 0x80000
	s_subb_u32 s101, s35, 0
	ds_read_b128 v[136:139], v129
	ds_read_b128 v[144:147], v129 offset:1024
	ds_read_b128 v[148:151], v129 offset:2048
	ds_read_b128 v[152:155], v129 offset:3072
	ds_read_b128 v[156:159], v141
	ds_read_b128 v[160:163], v141 offset:1024
	ds_read_b128 v[164:167], v141 offset:2048
	ds_read_b128 v[168:171], v141 offset:3072
	s_add_u32 s36, s34, 0xfff80080
	s_addc_u32 s37, s35, -1
	s_cmp_eq_u32 s53, 28
	s_cselect_b32 s39, s23, s37
	s_cselect_b32 s38, s49, s36
	s_cselect_b32 s37, s21, s52
	s_cselect_b32 s36, s50, s51
	ds_read_b128 v[172:175], v142
	ds_read_b128 v[176:179], v142 offset:1024
	ds_read_b128 v[180:183], v142 offset:2048
	ds_read_b128 v[184:187], v142 offset:3072
	ds_read_b128 v[188:191], v142 offset:4096
	ds_read_b128 v[204:207], v142 offset:5120
	ds_read_b128 v[208:211], v142 offset:6144
	ds_read_b128 v[212:215], v142 offset:7168
	s_mov_b32 m0, s43
	s_nop 0
	global_load_lds_dwordx4 v132, s[100:101]
	s_mov_b32 m0, s44
	s_nop 0
	global_load_lds_dwordx4 v134, s[100:101]
	s_add_i32 m0, s15, 0xc000
	s_nop 0
	global_load_lds_dwordx4 v132, s[34:35]
	s_add_i32 m0, s15, 0xe000
	s_nop 0
	global_load_lds_dwordx4 v134, s[34:35]
	s_waitcnt vmcnt(8)
	s_waitcnt lgkmcnt(0)
	s_setprio 1
	s_barrier
	v_mfma_f32_16x16x32_bf16 v[124:127], v[136:139], v[172:175], 0
	v_mfma_f32_16x16x32_bf16 v[120:123], v[148:151], v[172:175], 0
	v_mfma_f32_16x16x32_bf16 v[108:111], v[136:139], v[180:183], 0
	v_mfma_f32_16x16x32_bf16 v[104:107], v[148:151], v[180:183], 0
	v_mfma_f32_16x16x32_bf16 v[92:95], v[136:139], v[188:191], 0
	v_mfma_f32_16x16x32_bf16 v[88:91], v[148:151], v[188:191], 0
	v_mfma_f32_16x16x32_bf16 v[76:79], v[136:139], v[208:211], 0
	v_mfma_f32_16x16x32_bf16 v[72:75], v[148:151], v[208:211], 0
	v_mfma_f32_16x16x32_bf16 v[124:127], v[144:147], v[176:179], v[124:127]
	v_mfma_f32_16x16x32_bf16 v[120:123], v[152:155], v[176:179], v[120:123]
	v_mfma_f32_16x16x32_bf16 v[108:111], v[144:147], v[184:187], v[108:111]
	v_mfma_f32_16x16x32_bf16 v[104:107], v[152:155], v[184:187], v[104:107]
	v_mfma_f32_16x16x32_bf16 v[92:95], v[144:147], v[204:207], v[92:95]
	v_mfma_f32_16x16x32_bf16 v[88:91], v[152:155], v[204:207], v[88:91]
	v_mfma_f32_16x16x32_bf16 v[76:79], v[144:147], v[212:215], v[76:79]
	v_mfma_f32_16x16x32_bf16 v[72:75], v[152:155], v[212:215], v[72:75]
	v_mfma_f32_16x16x32_bf16 v[116:119], v[156:159], v[172:175], 0
	v_mfma_f32_16x16x32_bf16 v[112:115], v[164:167], v[172:175], 0
	v_mfma_f32_16x16x32_bf16 v[100:103], v[156:159], v[180:183], 0
	v_mfma_f32_16x16x32_bf16 v[96:99], v[164:167], v[180:183], 0
	v_mfma_f32_16x16x32_bf16 v[84:87], v[156:159], v[188:191], 0
	v_mfma_f32_16x16x32_bf16 v[80:83], v[164:167], v[188:191], 0
	v_mfma_f32_16x16x32_bf16 v[68:71], v[156:159], v[208:211], 0
	v_mfma_f32_16x16x32_bf16 v[64:67], v[164:167], v[208:211], 0
	v_mfma_f32_16x16x32_bf16 v[116:119], v[160:163], v[176:179], v[116:119]
	v_mfma_f32_16x16x32_bf16 v[112:115], v[168:171], v[176:179], v[112:115]
	v_mfma_f32_16x16x32_bf16 v[100:103], v[160:163], v[184:187], v[100:103]
	v_mfma_f32_16x16x32_bf16 v[96:99], v[168:171], v[184:187], v[96:99]
	v_mfma_f32_16x16x32_bf16 v[84:87], v[160:163], v[204:207], v[84:87]
	v_mfma_f32_16x16x32_bf16 v[80:83], v[168:171], v[204:207], v[80:83]
	v_mfma_f32_16x16x32_bf16 v[68:71], v[160:163], v[212:215], v[68:71]
	v_mfma_f32_16x16x32_bf16 v[64:67], v[168:171], v[212:215], v[64:67]
	s_barrier
	s_setprio 0
	s_add_i32 s54, s46, s2
	s_mov_b32 m0, s54
	ds_read_b128 v[172:175], v142 offset:16384
	ds_read_b128 v[176:179], v142 offset:17408
	ds_read_b128 v[180:183], v142 offset:18432
	ds_read_b128 v[184:187], v142 offset:19456
	ds_read_b128 v[188:191], v142 offset:20480
	ds_read_b128 v[204:207], v142 offset:21504
	ds_read_b128 v[208:211], v142 offset:22528
	ds_read_b128 v[212:215], v142 offset:23552
	global_load_lds_dwordx4 v194, s[36:37]
	s_add_i32 m0, s54, 0x2000
	s_add_u32 s54, s36, 0x4000
	s_addc_u32 s55, s37, 0
	s_add_i32 s56, s47, s2
	global_load_lds_dwordx4 v198, s[36:37]
	s_mov_b32 m0, s56
	s_nop 0
	global_load_lds_dwordx4 v194, s[54:55]
	s_add_i32 m0, s56, 0x2000
	s_nop 0
	global_load_lds_dwordx4 v198, s[54:55]
	s_waitcnt vmcnt(6)
	s_waitcnt lgkmcnt(0)
	s_setprio 1
	s_barrier
; #define PG8_STAGE(bufoff, gbase, voff) do { _Pragma("unroll") for (int _i = 0; _i < 2; ++_i) \
;         __builtin_amdgcn_global_load_lds((const unsigned*)((const char*)(gbase) + (voff)[_i]), (PG8_LAS unsigned*)(lds + (bufoff) + ldsw + _i * 8192), 16, 0, 0); } while (0)
; #define PG8_LDA(dst, b, h) do { _Pragma("unroll") for (int m = 0; m < 4; ++m) _Pragma("unroll") for (int k = 0; k < 2; ++k) dst[m][k] = *(const PG8_LAS bf16x8*)(lds + PG8_SA(b, h) + aoff + m * 2048 + k * 1024); } while (0)
; #define PG8_LDB(dst, b, h) do { _Pragma("unroll") for (int n = 0; n < 2; ++n) _Pragma("unroll") for (int k = 0; k < 2; ++k) dst[n][k] = *(const PG8_LAS bf16x8*)(lds + PG8_SB(b, h) + boff + n * 2048 + k * 1024); } while (0)
; #define PG8_MMA(ai, bj, At, Bt) do { __builtin_amdgcn_s_setprio(1); _Pragma("unroll") for (int m = 0; m < 4; ++m) _Pragma("unroll") for (int n = 0; n < 2; ++n) _Pragma("unroll") for (int k = 0; k < 2; ++k) \
;         acc[ai][bj][m][n] = __builtin_amdgcn_mfma_f32_16x16x32_bf16(Bt[n][k], At[m][k], acc[ai][bj][m][n], 0, 0, 0); __builtin_amdgcn_s_setprio(0); } while (0)
; #define PG8_WAIT_V(n) asm volatile("s_waitcnt vmcnt(" #n ")" ::: "memory")
; #define PG8_WAIT_L(n) asm volatile("s_waitcnt lgkmcnt(" #n ")" ::: "memory")
; #define PG8_BAR __builtin_amdgcn_s_barrier()
; #define PG8_SCHED __builtin_amdgcn_sched_barrier(0)
; template <class Epi, class Sched, bool ALIGN_EPI = false, bool SP2 = false>
; __device__ __forceinline__ void gemm_phase(PG8_LAS unsigned char* lds, const Gemm g, const Sched& S, const Epi& E) {
;     ...
;             PG8_WAIT_V(8); PG8_WAIT_L(0); PG8_BAR; PG8_MMA(1, 0, At, B0); PG8_MMA(1, 1, At, B1); PG8_BAR; PG8_SCHED;
;             PG8_LDB(B0, 1, 0); PG8_LDB(B1, 1, 1); PG8_SCHED; PG8_LDA(At, 1, 0); PG8_STAGE(PG8_SA(0, 1), a2 + hstepA, voffA);
	v_mfma_f32_16x16x32_bf16 v[60:63], v[136:139], v[172:175], 0
	v_mfma_f32_16x16x32_bf16 v[56:59], v[148:151], v[172:175], 0
	v_mfma_f32_16x16x32_bf16 v[44:47], v[136:139], v[180:183], 0
	v_mfma_f32_16x16x32_bf16 v[40:43], v[148:151], v[180:183], 0
	v_mfma_f32_16x16x32_bf16 v[28:31], v[136:139], v[188:191], 0
	v_mfma_f32_16x16x32_bf16 v[24:27], v[148:151], v[188:191], 0
	v_mfma_f32_16x16x32_bf16 v[12:15], v[136:139], v[208:211], 0
	v_mfma_f32_16x16x32_bf16 v[8:11], v[148:151], v[208:211], 0
	v_mfma_f32_16x16x32_bf16 v[60:63], v[144:147], v[176:179], v[60:63]
	v_mfma_f32_16x16x32_bf16 v[56:59], v[152:155], v[176:179], v[56:59]
	v_mfma_f32_16x16x32_bf16 v[44:47], v[144:147], v[184:187], v[44:47]
	v_mfma_f32_16x16x32_bf16 v[40:43], v[152:155], v[184:187], v[40:43]
	v_mfma_f32_16x16x32_bf16 v[28:31], v[144:147], v[204:207], v[28:31]
	v_mfma_f32_16x16x32_bf16 v[24:27], v[152:155], v[204:207], v[24:27]
	v_mfma_f32_16x16x32_bf16 v[12:15], v[144:147], v[212:215], v[12:15]
	v_mfma_f32_16x16x32_bf16 v[8:11], v[152:155], v[212:215], v[8:11]
	v_mfma_f32_16x16x32_bf16 v[52:55], v[156:159], v[172:175], 0
	v_mfma_f32_16x16x32_bf16 v[48:51], v[164:167], v[172:175], 0
	v_mfma_f32_16x16x32_bf16 v[36:39], v[156:159], v[180:183], 0
	v_mfma_f32_16x16x32_bf16 v[32:35], v[164:167], v[180:183], 0
	v_mfma_f32_16x16x32_bf16 v[20:23], v[156:159], v[188:191], 0
	v_mfma_f32_16x16x32_bf16 v[16:19], v[164:167], v[188:191], 0
	v_mfma_f32_16x16x32_bf16 v[4:7], v[156:159], v[208:211], 0
	v_mfma_f32_16x16x32_bf16 v[0:3], v[164:167], v[208:211], 0
	v_mfma_f32_16x16x32_bf16 v[52:55], v[160:163], v[176:179], v[52:55]
	v_mfma_f32_16x16x32_bf16 v[48:51], v[168:171], v[176:179], v[48:51]
	v_mfma_f32_16x16x32_bf16 v[36:39], v[160:163], v[184:187], v[36:39]
	v_mfma_f32_16x16x32_bf16 v[32:35], v[168:171], v[184:187], v[32:35]
	v_mfma_f32_16x16x32_bf16 v[20:23], v[160:163], v[204:207], v[20:23]
	v_mfma_f32_16x16x32_bf16 v[16:19], v[168:171], v[204:207], v[16:19]
	v_mfma_f32_16x16x32_bf16 v[4:7], v[160:163], v[212:215], v[4:7]
	v_mfma_f32_16x16x32_bf16 v[0:3], v[168:171], v[212:215], v[0:3]
	s_barrier
	s_setprio 0
	s_add_i32 s54, 0, 0x18000
	s_add_i32 s55, 0, 0x1c000
	v_add_u32_e32 v152, s54, v140
	v_add_u32_e32 v168, s55, v140
	ds_read_b128 v[136:139], v152
	ds_read_b128 v[144:147], v152 offset:1024
	ds_read_b128 v[148:151], v152 offset:2048
	ds_read_b128 v[152:155], v152 offset:3072
	ds_read_b128 v[156:159], v168
	ds_read_b128 v[160:163], v168 offset:1024
	ds_read_b128 v[164:167], v168 offset:2048
	ds_read_b128 v[168:171], v168 offset:3072
	s_mov_b32 m0, s15
	s_nop 0
	global_load_lds_dwordx4 v192, s[38:39]
	s_mov_b32 m0, s40
	s_nop 0
	global_load_lds_dwordx4 v196, s[38:39]
	s_add_u32 s38, s38, 0x80000
	s_addc_u32 s39, s39, 0
	s_mov_b32 m0, s41
	ds_read_b128 v[172:175], v142 offset:32768
	ds_read_b128 v[176:179], v142 offset:33792
	ds_read_b128 v[180:183], v142 offset:34816
	ds_read_b128 v[184:187], v142 offset:35840
	ds_read_b128 v[188:191], v142 offset:36864
	ds_read_b128 v[204:207], v142 offset:37888
	ds_read_b128 v[208:211], v142 offset:38912
	ds_read_b128 v[212:215], v142 offset:39936
	global_load_lds_dwordx4 v192, s[38:39]
	s_mov_b32 m0, s42
	s_nop 0
	global_load_lds_dwordx4 v196, s[38:39]
	s_waitcnt vmcnt(8)
	s_waitcnt lgkmcnt(0)
	s_setprio 1
	s_barrier
; #define PG8_STAGE(bufoff, gbase, voff) do { _Pragma("unroll") for (int _i = 0; _i < 2; ++_i) \
;         __builtin_amdgcn_global_load_lds((const unsigned*)((const char*)(gbase) + (voff)[_i]), (PG8_LAS unsigned*)(lds + (bufoff) + ldsw + _i * 8192), 16, 0, 0); } while (0)
; #define PG8_LDA(dst, b, h) do { _Pragma("unroll") for (int m = 0; m < 4; ++m) _Pragma("unroll") for (int k = 0; k < 2; ++k) dst[m][k] = *(const PG8_LAS bf16x8*)(lds + PG8_SA(b, h) + aoff + m * 2048 + k * 1024); } while (0)
; #define PG8_MMA(ai, bj, At, Bt) do { __builtin_amdgcn_s_setprio(1); _Pragma("unroll") for (int m = 0; m < 4; ++m) _Pragma("unroll") for (int n = 0; n < 2; ++n) _Pragma("unroll") for (int k = 0; k < 2; ++k) \
;         acc[ai][bj][m][n] = __builtin_amdgcn_mfma_f32_16x16x32_bf16(Bt[n][k], At[m][k], acc[ai][bj][m][n], 0, 0, 0); __builtin_amdgcn_s_setprio(0); } while (0)
; #define PG8_WAIT_V(n) asm volatile("s_waitcnt vmcnt(" #n ")" ::: "memory")
; #define PG8_WAIT_L(n) asm volatile("s_waitcnt lgkmcnt(" #n ")" ::: "memory")
; #define PG8_BAR __builtin_amdgcn_s_barrier()
; #define PG8_SCHED __builtin_amdgcn_sched_barrier(0)
; template <class Epi, class Sched, bool ALIGN_EPI = false, bool SP2 = false>
; __device__ __forceinline__ void gemm_phase(PG8_LAS unsigned char* lds, const Gemm g, const Sched& S, const Epi& E) {
;     ...
;         for (int t = 0; t < nt; t += 2) {
;     ...
;             PG8_WAIT_V(8); PG8_WAIT_L(0); PG8_BAR; PG8_MMA(0, 0, At, B0); PG8_MMA(0, 1, At, B1); PG8_BAR; PG8_SCHED;
;             PG8_LDA(At, 1, 1); PG8_STAGE(PG8_SB(1, 0), b3, voffB); PG8_STAGE(PG8_SB(1, 1), b3 + hstepB, voffB); PG8_STAGE(PG8_SA(1, 0), a3, voffA);
;             PG8_WAIT_V(8); PG8_WAIT_L(0); PG8_BAR; PG8_MMA(1, 0, At, B0); PG8_MMA(1, 1, At, B1); PG8_BAR; PG8_SCHED;
	v_mfma_f32_16x16x32_bf16 v[124:127], v[136:139], v[172:175], v[124:127]
	v_mfma_f32_16x16x32_bf16 v[120:123], v[148:151], v[172:175], v[120:123]
	v_mfma_f32_16x16x32_bf16 v[108:111], v[136:139], v[180:183], v[108:111]
	v_mfma_f32_16x16x32_bf16 v[104:107], v[148:151], v[180:183], v[104:107]
	v_mfma_f32_16x16x32_bf16 v[92:95], v[136:139], v[188:191], v[92:95]
	v_mfma_f32_16x16x32_bf16 v[88:91], v[148:151], v[188:191], v[88:91]
	v_mfma_f32_16x16x32_bf16 v[76:79], v[136:139], v[208:211], v[76:79]
	v_mfma_f32_16x16x32_bf16 v[72:75], v[148:151], v[208:211], v[72:75]
	v_mfma_f32_16x16x32_bf16 v[124:127], v[144:147], v[176:179], v[124:127]
	v_mfma_f32_16x16x32_bf16 v[120:123], v[152:155], v[176:179], v[120:123]
	v_mfma_f32_16x16x32_bf16 v[108:111], v[144:147], v[184:187], v[108:111]
	v_mfma_f32_16x16x32_bf16 v[104:107], v[152:155], v[184:187], v[104:107]
	v_mfma_f32_16x16x32_bf16 v[92:95], v[144:147], v[204:207], v[92:95]
	v_mfma_f32_16x16x32_bf16 v[88:91], v[152:155], v[204:207], v[88:91]
	v_mfma_f32_16x16x32_bf16 v[76:79], v[144:147], v[212:215], v[76:79]
	v_mfma_f32_16x16x32_bf16 v[72:75], v[152:155], v[212:215], v[72:75]
	v_mfma_f32_16x16x32_bf16 v[116:119], v[156:159], v[172:175], v[116:119]
	v_mfma_f32_16x16x32_bf16 v[112:115], v[164:167], v[172:175], v[112:115]
	v_mfma_f32_16x16x32_bf16 v[100:103], v[156:159], v[180:183], v[100:103]
	v_mfma_f32_16x16x32_bf16 v[96:99], v[164:167], v[180:183], v[96:99]
	v_mfma_f32_16x16x32_bf16 v[84:87], v[156:159], v[188:191], v[84:87]
	v_mfma_f32_16x16x32_bf16 v[80:83], v[164:167], v[188:191], v[80:83]
	v_mfma_f32_16x16x32_bf16 v[68:71], v[156:159], v[208:211], v[68:71]
	v_mfma_f32_16x16x32_bf16 v[64:67], v[164:167], v[208:211], v[64:67]
	v_mfma_f32_16x16x32_bf16 v[116:119], v[160:163], v[176:179], v[116:119]
	v_mfma_f32_16x16x32_bf16 v[112:115], v[168:171], v[176:179], v[112:115]
	v_mfma_f32_16x16x32_bf16 v[100:103], v[160:163], v[184:187], v[100:103]
	v_mfma_f32_16x16x32_bf16 v[96:99], v[168:171], v[184:187], v[96:99]
	v_mfma_f32_16x16x32_bf16 v[84:87], v[160:163], v[204:207], v[84:87]
	v_mfma_f32_16x16x32_bf16 v[80:83], v[168:171], v[204:207], v[80:83]
	v_mfma_f32_16x16x32_bf16 v[68:71], v[160:163], v[212:215], v[68:71]
	v_mfma_f32_16x16x32_bf16 v[64:67], v[168:171], v[212:215], v[64:67]
	s_barrier
	s_setprio 0
	s_add_u32 s38, s36, 0x8000
	s_addc_u32 s39, s37, 0
	s_add_i32 s54, s54, s2
	s_mov_b32 m0, s54
	ds_read_b128 v[172:175], v142 offset:49152
	ds_read_b128 v[176:179], v142 offset:50176
	ds_read_b128 v[180:183], v142 offset:51200
	ds_read_b128 v[184:187], v142 offset:52224
	ds_read_b128 v[188:191], v142 offset:53248
	ds_read_b128 v[204:207], v142 offset:54272
	ds_read_b128 v[208:211], v142 offset:55296
	ds_read_b128 v[212:215], v142 offset:56320
	global_load_lds_dwordx4 v194, s[38:39]
	s_add_i32 m0, s54, 0x2000
	s_add_u32 s36, s36, 0xc000
	s_addc_u32 s37, s37, 0
	global_load_lds_dwordx4 v198, s[38:39]
	s_add_i32 s38, s55, s2
	s_mov_b32 m0, s38
	s_nop 0
	global_load_lds_dwordx4 v194, s[36:37]
	s_add_i32 m0, s38, 0x2000
	s_nop 0
	global_load_lds_dwordx4 v198, s[36:37]
	s_waitcnt vmcnt(6)
	s_waitcnt lgkmcnt(0)
	s_setprio 1
	s_barrier
	v_mfma_f32_16x16x32_bf16 v[60:63], v[136:139], v[172:175], v[60:63]
	v_mfma_f32_16x16x32_bf16 v[56:59], v[148:151], v[172:175], v[56:59]
	v_mfma_f32_16x16x32_bf16 v[44:47], v[136:139], v[180:183], v[44:47]
	v_mfma_f32_16x16x32_bf16 v[40:43], v[148:151], v[180:183], v[40:43]
	v_mfma_f32_16x16x32_bf16 v[28:31], v[136:139], v[188:191], v[28:31]
	v_mfma_f32_16x16x32_bf16 v[24:27], v[148:151], v[188:191], v[24:27]
	v_mfma_f32_16x16x32_bf16 v[12:15], v[136:139], v[208:211], v[12:15]
	v_mfma_f32_16x16x32_bf16 v[8:11], v[148:151], v[208:211], v[8:11]
	v_mfma_f32_16x16x32_bf16 v[60:63], v[144:147], v[176:179], v[60:63]
	v_mfma_f32_16x16x32_bf16 v[56:59], v[152:155], v[176:179], v[56:59]
	v_mfma_f32_16x16x32_bf16 v[44:47], v[144:147], v[184:187], v[44:47]
	v_mfma_f32_16x16x32_bf16 v[40:43], v[152:155], v[184:187], v[40:43]
	v_mfma_f32_16x16x32_bf16 v[28:31], v[144:147], v[204:207], v[28:31]
	v_mfma_f32_16x16x32_bf16 v[24:27], v[152:155], v[204:207], v[24:27]
	v_mfma_f32_16x16x32_bf16 v[12:15], v[144:147], v[212:215], v[12:15]
	v_mfma_f32_16x16x32_bf16 v[8:11], v[152:155], v[212:215], v[8:11]
	v_mfma_f32_16x16x32_bf16 v[52:55], v[156:159], v[172:175], v[52:55]
	v_mfma_f32_16x16x32_bf16 v[48:51], v[164:167], v[172:175], v[48:51]
	v_mfma_f32_16x16x32_bf16 v[36:39], v[156:159], v[180:183], v[36:39]
	v_mfma_f32_16x16x32_bf16 v[32:35], v[164:167], v[180:183], v[32:35]
	v_mfma_f32_16x16x32_bf16 v[20:23], v[156:159], v[188:191], v[20:23]
	v_mfma_f32_16x16x32_bf16 v[16:19], v[164:167], v[188:191], v[16:19]
	v_mfma_f32_16x16x32_bf16 v[4:7], v[156:159], v[208:211], v[4:7]
	v_mfma_f32_16x16x32_bf16 v[0:3], v[164:167], v[208:211], v[0:3]
	v_mfma_f32_16x16x32_bf16 v[52:55], v[160:163], v[176:179], v[52:55]
	v_mfma_f32_16x16x32_bf16 v[48:51], v[168:171], v[176:179], v[48:51]
	v_mfma_f32_16x16x32_bf16 v[36:39], v[160:163], v[184:187], v[36:39]
	v_mfma_f32_16x16x32_bf16 v[32:35], v[168:171], v[184:187], v[32:35]
	v_mfma_f32_16x16x32_bf16 v[20:23], v[160:163], v[204:207], v[20:23]
	v_mfma_f32_16x16x32_bf16 v[16:19], v[168:171], v[204:207], v[16:19]
	v_mfma_f32_16x16x32_bf16 v[4:7], v[160:163], v[212:215], v[4:7]
	v_mfma_f32_16x16x32_bf16 v[0:3], v[168:171], v[212:215], v[0:3]
	s_barrier
	s_setprio 0
	s_add_i32 s53, s53, 2
	s_add_u32 s51, s51, 0x10000
	s_addc_u32 s52, s52, 0
	s_add_u32 s34, s34, 0x100
	s_addc_u32 s35, s35, 0
	s_cmp_gt_u32 s53, 29
	s_cbranch_scc1 .Lpeel_exit_5

; #define PG8_BAR __builtin_amdgcn_s_barrier()
; template <class Epi, class Sched, bool ALIGN_EPI = false, bool SP2 = false>
; __device__ __forceinline__ void gemm_phase(PG8_LAS unsigned char* lds, const Gemm g, const Sched& S, const Epi& E) {
;     ...
;         if constexpr (ALIGN_EPI) { if (wr == 0) PG8_BAR; }
;         if constexpr (!Epi::AFTER_DRAIN) { if (cur.part < 0) E(acc, cur, wr, wc, fr, fq); else store_part<Epi::PERM>(acc, cur, g.part, wr, wc, fr, fq); S.done(cur); }
.Lpeel_exit_5:
	s_and_b64 vcc, exec, s[18:19]
	s_cbranch_vccz .LBB0_1342
	s_barrier

; #define PG8_STAGE(bufoff, gbase, voff) do { _Pragma("unroll") for (int _i = 0; _i < 2; ++_i) \
;         __builtin_amdgcn_global_load_lds((const unsigned*)((const char*)(gbase) + (voff)[_i]), (PG8_LAS unsigned*)(lds + (bufoff) + ldsw + _i * 8192), 16, 0, 0); } while (0)
; #define PG8_LDA(dst, b, h) do { _Pragma("unroll") for (int m = 0; m < 4; ++m) _Pragma("unroll") for (int k = 0; k < 2; ++k) dst[m][k] = *(const PG8_LAS bf16x8*)(lds + PG8_SA(b, h) + aoff + m * 2048 + k * 1024); } while (0)
; #define PG8_LDB(dst, b, h) do { _Pragma("unroll") for (int n = 0; n < 2; ++n) _Pragma("unroll") for (int k = 0; k < 2; ++k) dst[n][k] = *(const PG8_LAS bf16x8*)(lds + PG8_SB(b, h) + boff + n * 2048 + k * 1024); } while (0)
; #define PG8_MMA(ai, bj, At, Bt) do { __builtin_amdgcn_s_setprio(1); _Pragma("unroll") for (int m = 0; m < 4; ++m) _Pragma("unroll") for (int n = 0; n < 2; ++n) _Pragma("unroll") for (int k = 0; k < 2; ++k) \
;         acc[ai][bj][m][n] = __builtin_amdgcn_mfma_f32_16x16x32_bf16(Bt[n][k], At[m][k], acc[ai][bj][m][n], 0, 0, 0); __builtin_amdgcn_s_setprio(0); } while (0)
; #define PG8_WAIT_V(n) asm volatile("s_waitcnt vmcnt(" #n ")" ::: "memory")
; #define PG8_WAIT_L(n) asm volatile("s_waitcnt lgkmcnt(" #n ")" ::: "memory")
; #define PG8_BAR __builtin_amdgcn_s_barrier()
; #define PG8_SCHED __builtin_amdgcn_sched_barrier(0)
; template <class Epi, class Sched, bool ALIGN_EPI = false, bool SP2 = false>
; __device__ __forceinline__ void gemm_phase(PG8_LAS unsigned char* lds, const Gemm g, const Sched& S, const Epi& E) {
;     ...
;             PG8_LDB(B0, 0, 0); PG8_LDB(B1, 0, 1); PG8_SCHED; PG8_LDA(At, 0, 0); PG8_STAGE(PG8_SA(1, 1), a1 + hstepA, voffA);
;             PG8_WAIT_V(8); PG8_WAIT_L(0); PG8_BAR; PG8_MMA(0, 0, At, B0); PG8_MMA(0, 1, At, B1); PG8_BAR; PG8_SCHED;
;             PG8_LDA(At, 0, 1); PG8_STAGE(PG8_SB(0, 0), b2, voffB); PG8_STAGE(PG8_SB(0, 1), b2 + hstepB, voffB); PG8_STAGE(PG8_SA(0, 0), a2, voffA);
;             PG8_WAIT_V(8); PG8_WAIT_L(0); PG8_BAR; PG8_MMA(1, 0, At, B0); PG8_MMA(1, 1, At, B1); PG8_BAR; PG8_SCHED;
.LBB0_1420:
	s_add_i32 s35, s76, -2
	s_add_u32 s40, s40, 0xc000
	s_addc_u32 s41, s41, 0
	s_add_u32 s77, s42, 0x10000
	s_addc_u32 s78, s43, 0
	s_mov_b32 s42, 0
	s_waitcnt vmcnt(0)
	s_sub_u32 s100, s40, 0x4000
	s_subb_u32 s101, s41, 0
	ds_read_b128 v[142:145], v191
	ds_read_b128 v[146:149], v191 offset:1024
	ds_read_b128 v[150:153], v191 offset:2048
	ds_read_b128 v[154:157], v191 offset:3072
	ds_read_b128 v[158:161], v192
	ds_read_b128 v[162:165], v192 offset:1024
	ds_read_b128 v[166:169], v192 offset:2048
	ds_read_b128 v[170:173], v192 offset:3072
	s_add_i32 s79, s42, 2
	s_add_u32 s43, s40, 0x4000
	s_addc_u32 s44, s41, 0
	s_cmp_eq_u32 s35, s42
	s_cselect_b32 s46, s36, s43
	s_cselect_b32 s47, s37, s44
	s_cselect_b32 s44, s38, s77
	s_cselect_b32 s45, s39, s78
	s_add_u32 s42, s46, 0x8000
	s_addc_u32 s43, s47, 0
	ds_read_b128 v[174:177], v193
	ds_read_b128 v[178:181], v193 offset:1024
	ds_read_b128 v[182:185], v193 offset:2048
	ds_read_b128 v[194:197], v193 offset:3072
	ds_read_b128 v[198:201], v193 offset:4096
	ds_read_b128 v[202:205], v193 offset:5120
	ds_read_b128 v[206:209], v193 offset:6144
	ds_read_b128 v[210:213], v193 offset:7168
	s_mov_b32 m0, s50
	s_nop 0
	global_load_lds_dwordx4 v134, s[100:101]
	s_mov_b32 m0, s51
	s_nop 0
	global_load_lds_dwordx4 v136, s[100:101]
	s_add_i32 m0, s10, 0xc000
	s_nop 0
	global_load_lds_dwordx4 v134, s[40:41]
	s_add_i32 m0, s10, 0xe000
	s_nop 0
	global_load_lds_dwordx4 v136, s[40:41]
	s_waitcnt vmcnt(8)
	s_waitcnt lgkmcnt(0)
	s_setprio 1
	s_barrier
	v_mfma_f32_16x16x32_bf16 v[124:127], v[142:145], v[174:177], 0
	v_mfma_f32_16x16x32_bf16 v[120:123], v[150:153], v[174:177], 0
	v_mfma_f32_16x16x32_bf16 v[108:111], v[142:145], v[182:185], 0
	v_mfma_f32_16x16x32_bf16 v[104:107], v[150:153], v[182:185], 0
	v_mfma_f32_16x16x32_bf16 v[92:95], v[142:145], v[198:201], 0
	v_mfma_f32_16x16x32_bf16 v[88:91], v[150:153], v[198:201], 0
	v_mfma_f32_16x16x32_bf16 v[76:79], v[142:145], v[206:209], 0
	v_mfma_f32_16x16x32_bf16 v[72:75], v[150:153], v[206:209], 0
	v_mfma_f32_16x16x32_bf16 v[124:127], v[146:149], v[178:181], v[124:127]
	v_mfma_f32_16x16x32_bf16 v[120:123], v[154:157], v[178:181], v[120:123]
	v_mfma_f32_16x16x32_bf16 v[108:111], v[146:149], v[194:197], v[108:111]
	v_mfma_f32_16x16x32_bf16 v[104:107], v[154:157], v[194:197], v[104:107]
	v_mfma_f32_16x16x32_bf16 v[92:95], v[146:149], v[202:205], v[92:95]
	v_mfma_f32_16x16x32_bf16 v[88:91], v[154:157], v[202:205], v[88:91]
	v_mfma_f32_16x16x32_bf16 v[76:79], v[146:149], v[210:213], v[76:79]
	v_mfma_f32_16x16x32_bf16 v[72:75], v[154:157], v[210:213], v[72:75]
	v_mfma_f32_16x16x32_bf16 v[116:119], v[158:161], v[174:177], 0
	v_mfma_f32_16x16x32_bf16 v[112:115], v[166:169], v[174:177], 0
	v_mfma_f32_16x16x32_bf16 v[100:103], v[158:161], v[182:185], 0
	v_mfma_f32_16x16x32_bf16 v[96:99], v[166:169], v[182:185], 0
	v_mfma_f32_16x16x32_bf16 v[84:87], v[158:161], v[198:201], 0
	v_mfma_f32_16x16x32_bf16 v[80:83], v[166:169], v[198:201], 0
	v_mfma_f32_16x16x32_bf16 v[68:71], v[158:161], v[206:209], 0
	v_mfma_f32_16x16x32_bf16 v[64:67], v[166:169], v[206:209], 0
	v_mfma_f32_16x16x32_bf16 v[116:119], v[162:165], v[178:181], v[116:119]
	v_mfma_f32_16x16x32_bf16 v[112:115], v[170:173], v[178:181], v[112:115]
	v_mfma_f32_16x16x32_bf16 v[100:103], v[162:165], v[194:197], v[100:103]
	v_mfma_f32_16x16x32_bf16 v[96:99], v[170:173], v[194:197], v[96:99]
	v_mfma_f32_16x16x32_bf16 v[84:87], v[162:165], v[202:205], v[84:87]
	v_mfma_f32_16x16x32_bf16 v[80:83], v[170:173], v[202:205], v[80:83]
	v_mfma_f32_16x16x32_bf16 v[68:71], v[162:165], v[210:213], v[68:71]
	v_mfma_f32_16x16x32_bf16 v[64:67], v[170:173], v[210:213], v[64:67]
	s_barrier
	s_setprio 0
	s_add_i32 s80, s52, s2
	s_mov_b32 m0, s80
	ds_read_b128 v[174:177], v193 offset:16384
	ds_read_b128 v[178:181], v193 offset:17408
	ds_read_b128 v[182:185], v193 offset:18432
	ds_read_b128 v[194:197], v193 offset:19456
	ds_read_b128 v[198:201], v193 offset:20480
	ds_read_b128 v[202:205], v193 offset:21504
	ds_read_b128 v[206:209], v193 offset:22528
	ds_read_b128 v[210:213], v193 offset:23552
	global_load_lds_dwordx4 v128, s[44:45]
	s_add_i32 m0, s80, 0x2000
	s_add_u32 s80, s44, 0x4000
	s_addc_u32 s81, s45, 0
	s_add_i32 s82, s53, s2
	global_load_lds_dwordx4 v130, s[44:45]
	s_mov_b32 m0, s82
	s_nop 0
	global_load_lds_dwordx4 v128, s[80:81]
	s_add_i32 m0, s82, 0x2000
	s_nop 0
	global_load_lds_dwordx4 v130, s[80:81]
	s_waitcnt vmcnt(6)
	s_waitcnt lgkmcnt(0)
	s_setprio 1
	s_barrier
	v_mfma_f32_16x16x32_bf16 v[60:63], v[142:145], v[174:177], 0
	v_mfma_f32_16x16x32_bf16 v[56:59], v[150:153], v[174:177], 0
	v_mfma_f32_16x16x32_bf16 v[44:47], v[142:145], v[182:185], 0
	v_mfma_f32_16x16x32_bf16 v[40:43], v[150:153], v[182:185], 0
	v_mfma_f32_16x16x32_bf16 v[28:31], v[142:145], v[198:201], 0
	v_mfma_f32_16x16x32_bf16 v[24:27], v[150:153], v[198:201], 0
	v_mfma_f32_16x16x32_bf16 v[12:15], v[142:145], v[206:209], 0
	v_mfma_f32_16x16x32_bf16 v[8:11], v[150:153], v[206:209], 0
	v_mfma_f32_16x16x32_bf16 v[60:63], v[146:149], v[178:181], v[60:63]
	v_mfma_f32_16x16x32_bf16 v[56:59], v[154:157], v[178:181], v[56:59]
	v_mfma_f32_16x16x32_bf16 v[44:47], v[146:149], v[194:197], v[44:47]
	v_mfma_f32_16x16x32_bf16 v[40:43], v[154:157], v[194:197], v[40:43]
	v_mfma_f32_16x16x32_bf16 v[28:31], v[146:149], v[202:205], v[28:31]
	v_mfma_f32_16x16x32_bf16 v[24:27], v[154:157], v[202:205], v[24:27]
	v_mfma_f32_16x16x32_bf16 v[12:15], v[146:149], v[210:213], v[12:15]
	v_mfma_f32_16x16x32_bf16 v[8:11], v[154:157], v[210:213], v[8:11]
	v_mfma_f32_16x16x32_bf16 v[52:55], v[158:161], v[174:177], 0
	v_mfma_f32_16x16x32_bf16 v[48:51], v[166:169], v[174:177], 0
	v_mfma_f32_16x16x32_bf16 v[36:39], v[158:161], v[182:185], 0
	v_mfma_f32_16x16x32_bf16 v[32:35], v[166:169], v[182:185], 0
	v_mfma_f32_16x16x32_bf16 v[20:23], v[158:161], v[198:201], 0
	v_mfma_f32_16x16x32_bf16 v[16:19], v[166:169], v[198:201], 0
	v_mfma_f32_16x16x32_bf16 v[4:7], v[158:161], v[206:209], 0
	v_mfma_f32_16x16x32_bf16 v[0:3], v[166:169], v[206:209], 0
	v_mfma_f32_16x16x32_bf16 v[52:55], v[162:165], v[178:181], v[52:55]
	v_mfma_f32_16x16x32_bf16 v[48:51], v[170:173], v[178:181], v[48:51]
	v_mfma_f32_16x16x32_bf16 v[36:39], v[162:165], v[194:197], v[36:39]
	v_mfma_f32_16x16x32_bf16 v[32:35], v[170:173], v[194:197], v[32:35]
	v_mfma_f32_16x16x32_bf16 v[20:23], v[162:165], v[202:205], v[20:23]
	v_mfma_f32_16x16x32_bf16 v[16:19], v[170:173], v[202:205], v[16:19]
	v_mfma_f32_16x16x32_bf16 v[4:7], v[162:165], v[210:213], v[4:7]
	v_mfma_f32_16x16x32_bf16 v[0:3], v[170:173], v[210:213], v[0:3]
	s_barrier
; #define PG8_STAGE(bufoff, gbase, voff) do { _Pragma("unroll") for (int _i = 0; _i < 2; ++_i) \
;         __builtin_amdgcn_global_load_lds((const unsigned*)((const char*)(gbase) + (voff)[_i]), (PG8_LAS unsigned*)(lds + (bufoff) + ldsw + _i * 8192), 16, 0, 0); } while (0)
; #define PG8_LDA(dst, b, h) do { _Pragma("unroll") for (int m = 0; m < 4; ++m) _Pragma("unroll") for (int k = 0; k < 2; ++k) dst[m][k] = *(const PG8_LAS bf16x8*)(lds + PG8_SA(b, h) + aoff + m * 2048 + k * 1024); } while (0)
; #define PG8_LDB(dst, b, h) do { _Pragma("unroll") for (int n = 0; n < 2; ++n) _Pragma("unroll") for (int k = 0; k < 2; ++k) dst[n][k] = *(const PG8_LAS bf16x8*)(lds + PG8_SB(b, h) + boff + n * 2048 + k * 1024); } while (0)
; #define PG8_MMA(ai, bj, At, Bt) do { __builtin_amdgcn_s_setprio(1); _Pragma("unroll") for (int m = 0; m < 4; ++m) _Pragma("unroll") for (int n = 0; n < 2; ++n) _Pragma("unroll") for (int k = 0; k < 2; ++k) \
;         acc[ai][bj][m][n] = __builtin_amdgcn_mfma_f32_16x16x32_bf16(Bt[n][k], At[m][k], acc[ai][bj][m][n], 0, 0, 0); __builtin_amdgcn_s_setprio(0); } while (0)
; #define PG8_WAIT_V(n) asm volatile("s_waitcnt vmcnt(" #n ")" ::: "memory")
; #define PG8_WAIT_L(n) asm volatile("s_waitcnt lgkmcnt(" #n ")" ::: "memory")
; #define PG8_BAR __builtin_amdgcn_s_barrier()
; #define PG8_SCHED __builtin_amdgcn_sched_barrier(0)
; template <class Epi, class Sched, bool ALIGN_EPI = false, bool SP2 = false>
; __device__ __forceinline__ void gemm_phase(PG8_LAS unsigned char* lds, const Gemm g, const Sched& S, const Epi& E) {
;     ...
;             PG8_LDB(B0, 1, 0); PG8_LDB(B1, 1, 1); PG8_SCHED; PG8_LDA(At, 1, 0); PG8_STAGE(PG8_SA(0, 1), a2 + hstepA, voffA);
;             PG8_WAIT_V(8); PG8_WAIT_L(0); PG8_BAR; PG8_MMA(0, 0, At, B0); PG8_MMA(0, 1, At, B1); PG8_BAR; PG8_SCHED;
;             PG8_LDA(At, 1, 1); PG8_STAGE(PG8_SB(1, 0), b3, voffB); PG8_STAGE(PG8_SB(1, 1), b3 + hstepB, voffB); PG8_STAGE(PG8_SA(1, 0), a3, voffA);
;             PG8_WAIT_V(8); PG8_WAIT_L(0); PG8_BAR; PG8_MMA(1, 0, At, B0); PG8_MMA(1, 1, At, B1); PG8_BAR; PG8_SCHED;
	s_setprio 0
	s_add_i32 s80, 0, 0x18000
	v_add_u32_e32 v132, s80, v189
	s_add_i32 s81, 0, 0x1c000
	ds_read_b128 v[142:145], v132
	ds_read_b128 v[146:149], v132 offset:1024
	ds_read_b128 v[150:153], v132 offset:2048
	ds_read_b128 v[154:157], v132 offset:3072
	v_add_u32_e32 v132, s81, v189
	ds_read_b128 v[158:161], v132
	ds_read_b128 v[162:165], v132 offset:1024
	ds_read_b128 v[166:169], v132 offset:2048
	ds_read_b128 v[170:173], v132 offset:3072
	s_mov_b32 m0, s10
	s_nop 0
	global_load_lds_dwordx4 v128, s[46:47]
	s_mov_b32 m0, s14
	s_nop 0
	global_load_lds_dwordx4 v130, s[46:47]
	s_add_u32 s46, s46, 0x4000
	s_addc_u32 s47, s47, 0
	s_mov_b32 m0, s15
	ds_read_b128 v[174:177], v193 offset:32768
	ds_read_b128 v[178:181], v193 offset:33792
	ds_read_b128 v[182:185], v193 offset:34816
	ds_read_b128 v[194:197], v193 offset:35840
	ds_read_b128 v[198:201], v193 offset:36864
	ds_read_b128 v[202:205], v193 offset:37888
	ds_read_b128 v[206:209], v193 offset:38912
	ds_read_b128 v[210:213], v193 offset:39936
	global_load_lds_dwordx4 v128, s[46:47]
	s_mov_b32 m0, s48
	s_nop 0
	global_load_lds_dwordx4 v130, s[46:47]
	s_waitcnt vmcnt(8)
	s_waitcnt lgkmcnt(0)
	s_setprio 1
	s_barrier
	v_mfma_f32_16x16x32_bf16 v[124:127], v[142:145], v[174:177], v[124:127]
	v_mfma_f32_16x16x32_bf16 v[120:123], v[150:153], v[174:177], v[120:123]
	v_mfma_f32_16x16x32_bf16 v[108:111], v[142:145], v[182:185], v[108:111]
	v_mfma_f32_16x16x32_bf16 v[104:107], v[150:153], v[182:185], v[104:107]
	v_mfma_f32_16x16x32_bf16 v[92:95], v[142:145], v[198:201], v[92:95]
	v_mfma_f32_16x16x32_bf16 v[88:91], v[150:153], v[198:201], v[88:91]
	v_mfma_f32_16x16x32_bf16 v[76:79], v[142:145], v[206:209], v[76:79]
	v_mfma_f32_16x16x32_bf16 v[72:75], v[150:153], v[206:209], v[72:75]
	v_mfma_f32_16x16x32_bf16 v[124:127], v[146:149], v[178:181], v[124:127]
	v_mfma_f32_16x16x32_bf16 v[120:123], v[154:157], v[178:181], v[120:123]
	v_mfma_f32_16x16x32_bf16 v[108:111], v[146:149], v[194:197], v[108:111]
	v_mfma_f32_16x16x32_bf16 v[104:107], v[154:157], v[194:197], v[104:107]
	v_mfma_f32_16x16x32_bf16 v[92:95], v[146:149], v[202:205], v[92:95]
	v_mfma_f32_16x16x32_bf16 v[88:91], v[154:157], v[202:205], v[88:91]
	v_mfma_f32_16x16x32_bf16 v[76:79], v[146:149], v[210:213], v[76:79]
	v_mfma_f32_16x16x32_bf16 v[72:75], v[154:157], v[210:213], v[72:75]
	v_mfma_f32_16x16x32_bf16 v[116:119], v[158:161], v[174:177], v[116:119]
	v_mfma_f32_16x16x32_bf16 v[112:115], v[166:169], v[174:177], v[112:115]
	v_mfma_f32_16x16x32_bf16 v[100:103], v[158:161], v[182:185], v[100:103]
	v_mfma_f32_16x16x32_bf16 v[96:99], v[166:169], v[182:185], v[96:99]
	v_mfma_f32_16x16x32_bf16 v[84:87], v[158:161], v[198:201], v[84:87]
	v_mfma_f32_16x16x32_bf16 v[80:83], v[166:169], v[198:201], v[80:83]
	v_mfma_f32_16x16x32_bf16 v[68:71], v[158:161], v[206:209], v[68:71]
	v_mfma_f32_16x16x32_bf16 v[64:67], v[166:169], v[206:209], v[64:67]
	v_mfma_f32_16x16x32_bf16 v[116:119], v[162:165], v[178:181], v[116:119]
	v_mfma_f32_16x16x32_bf16 v[112:115], v[170:173], v[178:181], v[112:115]
	v_mfma_f32_16x16x32_bf16 v[100:103], v[162:165], v[194:197], v[100:103]
	v_mfma_f32_16x16x32_bf16 v[96:99], v[170:173], v[194:197], v[96:99]
	v_mfma_f32_16x16x32_bf16 v[84:87], v[162:165], v[202:205], v[84:87]
	v_mfma_f32_16x16x32_bf16 v[80:83], v[170:173], v[202:205], v[80:83]
	v_mfma_f32_16x16x32_bf16 v[68:71], v[162:165], v[210:213], v[68:71]
	v_mfma_f32_16x16x32_bf16 v[64:67], v[170:173], v[210:213], v[64:67]
	s_barrier
	s_setprio 0
	s_add_u32 s46, s44, 0x8000
	s_addc_u32 s47, s45, 0
	s_add_i32 s80, s80, s2
	s_mov_b32 m0, s80
	ds_read_b128 v[174:177], v193 offset:49152
	ds_read_b128 v[178:181], v193 offset:50176
	ds_read_b128 v[182:185], v193 offset:51200
	ds_read_b128 v[194:197], v193 offset:52224
	ds_read_b128 v[198:201], v193 offset:53248
	ds_read_b128 v[202:205], v193 offset:54272
	ds_read_b128 v[206:209], v193 offset:55296
	ds_read_b128 v[210:213], v193 offset:56320
	global_load_lds_dwordx4 v128, s[46:47]
	s_add_i32 m0, s80, 0x2000
	s_add_u32 s44, s44, 0xc000
	s_addc_u32 s45, s45, 0
	global_load_lds_dwordx4 v130, s[46:47]
	s_add_i32 s46, s81, s2
	s_mov_b32 m0, s46
	s_nop 0
	global_load_lds_dwordx4 v128, s[44:45]
	s_add_i32 m0, s46, 0x2000
	s_nop 0
	global_load_lds_dwordx4 v130, s[44:45]
	s_waitcnt vmcnt(6)
	s_waitcnt lgkmcnt(0)
	s_setprio 1
	s_barrier
	v_mfma_f32_16x16x32_bf16 v[60:63], v[142:145], v[174:177], v[60:63]
	v_mfma_f32_16x16x32_bf16 v[56:59], v[150:153], v[174:177], v[56:59]
	v_mfma_f32_16x16x32_bf16 v[44:47], v[142:145], v[182:185], v[44:47]
	v_mfma_f32_16x16x32_bf16 v[40:43], v[150:153], v[182:185], v[40:43]
	v_mfma_f32_16x16x32_bf16 v[28:31], v[142:145], v[198:201], v[28:31]
	v_mfma_f32_16x16x32_bf16 v[24:27], v[150:153], v[198:201], v[24:27]
	v_mfma_f32_16x16x32_bf16 v[12:15], v[142:145], v[206:209], v[12:15]
	v_mfma_f32_16x16x32_bf16 v[8:11], v[150:153], v[206:209], v[8:11]
	v_mfma_f32_16x16x32_bf16 v[60:63], v[146:149], v[178:181], v[60:63]
	v_mfma_f32_16x16x32_bf16 v[56:59], v[154:157], v[178:181], v[56:59]
	v_mfma_f32_16x16x32_bf16 v[44:47], v[146:149], v[194:197], v[44:47]
	v_mfma_f32_16x16x32_bf16 v[40:43], v[154:157], v[194:197], v[40:43]
	v_mfma_f32_16x16x32_bf16 v[28:31], v[146:149], v[202:205], v[28:31]
	v_mfma_f32_16x16x32_bf16 v[24:27], v[154:157], v[202:205], v[24:27]
	v_mfma_f32_16x16x32_bf16 v[12:15], v[146:149], v[210:213], v[12:15]
	v_mfma_f32_16x16x32_bf16 v[8:11], v[154:157], v[210:213], v[8:11]
	v_mfma_f32_16x16x32_bf16 v[52:55], v[158:161], v[174:177], v[52:55]
	v_mfma_f32_16x16x32_bf16 v[48:51], v[166:169], v[174:177], v[48:51]
	v_mfma_f32_16x16x32_bf16 v[36:39], v[158:161], v[182:185], v[36:39]
	v_mfma_f32_16x16x32_bf16 v[32:35], v[166:169], v[182:185], v[32:35]
	v_mfma_f32_16x16x32_bf16 v[20:23], v[158:161], v[198:201], v[20:23]
	v_mfma_f32_16x16x32_bf16 v[16:19], v[166:169], v[198:201], v[16:19]
	v_mfma_f32_16x16x32_bf16 v[4:7], v[158:161], v[206:209], v[4:7]
	v_mfma_f32_16x16x32_bf16 v[0:3], v[166:169], v[206:209], v[0:3]
	v_mfma_f32_16x16x32_bf16 v[52:55], v[162:165], v[178:181], v[52:55]
	v_mfma_f32_16x16x32_bf16 v[48:51], v[170:173], v[178:181], v[48:51]
	v_mfma_f32_16x16x32_bf16 v[36:39], v[162:165], v[194:197], v[36:39]
	v_mfma_f32_16x16x32_bf16 v[32:35], v[170:173], v[194:197], v[32:35]
	v_mfma_f32_16x16x32_bf16 v[20:23], v[162:165], v[202:205], v[20:23]
	v_mfma_f32_16x16x32_bf16 v[16:19], v[170:173], v[202:205], v[16:19]
	v_mfma_f32_16x16x32_bf16 v[4:7], v[162:165], v[210:213], v[4:7]
	v_mfma_f32_16x16x32_bf16 v[0:3], v[170:173], v[210:213], v[0:3]
	s_barrier
	s_setprio 0
	s_add_u32 s40, s40, 0x10000
	s_addc_u32 s41, s41, 0
	s_add_u32 s77, s77, 0x10000
	s_addc_u32 s78, s78, 0
	s_cmp_ge_i32 s79, s76
	s_mov_b32 s42, s79
	s_cbranch_scc1 .Lpeel_exit_6

; #define PG8_BAR __builtin_amdgcn_s_barrier()
; template <class Epi, class Sched, bool ALIGN_EPI = false, bool SP2 = false>
; __device__ __forceinline__ void gemm_phase(PG8_LAS unsigned char* lds, const Gemm g, const Sched& S, const Epi& E) {
;     ...
;         if constexpr (ALIGN_EPI) { if (wr == 0) PG8_BAR; }
;         if constexpr (!Epi::AFTER_DRAIN) { if (cur.part < 0) E(acc, cur, wr, wc, fr, fq); else store_part<Epi::PERM>(acc, cur, g.part, wr, wc, fr, fq); S.done(cur); }
.Lpeel_exit_6:
	s_and_b64 vcc, exec, s[20:21]
	s_cbranch_vccnz .LBB0_1426
	s_mov_b64 s[40:41], -1
	s_cmp_gt_i32 s16, -1
	v_lshl_or_b32 v142, s75, 8, v190
	s_cbranch_scc1 .LBB0_1427
